# hand-written packed-f32 GELU/SiLU epilogues (same functions, algebraically refactored) with own LDS staging+flush for P2 gelu/silu tiles and P6 gate tiles; P7b corrections bulk-loaded
# speedup vs baseline: 1.1220x; 1.0105x over previous
.Lg8_p2_eg1:
	s_nop 7
	s_nop 7
	v_permlane16_swap_b32_e32 v112, v116
	v_permlane16_swap_b32_e32 v113, v117
	v_permlane16_swap_b32_e32 v114, v118
	v_permlane16_swap_b32_e32 v115, v119
	v_permlane16_swap_b32_e32 v120, v124
	v_permlane16_swap_b32_e32 v121, v125
	v_permlane16_swap_b32_e32 v122, v126
	v_permlane16_swap_b32_e32 v123, v127
	v_permlane16_swap_b32_e32 v80, v84
	v_permlane16_swap_b32_e32 v81, v85
	v_permlane16_swap_b32_e32 v82, v86
	v_permlane16_swap_b32_e32 v83, v87
	v_permlane16_swap_b32_e32 v88, v92
	v_permlane16_swap_b32_e32 v89, v93
	v_permlane16_swap_b32_e32 v90, v94
	v_permlane16_swap_b32_e32 v91, v95
	v_permlane16_swap_b32_e32 v96, v100
	v_permlane16_swap_b32_e32 v97, v101
	v_permlane16_swap_b32_e32 v98, v102
	v_permlane16_swap_b32_e32 v99, v103
	v_permlane16_swap_b32_e32 v104, v108
	v_permlane16_swap_b32_e32 v105, v109
	v_permlane16_swap_b32_e32 v106, v110
	v_permlane16_swap_b32_e32 v107, v111
	v_permlane16_swap_b32_e32 v64, v68
	v_permlane16_swap_b32_e32 v65, v69
	v_permlane16_swap_b32_e32 v66, v70
	v_permlane16_swap_b32_e32 v67, v71
	v_permlane16_swap_b32_e32 v72, v76
	v_permlane16_swap_b32_e32 v73, v77
	v_permlane16_swap_b32_e32 v74, v78
	v_permlane16_swap_b32_e32 v75, v79
	v_permlane16_swap_b32_e32 v48, v52
	v_permlane16_swap_b32_e32 v49, v53
	v_permlane16_swap_b32_e32 v50, v54
	v_permlane16_swap_b32_e32 v51, v55
	v_permlane16_swap_b32_e32 v56, v60
	v_permlane16_swap_b32_e32 v57, v61
	v_permlane16_swap_b32_e32 v58, v62
	v_permlane16_swap_b32_e32 v59, v63
	v_permlane16_swap_b32_e32 v16, v20
	v_permlane16_swap_b32_e32 v17, v21
	v_permlane16_swap_b32_e32 v18, v22
	v_permlane16_swap_b32_e32 v19, v23
	v_permlane16_swap_b32_e32 v24, v28
	v_permlane16_swap_b32_e32 v25, v29
	v_permlane16_swap_b32_e32 v26, v30
	v_permlane16_swap_b32_e32 v27, v31
	v_permlane16_swap_b32_e32 v32, v36
	v_permlane16_swap_b32_e32 v33, v37
	v_permlane16_swap_b32_e32 v34, v38
	v_permlane16_swap_b32_e32 v35, v39
	v_permlane16_swap_b32_e32 v40, v44
	v_permlane16_swap_b32_e32 v41, v45
	v_permlane16_swap_b32_e32 v42, v46
	v_permlane16_swap_b32_e32 v43, v47
	v_permlane16_swap_b32_e32 v0, v4
	v_permlane16_swap_b32_e32 v1, v5
	v_permlane16_swap_b32_e32 v2, v6
	v_permlane16_swap_b32_e32 v3, v7
	v_permlane16_swap_b32_e32 v8, v12
	v_permlane16_swap_b32_e32 v9, v13
	v_permlane16_swap_b32_e32 v10, v14
	v_permlane16_swap_b32_e32 v11, v15
	s_nop 1
	s_cmp_lt_i32 s36, 6
	s_cbranch_scc1 .Lepi2_orig
	s_cmp_gt_i32 s36, 13
	s_cbranch_scc1 .Lepi2_silu
	s_cmp_lt_i32 s36, 10
	s_mov_b32 s55, 0x19000000
	s_cselect_b32 s55, 0x12c00000, s55
	s_cselect_b32 s58, 6, 10
	s_sub_i32 s58, s36, s58
	s_lshl_b32 s58, s58, 9
	s_add_u32 s55, s55, s58
	s_lshl_b64 s[58:59], s[34:35], 19
	s_add_u32 s58, s58, s55
	s_addc_u32 s59, s59, 0
	s_add_u32 s56, s90, s58
	s_addc_u32 s57, s91, s59
	v_lshrrev_b32_e32 v144, 1, v208
	v_and_b32_e32 v144, 0xffffffc0, v144
	v_and_b32_e32 v140, 31, v208
	v_or_b32_e32 v140, v144, v140
	v_mul_u32_u24_e32 v140, 0x210, v140
	v_lshlrev_b32_e32 v144, 2, v208
	v_and_b32_e32 v144, 0x100, v144
	v_add_u32_e32 v140, v140, v144
	v_lshrrev_b32_e32 v144, 2, v208
	v_and_b32_e32 v144, 8, v144
	v_add_u32_e32 v140, v140, v144
	v_lshrrev_b32_e32 v144, 5, v208
	v_and_b32_e32 v143, 31, v208
	v_lshlrev_b32_e32 v143, 4, v143
	v_mul_u32_u24_e32 v141, 0x210, v144
	v_add_u32_e32 v141, v141, v143
	v_add_u32_e32 v142, 0x10800, v141
	v_mul_u32_u24_e32 v144, 0x800, v144
	v_add_u32_e32 v143, v143, v144
	v_mov_b32_e32 v136, 0x40135761
	v_mov_b32_e32 v137, 0x40135761
	v_mov_b32_e32 v138, 0x3dd2d3e8
	v_mov_b32_e32 v139, 0x3dd2d3e8
	v_pk_mul_f32 v[128:129], v[112:113], v[112:113]
	v_pk_mul_f32 v[130:131], v[114:115], v[114:115]
	v_pk_mul_f32 v[132:133], v[116:117], v[116:117]
	v_pk_mul_f32 v[134:135], v[118:119], v[118:119]
	v_pk_fma_f32 v[128:129], v[128:129], v[138:139], v[136:137]
	v_pk_fma_f32 v[130:131], v[130:131], v[138:139], v[136:137]
	v_pk_fma_f32 v[132:133], v[132:133], v[138:139], v[136:137]
	v_pk_fma_f32 v[134:135], v[134:135], v[138:139], v[136:137]
	v_pk_mul_f32 v[128:129], v[128:129], v[112:113]
	v_pk_mul_f32 v[130:131], v[130:131], v[114:115]
	v_pk_mul_f32 v[132:133], v[132:133], v[116:117]
	v_pk_mul_f32 v[134:135], v[134:135], v[118:119]
	v_exp_f32_e32 v128, v128
	v_exp_f32_e32 v129, v129
	v_exp_f32_e32 v130, v130
	v_exp_f32_e32 v131, v131
	v_exp_f32_e32 v132, v132
	v_exp_f32_e32 v133, v133
	v_exp_f32_e32 v134, v134
	v_exp_f32_e32 v135, v135
	s_nop 0
	v_pk_add_f32 v[128:129], v[128:129], 1.0 op_sel_hi:[1,0]
	v_pk_add_f32 v[130:131], v[130:131], 1.0 op_sel_hi:[1,0]
	v_pk_add_f32 v[132:133], v[132:133], 1.0 op_sel_hi:[1,0]
	v_pk_add_f32 v[134:135], v[134:135], 1.0 op_sel_hi:[1,0]
	v_rcp_f32_e32 v128, v128
	v_rcp_f32_e32 v129, v129
	v_rcp_f32_e32 v130, v130
	v_rcp_f32_e32 v131, v131
	v_rcp_f32_e32 v132, v132
	v_rcp_f32_e32 v133, v133
	v_rcp_f32_e32 v134, v134
	v_rcp_f32_e32 v135, v135
	s_nop 0
	v_pk_fma_f32 v[112:113], v[112:113], v[128:129], v[112:113] neg_lo:[1,0,0] neg_hi:[1,0,0]
	v_pk_fma_f32 v[114:115], v[114:115], v[130:131], v[114:115] neg_lo:[1,0,0] neg_hi:[1,0,0]
	v_pk_fma_f32 v[116:117], v[116:117], v[132:133], v[116:117] neg_lo:[1,0,0] neg_hi:[1,0,0]
	v_pk_fma_f32 v[118:119], v[118:119], v[134:135], v[118:119] neg_lo:[1,0,0] neg_hi:[1,0,0]
	v_cvt_pk_bf16_f32 v128, v112, v113
	v_cvt_pk_bf16_f32 v129, v114, v115
	ds_write_b64 v140, v[128:129] offset:0
	v_cvt_pk_bf16_f32 v132, v116, v117
	v_cvt_pk_bf16_f32 v133, v118, v119
	ds_write_b64 v140, v[132:133] offset:16
	v_pk_mul_f32 v[128:129], v[120:121], v[120:121]
	v_pk_mul_f32 v[130:131], v[122:123], v[122:123]
	v_pk_mul_f32 v[132:133], v[124:125], v[124:125]
	v_pk_mul_f32 v[134:135], v[126:127], v[126:127]
	v_pk_fma_f32 v[128:129], v[128:129], v[138:139], v[136:137]
	v_pk_fma_f32 v[130:131], v[130:131], v[138:139], v[136:137]
	v_pk_fma_f32 v[132:133], v[132:133], v[138:139], v[136:137]
	v_pk_fma_f32 v[134:135], v[134:135], v[138:139], v[136:137]
	v_pk_mul_f32 v[128:129], v[128:129], v[120:121]
	v_pk_mul_f32 v[130:131], v[130:131], v[122:123]
	v_pk_mul_f32 v[132:133], v[132:133], v[124:125]
	v_pk_mul_f32 v[134:135], v[134:135], v[126:127]
	v_exp_f32_e32 v128, v128
	v_exp_f32_e32 v129, v129
	v_exp_f32_e32 v130, v130
	v_exp_f32_e32 v131, v131
	v_exp_f32_e32 v132, v132
	v_exp_f32_e32 v133, v133
	v_exp_f32_e32 v134, v134
	v_exp_f32_e32 v135, v135
	s_nop 0
	v_pk_add_f32 v[128:129], v[128:129], 1.0 op_sel_hi:[1,0]
	v_pk_add_f32 v[130:131], v[130:131], 1.0 op_sel_hi:[1,0]
	v_pk_add_f32 v[132:133], v[132:133], 1.0 op_sel_hi:[1,0]
	v_pk_add_f32 v[134:135], v[134:135], 1.0 op_sel_hi:[1,0]
	v_rcp_f32_e32 v128, v128
	v_rcp_f32_e32 v129, v129
	v_rcp_f32_e32 v130, v130
	v_rcp_f32_e32 v131, v131
	v_rcp_f32_e32 v132, v132
	v_rcp_f32_e32 v133, v133
	v_rcp_f32_e32 v134, v134
	v_rcp_f32_e32 v135, v135
	s_nop 0
	v_pk_fma_f32 v[120:121], v[120:121], v[128:129], v[120:121] neg_lo:[1,0,0] neg_hi:[1,0,0]
	v_pk_fma_f32 v[122:123], v[122:123], v[130:131], v[122:123] neg_lo:[1,0,0] neg_hi:[1,0,0]
	v_pk_fma_f32 v[124:125], v[124:125], v[132:133], v[124:125] neg_lo:[1,0,0] neg_hi:[1,0,0]
	v_pk_fma_f32 v[126:127], v[126:127], v[134:135], v[126:127] neg_lo:[1,0,0] neg_hi:[1,0,0]
	v_cvt_pk_bf16_f32 v128, v120, v121
	v_cvt_pk_bf16_f32 v129, v122, v123
	ds_write_b64 v140, v[128:129] offset:32
	v_cvt_pk_bf16_f32 v132, v124, v125
	v_cvt_pk_bf16_f32 v133, v126, v127
	ds_write_b64 v140, v[132:133] offset:48
	v_pk_mul_f32 v[128:129], v[80:81], v[80:81]
	v_pk_mul_f32 v[130:131], v[82:83], v[82:83]
	v_pk_mul_f32 v[132:133], v[84:85], v[84:85]
	v_pk_mul_f32 v[134:135], v[86:87], v[86:87]
	v_pk_fma_f32 v[128:129], v[128:129], v[138:139], v[136:137]
	v_pk_fma_f32 v[130:131], v[130:131], v[138:139], v[136:137]
	v_pk_fma_f32 v[132:133], v[132:133], v[138:139], v[136:137]
	v_pk_fma_f32 v[134:135], v[134:135], v[138:139], v[136:137]
	v_pk_mul_f32 v[128:129], v[128:129], v[80:81]
	v_pk_mul_f32 v[130:131], v[130:131], v[82:83]
	v_pk_mul_f32 v[132:133], v[132:133], v[84:85]
	v_pk_mul_f32 v[134:135], v[134:135], v[86:87]
	v_exp_f32_e32 v128, v128
	v_exp_f32_e32 v129, v129
	v_exp_f32_e32 v130, v130
	v_exp_f32_e32 v131, v131
	v_exp_f32_e32 v132, v132
	v_exp_f32_e32 v133, v133
	v_exp_f32_e32 v134, v134
	v_exp_f32_e32 v135, v135
	s_nop 0
	v_pk_add_f32 v[128:129], v[128:129], 1.0 op_sel_hi:[1,0]
	v_pk_add_f32 v[130:131], v[130:131], 1.0 op_sel_hi:[1,0]
	v_pk_add_f32 v[132:133], v[132:133], 1.0 op_sel_hi:[1,0]
	v_pk_add_f32 v[134:135], v[134:135], 1.0 op_sel_hi:[1,0]
	v_rcp_f32_e32 v128, v128
	v_rcp_f32_e32 v129, v129
	v_rcp_f32_e32 v130, v130
	v_rcp_f32_e32 v131, v131
	v_rcp_f32_e32 v132, v132
	v_rcp_f32_e32 v133, v133
	v_rcp_f32_e32 v134, v134
	v_rcp_f32_e32 v135, v135
	s_nop 0
	v_pk_fma_f32 v[80:81], v[80:81], v[128:129], v[80:81] neg_lo:[1,0,0] neg_hi:[1,0,0]
	v_pk_fma_f32 v[82:83], v[82:83], v[130:131], v[82:83] neg_lo:[1,0,0] neg_hi:[1,0,0]
	v_pk_fma_f32 v[84:85], v[84:85], v[132:133], v[84:85] neg_lo:[1,0,0] neg_hi:[1,0,0]
	v_pk_fma_f32 v[86:87], v[86:87], v[134:135], v[86:87] neg_lo:[1,0,0] neg_hi:[1,0,0]
	v_cvt_pk_bf16_f32 v128, v80, v81
	v_cvt_pk_bf16_f32 v129, v82, v83
	ds_write_b64 v140, v[128:129] offset:64
	v_cvt_pk_bf16_f32 v132, v84, v85
	v_cvt_pk_bf16_f32 v133, v86, v87
	ds_write_b64 v140, v[132:133] offset:80
	v_pk_mul_f32 v[128:129], v[88:89], v[88:89]
	v_pk_mul_f32 v[130:131], v[90:91], v[90:91]
	v_pk_mul_f32 v[132:133], v[92:93], v[92:93]
	v_pk_mul_f32 v[134:135], v[94:95], v[94:95]
	v_pk_fma_f32 v[128:129], v[128:129], v[138:139], v[136:137]
	v_pk_fma_f32 v[130:131], v[130:131], v[138:139], v[136:137]
	v_pk_fma_f32 v[132:133], v[132:133], v[138:139], v[136:137]
	v_pk_fma_f32 v[134:135], v[134:135], v[138:139], v[136:137]
	v_pk_mul_f32 v[128:129], v[128:129], v[88:89]
	v_pk_mul_f32 v[130:131], v[130:131], v[90:91]
	v_pk_mul_f32 v[132:133], v[132:133], v[92:93]
	v_pk_mul_f32 v[134:135], v[134:135], v[94:95]
	v_exp_f32_e32 v128, v128
	v_exp_f32_e32 v129, v129
	v_exp_f32_e32 v130, v130
	v_exp_f32_e32 v131, v131
	v_exp_f32_e32 v132, v132
	v_exp_f32_e32 v133, v133
	v_exp_f32_e32 v134, v134
	v_exp_f32_e32 v135, v135
	s_nop 0
	v_pk_add_f32 v[128:129], v[128:129], 1.0 op_sel_hi:[1,0]
	v_pk_add_f32 v[130:131], v[130:131], 1.0 op_sel_hi:[1,0]
	v_pk_add_f32 v[132:133], v[132:133], 1.0 op_sel_hi:[1,0]
	v_pk_add_f32 v[134:135], v[134:135], 1.0 op_sel_hi:[1,0]
	v_rcp_f32_e32 v128, v128
	v_rcp_f32_e32 v129, v129
	v_rcp_f32_e32 v130, v130
	v_rcp_f32_e32 v131, v131
	v_rcp_f32_e32 v132, v132
	v_rcp_f32_e32 v133, v133
	v_rcp_f32_e32 v134, v134
	v_rcp_f32_e32 v135, v135
	s_nop 0
	v_pk_fma_f32 v[88:89], v[88:89], v[128:129], v[88:89] neg_lo:[1,0,0] neg_hi:[1,0,0]
	v_pk_fma_f32 v[90:91], v[90:91], v[130:131], v[90:91] neg_lo:[1,0,0] neg_hi:[1,0,0]
	v_pk_fma_f32 v[92:93], v[92:93], v[132:133], v[92:93] neg_lo:[1,0,0] neg_hi:[1,0,0]
	v_pk_fma_f32 v[94:95], v[94:95], v[134:135], v[94:95] neg_lo:[1,0,0] neg_hi:[1,0,0]
	v_cvt_pk_bf16_f32 v128, v88, v89
	v_cvt_pk_bf16_f32 v129, v90, v91
	ds_write_b64 v140, v[128:129] offset:96
	v_cvt_pk_bf16_f32 v132, v92, v93
	v_cvt_pk_bf16_f32 v133, v94, v95
	ds_write_b64 v140, v[132:133] offset:112
	v_pk_mul_f32 v[128:129], v[96:97], v[96:97]
	v_pk_mul_f32 v[130:131], v[98:99], v[98:99]
	v_pk_mul_f32 v[132:133], v[100:101], v[100:101]
	v_pk_mul_f32 v[134:135], v[102:103], v[102:103]
	v_pk_fma_f32 v[128:129], v[128:129], v[138:139], v[136:137]
	v_pk_fma_f32 v[130:131], v[130:131], v[138:139], v[136:137]
	v_pk_fma_f32 v[132:133], v[132:133], v[138:139], v[136:137]
	v_pk_fma_f32 v[134:135], v[134:135], v[138:139], v[136:137]
	v_pk_mul_f32 v[128:129], v[128:129], v[96:97]
	v_pk_mul_f32 v[130:131], v[130:131], v[98:99]
	v_pk_mul_f32 v[132:133], v[132:133], v[100:101]
	v_pk_mul_f32 v[134:135], v[134:135], v[102:103]
	v_exp_f32_e32 v128, v128
	v_exp_f32_e32 v129, v129
	v_exp_f32_e32 v130, v130
	v_exp_f32_e32 v131, v131
	v_exp_f32_e32 v132, v132
	v_exp_f32_e32 v133, v133
	v_exp_f32_e32 v134, v134
	v_exp_f32_e32 v135, v135
	s_nop 0
	v_pk_add_f32 v[128:129], v[128:129], 1.0 op_sel_hi:[1,0]
	v_pk_add_f32 v[130:131], v[130:131], 1.0 op_sel_hi:[1,0]
	v_pk_add_f32 v[132:133], v[132:133], 1.0 op_sel_hi:[1,0]
	v_pk_add_f32 v[134:135], v[134:135], 1.0 op_sel_hi:[1,0]
	v_rcp_f32_e32 v128, v128
	v_rcp_f32_e32 v129, v129
	v_rcp_f32_e32 v130, v130
	v_rcp_f32_e32 v131, v131
	v_rcp_f32_e32 v132, v132
	v_rcp_f32_e32 v133, v133
	v_rcp_f32_e32 v134, v134
	v_rcp_f32_e32 v135, v135
	s_nop 0
	v_pk_fma_f32 v[96:97], v[96:97], v[128:129], v[96:97] neg_lo:[1,0,0] neg_hi:[1,0,0]
	v_pk_fma_f32 v[98:99], v[98:99], v[130:131], v[98:99] neg_lo:[1,0,0] neg_hi:[1,0,0]
	v_pk_fma_f32 v[100:101], v[100:101], v[132:133], v[100:101] neg_lo:[1,0,0] neg_hi:[1,0,0]
	v_pk_fma_f32 v[102:103], v[102:103], v[134:135], v[102:103] neg_lo:[1,0,0] neg_hi:[1,0,0]
	v_cvt_pk_bf16_f32 v128, v96, v97
	v_cvt_pk_bf16_f32 v129, v98, v99
	ds_write_b64 v140, v[128:129] offset:128
	v_cvt_pk_bf16_f32 v132, v100, v101
	v_cvt_pk_bf16_f32 v133, v102, v103
	ds_write_b64 v140, v[132:133] offset:144
	v_pk_mul_f32 v[128:129], v[104:105], v[104:105]
	v_pk_mul_f32 v[130:131], v[106:107], v[106:107]
	v_pk_mul_f32 v[132:133], v[108:109], v[108:109]
	v_pk_mul_f32 v[134:135], v[110:111], v[110:111]
	v_pk_fma_f32 v[128:129], v[128:129], v[138:139], v[136:137]
	v_pk_fma_f32 v[130:131], v[130:131], v[138:139], v[136:137]
	v_pk_fma_f32 v[132:133], v[132:133], v[138:139], v[136:137]
	v_pk_fma_f32 v[134:135], v[134:135], v[138:139], v[136:137]
	v_pk_mul_f32 v[128:129], v[128:129], v[104:105]
	v_pk_mul_f32 v[130:131], v[130:131], v[106:107]
	v_pk_mul_f32 v[132:133], v[132:133], v[108:109]
	v_pk_mul_f32 v[134:135], v[134:135], v[110:111]
	v_exp_f32_e32 v128, v128
	v_exp_f32_e32 v129, v129
	v_exp_f32_e32 v130, v130
	v_exp_f32_e32 v131, v131
	v_exp_f32_e32 v132, v132
	v_exp_f32_e32 v133, v133
	v_exp_f32_e32 v134, v134
	v_exp_f32_e32 v135, v135
	s_nop 0
	v_pk_add_f32 v[128:129], v[128:129], 1.0 op_sel_hi:[1,0]
	v_pk_add_f32 v[130:131], v[130:131], 1.0 op_sel_hi:[1,0]
	v_pk_add_f32 v[132:133], v[132:133], 1.0 op_sel_hi:[1,0]
	v_pk_add_f32 v[134:135], v[134:135], 1.0 op_sel_hi:[1,0]
	v_rcp_f32_e32 v128, v128
	v_rcp_f32_e32 v129, v129
	v_rcp_f32_e32 v130, v130
	v_rcp_f32_e32 v131, v131
	v_rcp_f32_e32 v132, v132
	v_rcp_f32_e32 v133, v133
	v_rcp_f32_e32 v134, v134
	v_rcp_f32_e32 v135, v135
	s_nop 0
	v_pk_fma_f32 v[104:105], v[104:105], v[128:129], v[104:105] neg_lo:[1,0,0] neg_hi:[1,0,0]
	v_pk_fma_f32 v[106:107], v[106:107], v[130:131], v[106:107] neg_lo:[1,0,0] neg_hi:[1,0,0]
	v_pk_fma_f32 v[108:109], v[108:109], v[132:133], v[108:109] neg_lo:[1,0,0] neg_hi:[1,0,0]
	v_pk_fma_f32 v[110:111], v[110:111], v[134:135], v[110:111] neg_lo:[1,0,0] neg_hi:[1,0,0]
	v_cvt_pk_bf16_f32 v128, v104, v105
	v_cvt_pk_bf16_f32 v129, v106, v107
	ds_write_b64 v140, v[128:129] offset:160
	v_cvt_pk_bf16_f32 v132, v108, v109
	v_cvt_pk_bf16_f32 v133, v110, v111
	ds_write_b64 v140, v[132:133] offset:176
	v_pk_mul_f32 v[128:129], v[64:65], v[64:65]
	v_pk_mul_f32 v[130:131], v[66:67], v[66:67]
	v_pk_mul_f32 v[132:133], v[68:69], v[68:69]
	v_pk_mul_f32 v[134:135], v[70:71], v[70:71]
	v_pk_fma_f32 v[128:129], v[128:129], v[138:139], v[136:137]
	v_pk_fma_f32 v[130:131], v[130:131], v[138:139], v[136:137]
	v_pk_fma_f32 v[132:133], v[132:133], v[138:139], v[136:137]
	v_pk_fma_f32 v[134:135], v[134:135], v[138:139], v[136:137]
	v_pk_mul_f32 v[128:129], v[128:129], v[64:65]
	v_pk_mul_f32 v[130:131], v[130:131], v[66:67]
	v_pk_mul_f32 v[132:133], v[132:133], v[68:69]
	v_pk_mul_f32 v[134:135], v[134:135], v[70:71]
	v_exp_f32_e32 v128, v128
	v_exp_f32_e32 v129, v129
	v_exp_f32_e32 v130, v130
	v_exp_f32_e32 v131, v131
	v_exp_f32_e32 v132, v132
	v_exp_f32_e32 v133, v133
	v_exp_f32_e32 v134, v134
	v_exp_f32_e32 v135, v135
	s_nop 0
	v_pk_add_f32 v[128:129], v[128:129], 1.0 op_sel_hi:[1,0]
	v_pk_add_f32 v[130:131], v[130:131], 1.0 op_sel_hi:[1,0]
	v_pk_add_f32 v[132:133], v[132:133], 1.0 op_sel_hi:[1,0]
	v_pk_add_f32 v[134:135], v[134:135], 1.0 op_sel_hi:[1,0]
	v_rcp_f32_e32 v128, v128
	v_rcp_f32_e32 v129, v129
	v_rcp_f32_e32 v130, v130
	v_rcp_f32_e32 v131, v131
	v_rcp_f32_e32 v132, v132
	v_rcp_f32_e32 v133, v133
	v_rcp_f32_e32 v134, v134
	v_rcp_f32_e32 v135, v135
	s_nop 0
	v_pk_fma_f32 v[64:65], v[64:65], v[128:129], v[64:65] neg_lo:[1,0,0] neg_hi:[1,0,0]
	v_pk_fma_f32 v[66:67], v[66:67], v[130:131], v[66:67] neg_lo:[1,0,0] neg_hi:[1,0,0]
	v_pk_fma_f32 v[68:69], v[68:69], v[132:133], v[68:69] neg_lo:[1,0,0] neg_hi:[1,0,0]
	v_pk_fma_f32 v[70:71], v[70:71], v[134:135], v[70:71] neg_lo:[1,0,0] neg_hi:[1,0,0]
	v_cvt_pk_bf16_f32 v128, v64, v65
	v_cvt_pk_bf16_f32 v129, v66, v67
	ds_write_b64 v140, v[128:129] offset:192
	v_cvt_pk_bf16_f32 v132, v68, v69
	v_cvt_pk_bf16_f32 v133, v70, v71
	ds_write_b64 v140, v[132:133] offset:208
	v_pk_mul_f32 v[128:129], v[72:73], v[72:73]
	v_pk_mul_f32 v[130:131], v[74:75], v[74:75]
	v_pk_mul_f32 v[132:133], v[76:77], v[76:77]
	v_pk_mul_f32 v[134:135], v[78:79], v[78:79]
	v_pk_fma_f32 v[128:129], v[128:129], v[138:139], v[136:137]
	v_pk_fma_f32 v[130:131], v[130:131], v[138:139], v[136:137]
	v_pk_fma_f32 v[132:133], v[132:133], v[138:139], v[136:137]
	v_pk_fma_f32 v[134:135], v[134:135], v[138:139], v[136:137]
	v_pk_mul_f32 v[128:129], v[128:129], v[72:73]
	v_pk_mul_f32 v[130:131], v[130:131], v[74:75]
	v_pk_mul_f32 v[132:133], v[132:133], v[76:77]
	v_pk_mul_f32 v[134:135], v[134:135], v[78:79]
	v_exp_f32_e32 v128, v128
	v_exp_f32_e32 v129, v129
	v_exp_f32_e32 v130, v130
	v_exp_f32_e32 v131, v131
	v_exp_f32_e32 v132, v132
	v_exp_f32_e32 v133, v133
	v_exp_f32_e32 v134, v134
	v_exp_f32_e32 v135, v135
	s_nop 0
	v_pk_add_f32 v[128:129], v[128:129], 1.0 op_sel_hi:[1,0]
	v_pk_add_f32 v[130:131], v[130:131], 1.0 op_sel_hi:[1,0]
	v_pk_add_f32 v[132:133], v[132:133], 1.0 op_sel_hi:[1,0]
	v_pk_add_f32 v[134:135], v[134:135], 1.0 op_sel_hi:[1,0]
	v_rcp_f32_e32 v128, v128
	v_rcp_f32_e32 v129, v129
	v_rcp_f32_e32 v130, v130
	v_rcp_f32_e32 v131, v131
	v_rcp_f32_e32 v132, v132
	v_rcp_f32_e32 v133, v133
	v_rcp_f32_e32 v134, v134
	v_rcp_f32_e32 v135, v135
	s_nop 0
	v_pk_fma_f32 v[72:73], v[72:73], v[128:129], v[72:73] neg_lo:[1,0,0] neg_hi:[1,0,0]
	v_pk_fma_f32 v[74:75], v[74:75], v[130:131], v[74:75] neg_lo:[1,0,0] neg_hi:[1,0,0]
	v_pk_fma_f32 v[76:77], v[76:77], v[132:133], v[76:77] neg_lo:[1,0,0] neg_hi:[1,0,0]
	v_pk_fma_f32 v[78:79], v[78:79], v[134:135], v[78:79] neg_lo:[1,0,0] neg_hi:[1,0,0]
	v_cvt_pk_bf16_f32 v128, v72, v73
	v_cvt_pk_bf16_f32 v129, v74, v75
	ds_write_b64 v140, v[128:129] offset:224
	v_cvt_pk_bf16_f32 v132, v76, v77
	v_cvt_pk_bf16_f32 v133, v78, v79
	ds_write_b64 v140, v[132:133] offset:240
	v_pk_mul_f32 v[128:129], v[48:49], v[48:49]
	v_pk_mul_f32 v[130:131], v[50:51], v[50:51]
	v_pk_mul_f32 v[132:133], v[52:53], v[52:53]
	v_pk_mul_f32 v[134:135], v[54:55], v[54:55]
	v_pk_fma_f32 v[128:129], v[128:129], v[138:139], v[136:137]
	v_pk_fma_f32 v[130:131], v[130:131], v[138:139], v[136:137]
	v_pk_fma_f32 v[132:133], v[132:133], v[138:139], v[136:137]
	v_pk_fma_f32 v[134:135], v[134:135], v[138:139], v[136:137]
	v_pk_mul_f32 v[128:129], v[128:129], v[48:49]
	v_pk_mul_f32 v[130:131], v[130:131], v[50:51]
	v_pk_mul_f32 v[132:133], v[132:133], v[52:53]
	v_pk_mul_f32 v[134:135], v[134:135], v[54:55]
	v_exp_f32_e32 v128, v128
	v_exp_f32_e32 v129, v129
	v_exp_f32_e32 v130, v130
	v_exp_f32_e32 v131, v131
	v_exp_f32_e32 v132, v132
	v_exp_f32_e32 v133, v133
	v_exp_f32_e32 v134, v134
	v_exp_f32_e32 v135, v135
	s_nop 0
	v_pk_add_f32 v[128:129], v[128:129], 1.0 op_sel_hi:[1,0]
	v_pk_add_f32 v[130:131], v[130:131], 1.0 op_sel_hi:[1,0]
	v_pk_add_f32 v[132:133], v[132:133], 1.0 op_sel_hi:[1,0]
	v_pk_add_f32 v[134:135], v[134:135], 1.0 op_sel_hi:[1,0]
	v_rcp_f32_e32 v128, v128
	v_rcp_f32_e32 v129, v129
	v_rcp_f32_e32 v130, v130
	v_rcp_f32_e32 v131, v131
	v_rcp_f32_e32 v132, v132
	v_rcp_f32_e32 v133, v133
	v_rcp_f32_e32 v134, v134
	v_rcp_f32_e32 v135, v135
	s_nop 0
	v_pk_fma_f32 v[48:49], v[48:49], v[128:129], v[48:49] neg_lo:[1,0,0] neg_hi:[1,0,0]
	v_pk_fma_f32 v[50:51], v[50:51], v[130:131], v[50:51] neg_lo:[1,0,0] neg_hi:[1,0,0]
	v_pk_fma_f32 v[52:53], v[52:53], v[132:133], v[52:53] neg_lo:[1,0,0] neg_hi:[1,0,0]
	v_pk_fma_f32 v[54:55], v[54:55], v[134:135], v[54:55] neg_lo:[1,0,0] neg_hi:[1,0,0]
	v_cvt_pk_bf16_f32 v128, v48, v49
	v_cvt_pk_bf16_f32 v129, v50, v51
	ds_write_b64 v140, v[128:129] offset:16896
	v_cvt_pk_bf16_f32 v132, v52, v53
	v_cvt_pk_bf16_f32 v133, v54, v55
	ds_write_b64 v140, v[132:133] offset:16912
	v_pk_mul_f32 v[128:129], v[56:57], v[56:57]
	v_pk_mul_f32 v[130:131], v[58:59], v[58:59]
	v_pk_mul_f32 v[132:133], v[60:61], v[60:61]
	v_pk_mul_f32 v[134:135], v[62:63], v[62:63]
	v_pk_fma_f32 v[128:129], v[128:129], v[138:139], v[136:137]
	v_pk_fma_f32 v[130:131], v[130:131], v[138:139], v[136:137]
	v_pk_fma_f32 v[132:133], v[132:133], v[138:139], v[136:137]
	v_pk_fma_f32 v[134:135], v[134:135], v[138:139], v[136:137]
	v_pk_mul_f32 v[128:129], v[128:129], v[56:57]
	v_pk_mul_f32 v[130:131], v[130:131], v[58:59]
	v_pk_mul_f32 v[132:133], v[132:133], v[60:61]
	v_pk_mul_f32 v[134:135], v[134:135], v[62:63]
	v_exp_f32_e32 v128, v128
	v_exp_f32_e32 v129, v129
	v_exp_f32_e32 v130, v130
	v_exp_f32_e32 v131, v131
	v_exp_f32_e32 v132, v132
	v_exp_f32_e32 v133, v133
	v_exp_f32_e32 v134, v134
	v_exp_f32_e32 v135, v135
	s_nop 0
	v_pk_add_f32 v[128:129], v[128:129], 1.0 op_sel_hi:[1,0]
	v_pk_add_f32 v[130:131], v[130:131], 1.0 op_sel_hi:[1,0]
	v_pk_add_f32 v[132:133], v[132:133], 1.0 op_sel_hi:[1,0]
	v_pk_add_f32 v[134:135], v[134:135], 1.0 op_sel_hi:[1,0]
	v_rcp_f32_e32 v128, v128
	v_rcp_f32_e32 v129, v129
	v_rcp_f32_e32 v130, v130
	v_rcp_f32_e32 v131, v131
	v_rcp_f32_e32 v132, v132
	v_rcp_f32_e32 v133, v133
	v_rcp_f32_e32 v134, v134
	v_rcp_f32_e32 v135, v135
	s_nop 0
	v_pk_fma_f32 v[56:57], v[56:57], v[128:129], v[56:57] neg_lo:[1,0,0] neg_hi:[1,0,0]
	v_pk_fma_f32 v[58:59], v[58:59], v[130:131], v[58:59] neg_lo:[1,0,0] neg_hi:[1,0,0]
	v_pk_fma_f32 v[60:61], v[60:61], v[132:133], v[60:61] neg_lo:[1,0,0] neg_hi:[1,0,0]
	v_pk_fma_f32 v[62:63], v[62:63], v[134:135], v[62:63] neg_lo:[1,0,0] neg_hi:[1,0,0]
	v_cvt_pk_bf16_f32 v128, v56, v57
	v_cvt_pk_bf16_f32 v129, v58, v59
	ds_write_b64 v140, v[128:129] offset:16928
	v_cvt_pk_bf16_f32 v132, v60, v61
	v_cvt_pk_bf16_f32 v133, v62, v63
	ds_write_b64 v140, v[132:133] offset:16944
	v_pk_mul_f32 v[128:129], v[16:17], v[16:17]
	v_pk_mul_f32 v[130:131], v[18:19], v[18:19]
	v_pk_mul_f32 v[132:133], v[20:21], v[20:21]
	v_pk_mul_f32 v[134:135], v[22:23], v[22:23]
	v_pk_fma_f32 v[128:129], v[128:129], v[138:139], v[136:137]
	v_pk_fma_f32 v[130:131], v[130:131], v[138:139], v[136:137]
	v_pk_fma_f32 v[132:133], v[132:133], v[138:139], v[136:137]
	v_pk_fma_f32 v[134:135], v[134:135], v[138:139], v[136:137]
	v_pk_mul_f32 v[128:129], v[128:129], v[16:17]
	v_pk_mul_f32 v[130:131], v[130:131], v[18:19]
	v_pk_mul_f32 v[132:133], v[132:133], v[20:21]
	v_pk_mul_f32 v[134:135], v[134:135], v[22:23]
	v_exp_f32_e32 v128, v128
	v_exp_f32_e32 v129, v129
	v_exp_f32_e32 v130, v130
	v_exp_f32_e32 v131, v131
	v_exp_f32_e32 v132, v132
	v_exp_f32_e32 v133, v133
	v_exp_f32_e32 v134, v134
	v_exp_f32_e32 v135, v135
	s_nop 0
	v_pk_add_f32 v[128:129], v[128:129], 1.0 op_sel_hi:[1,0]
	v_pk_add_f32 v[130:131], v[130:131], 1.0 op_sel_hi:[1,0]
	v_pk_add_f32 v[132:133], v[132:133], 1.0 op_sel_hi:[1,0]
	v_pk_add_f32 v[134:135], v[134:135], 1.0 op_sel_hi:[1,0]
	v_rcp_f32_e32 v128, v128
	v_rcp_f32_e32 v129, v129
	v_rcp_f32_e32 v130, v130
	v_rcp_f32_e32 v131, v131
	v_rcp_f32_e32 v132, v132
	v_rcp_f32_e32 v133, v133
	v_rcp_f32_e32 v134, v134
	v_rcp_f32_e32 v135, v135
	s_nop 0
	v_pk_fma_f32 v[16:17], v[16:17], v[128:129], v[16:17] neg_lo:[1,0,0] neg_hi:[1,0,0]
	v_pk_fma_f32 v[18:19], v[18:19], v[130:131], v[18:19] neg_lo:[1,0,0] neg_hi:[1,0,0]
	v_pk_fma_f32 v[20:21], v[20:21], v[132:133], v[20:21] neg_lo:[1,0,0] neg_hi:[1,0,0]
	v_pk_fma_f32 v[22:23], v[22:23], v[134:135], v[22:23] neg_lo:[1,0,0] neg_hi:[1,0,0]
	v_cvt_pk_bf16_f32 v128, v16, v17
	v_cvt_pk_bf16_f32 v129, v18, v19
	ds_write_b64 v140, v[128:129] offset:16960
	v_cvt_pk_bf16_f32 v132, v20, v21
	v_cvt_pk_bf16_f32 v133, v22, v23
	ds_write_b64 v140, v[132:133] offset:16976
	v_pk_mul_f32 v[128:129], v[24:25], v[24:25]
	v_pk_mul_f32 v[130:131], v[26:27], v[26:27]
	v_pk_mul_f32 v[132:133], v[28:29], v[28:29]
	v_pk_mul_f32 v[134:135], v[30:31], v[30:31]
	v_pk_fma_f32 v[128:129], v[128:129], v[138:139], v[136:137]
	v_pk_fma_f32 v[130:131], v[130:131], v[138:139], v[136:137]
	v_pk_fma_f32 v[132:133], v[132:133], v[138:139], v[136:137]
	v_pk_fma_f32 v[134:135], v[134:135], v[138:139], v[136:137]
	v_pk_mul_f32 v[128:129], v[128:129], v[24:25]
	v_pk_mul_f32 v[130:131], v[130:131], v[26:27]
	v_pk_mul_f32 v[132:133], v[132:133], v[28:29]
	v_pk_mul_f32 v[134:135], v[134:135], v[30:31]
	v_exp_f32_e32 v128, v128
	v_exp_f32_e32 v129, v129
	v_exp_f32_e32 v130, v130
	v_exp_f32_e32 v131, v131
	v_exp_f32_e32 v132, v132
	v_exp_f32_e32 v133, v133
	v_exp_f32_e32 v134, v134
	v_exp_f32_e32 v135, v135
	s_nop 0
	v_pk_add_f32 v[128:129], v[128:129], 1.0 op_sel_hi:[1,0]
	v_pk_add_f32 v[130:131], v[130:131], 1.0 op_sel_hi:[1,0]
	v_pk_add_f32 v[132:133], v[132:133], 1.0 op_sel_hi:[1,0]
	v_pk_add_f32 v[134:135], v[134:135], 1.0 op_sel_hi:[1,0]
	v_rcp_f32_e32 v128, v128
	v_rcp_f32_e32 v129, v129
	v_rcp_f32_e32 v130, v130
	v_rcp_f32_e32 v131, v131
	v_rcp_f32_e32 v132, v132
	v_rcp_f32_e32 v133, v133
	v_rcp_f32_e32 v134, v134
	v_rcp_f32_e32 v135, v135
	s_nop 0
	v_pk_fma_f32 v[24:25], v[24:25], v[128:129], v[24:25] neg_lo:[1,0,0] neg_hi:[1,0,0]
	v_pk_fma_f32 v[26:27], v[26:27], v[130:131], v[26:27] neg_lo:[1,0,0] neg_hi:[1,0,0]
	v_pk_fma_f32 v[28:29], v[28:29], v[132:133], v[28:29] neg_lo:[1,0,0] neg_hi:[1,0,0]
	v_pk_fma_f32 v[30:31], v[30:31], v[134:135], v[30:31] neg_lo:[1,0,0] neg_hi:[1,0,0]
	v_cvt_pk_bf16_f32 v128, v24, v25
	v_cvt_pk_bf16_f32 v129, v26, v27
	ds_write_b64 v140, v[128:129] offset:16992
	v_cvt_pk_bf16_f32 v132, v28, v29
	v_cvt_pk_bf16_f32 v133, v30, v31
	ds_write_b64 v140, v[132:133] offset:17008
	v_pk_mul_f32 v[128:129], v[32:33], v[32:33]
	v_pk_mul_f32 v[130:131], v[34:35], v[34:35]
	v_pk_mul_f32 v[132:133], v[36:37], v[36:37]
	v_pk_mul_f32 v[134:135], v[38:39], v[38:39]
	v_pk_fma_f32 v[128:129], v[128:129], v[138:139], v[136:137]
	v_pk_fma_f32 v[130:131], v[130:131], v[138:139], v[136:137]
	v_pk_fma_f32 v[132:133], v[132:133], v[138:139], v[136:137]
	v_pk_fma_f32 v[134:135], v[134:135], v[138:139], v[136:137]
	v_pk_mul_f32 v[128:129], v[128:129], v[32:33]
	v_pk_mul_f32 v[130:131], v[130:131], v[34:35]
	v_pk_mul_f32 v[132:133], v[132:133], v[36:37]
	v_pk_mul_f32 v[134:135], v[134:135], v[38:39]
	v_exp_f32_e32 v128, v128
	v_exp_f32_e32 v129, v129
	v_exp_f32_e32 v130, v130
	v_exp_f32_e32 v131, v131
	v_exp_f32_e32 v132, v132
	v_exp_f32_e32 v133, v133
	v_exp_f32_e32 v134, v134
	v_exp_f32_e32 v135, v135
	s_nop 0
	v_pk_add_f32 v[128:129], v[128:129], 1.0 op_sel_hi:[1,0]
	v_pk_add_f32 v[130:131], v[130:131], 1.0 op_sel_hi:[1,0]
	v_pk_add_f32 v[132:133], v[132:133], 1.0 op_sel_hi:[1,0]
	v_pk_add_f32 v[134:135], v[134:135], 1.0 op_sel_hi:[1,0]
	v_rcp_f32_e32 v128, v128
	v_rcp_f32_e32 v129, v129
	v_rcp_f32_e32 v130, v130
	v_rcp_f32_e32 v131, v131
	v_rcp_f32_e32 v132, v132
	v_rcp_f32_e32 v133, v133
	v_rcp_f32_e32 v134, v134
	v_rcp_f32_e32 v135, v135
	s_nop 0
	v_pk_fma_f32 v[32:33], v[32:33], v[128:129], v[32:33] neg_lo:[1,0,0] neg_hi:[1,0,0]
	v_pk_fma_f32 v[34:35], v[34:35], v[130:131], v[34:35] neg_lo:[1,0,0] neg_hi:[1,0,0]
	v_pk_fma_f32 v[36:37], v[36:37], v[132:133], v[36:37] neg_lo:[1,0,0] neg_hi:[1,0,0]
	v_pk_fma_f32 v[38:39], v[38:39], v[134:135], v[38:39] neg_lo:[1,0,0] neg_hi:[1,0,0]
	v_cvt_pk_bf16_f32 v128, v32, v33
	v_cvt_pk_bf16_f32 v129, v34, v35
	ds_write_b64 v140, v[128:129] offset:17024
	v_cvt_pk_bf16_f32 v132, v36, v37
	v_cvt_pk_bf16_f32 v133, v38, v39
	ds_write_b64 v140, v[132:133] offset:17040
	v_pk_mul_f32 v[128:129], v[40:41], v[40:41]
	v_pk_mul_f32 v[130:131], v[42:43], v[42:43]
	v_pk_mul_f32 v[132:133], v[44:45], v[44:45]
	v_pk_mul_f32 v[134:135], v[46:47], v[46:47]
	v_pk_fma_f32 v[128:129], v[128:129], v[138:139], v[136:137]
	v_pk_fma_f32 v[130:131], v[130:131], v[138:139], v[136:137]
	v_pk_fma_f32 v[132:133], v[132:133], v[138:139], v[136:137]
	v_pk_fma_f32 v[134:135], v[134:135], v[138:139], v[136:137]
	v_pk_mul_f32 v[128:129], v[128:129], v[40:41]
	v_pk_mul_f32 v[130:131], v[130:131], v[42:43]
	v_pk_mul_f32 v[132:133], v[132:133], v[44:45]
	v_pk_mul_f32 v[134:135], v[134:135], v[46:47]
	v_exp_f32_e32 v128, v128
	v_exp_f32_e32 v129, v129
	v_exp_f32_e32 v130, v130
	v_exp_f32_e32 v131, v131
	v_exp_f32_e32 v132, v132
	v_exp_f32_e32 v133, v133
	v_exp_f32_e32 v134, v134
	v_exp_f32_e32 v135, v135
	s_nop 0
	v_pk_add_f32 v[128:129], v[128:129], 1.0 op_sel_hi:[1,0]
	v_pk_add_f32 v[130:131], v[130:131], 1.0 op_sel_hi:[1,0]
	v_pk_add_f32 v[132:133], v[132:133], 1.0 op_sel_hi:[1,0]
	v_pk_add_f32 v[134:135], v[134:135], 1.0 op_sel_hi:[1,0]
	v_rcp_f32_e32 v128, v128
	v_rcp_f32_e32 v129, v129
	v_rcp_f32_e32 v130, v130
	v_rcp_f32_e32 v131, v131
	v_rcp_f32_e32 v132, v132
	v_rcp_f32_e32 v133, v133
	v_rcp_f32_e32 v134, v134
	v_rcp_f32_e32 v135, v135
	s_nop 0
	v_pk_fma_f32 v[40:41], v[40:41], v[128:129], v[40:41] neg_lo:[1,0,0] neg_hi:[1,0,0]
	v_pk_fma_f32 v[42:43], v[42:43], v[130:131], v[42:43] neg_lo:[1,0,0] neg_hi:[1,0,0]
	v_pk_fma_f32 v[44:45], v[44:45], v[132:133], v[44:45] neg_lo:[1,0,0] neg_hi:[1,0,0]
	v_pk_fma_f32 v[46:47], v[46:47], v[134:135], v[46:47] neg_lo:[1,0,0] neg_hi:[1,0,0]
	v_cvt_pk_bf16_f32 v128, v40, v41
	v_cvt_pk_bf16_f32 v129, v42, v43
	ds_write_b64 v140, v[128:129] offset:17056
	v_cvt_pk_bf16_f32 v132, v44, v45
	v_cvt_pk_bf16_f32 v133, v46, v47
	ds_write_b64 v140, v[132:133] offset:17072
	v_pk_mul_f32 v[128:129], v[0:1], v[0:1]
	v_pk_mul_f32 v[130:131], v[2:3], v[2:3]
	v_pk_mul_f32 v[132:133], v[4:5], v[4:5]
	v_pk_mul_f32 v[134:135], v[6:7], v[6:7]
	v_pk_fma_f32 v[128:129], v[128:129], v[138:139], v[136:137]
	v_pk_fma_f32 v[130:131], v[130:131], v[138:139], v[136:137]
	v_pk_fma_f32 v[132:133], v[132:133], v[138:139], v[136:137]
	v_pk_fma_f32 v[134:135], v[134:135], v[138:139], v[136:137]
	v_pk_mul_f32 v[128:129], v[128:129], v[0:1]
	v_pk_mul_f32 v[130:131], v[130:131], v[2:3]
	v_pk_mul_f32 v[132:133], v[132:133], v[4:5]
	v_pk_mul_f32 v[134:135], v[134:135], v[6:7]
	v_exp_f32_e32 v128, v128
	v_exp_f32_e32 v129, v129
	v_exp_f32_e32 v130, v130
	v_exp_f32_e32 v131, v131
	v_exp_f32_e32 v132, v132
	v_exp_f32_e32 v133, v133
	v_exp_f32_e32 v134, v134
	v_exp_f32_e32 v135, v135
	s_nop 0
	v_pk_add_f32 v[128:129], v[128:129], 1.0 op_sel_hi:[1,0]
	v_pk_add_f32 v[130:131], v[130:131], 1.0 op_sel_hi:[1,0]
	v_pk_add_f32 v[132:133], v[132:133], 1.0 op_sel_hi:[1,0]
	v_pk_add_f32 v[134:135], v[134:135], 1.0 op_sel_hi:[1,0]
	v_rcp_f32_e32 v128, v128
	v_rcp_f32_e32 v129, v129
	v_rcp_f32_e32 v130, v130
	v_rcp_f32_e32 v131, v131
	v_rcp_f32_e32 v132, v132
	v_rcp_f32_e32 v133, v133
	v_rcp_f32_e32 v134, v134
	v_rcp_f32_e32 v135, v135
	s_nop 0
	v_pk_fma_f32 v[0:1], v[0:1], v[128:129], v[0:1] neg_lo:[1,0,0] neg_hi:[1,0,0]
	v_pk_fma_f32 v[2:3], v[2:3], v[130:131], v[2:3] neg_lo:[1,0,0] neg_hi:[1,0,0]
	v_pk_fma_f32 v[4:5], v[4:5], v[132:133], v[4:5] neg_lo:[1,0,0] neg_hi:[1,0,0]
	v_pk_fma_f32 v[6:7], v[6:7], v[134:135], v[6:7] neg_lo:[1,0,0] neg_hi:[1,0,0]
	v_cvt_pk_bf16_f32 v128, v0, v1
	v_cvt_pk_bf16_f32 v129, v2, v3
	ds_write_b64 v140, v[128:129] offset:17088
	v_cvt_pk_bf16_f32 v132, v4, v5
	v_cvt_pk_bf16_f32 v133, v6, v7
	ds_write_b64 v140, v[132:133] offset:17104
	v_pk_mul_f32 v[128:129], v[8:9], v[8:9]
	v_pk_mul_f32 v[130:131], v[10:11], v[10:11]
	v_pk_mul_f32 v[132:133], v[12:13], v[12:13]
	v_pk_mul_f32 v[134:135], v[14:15], v[14:15]
	v_pk_fma_f32 v[128:129], v[128:129], v[138:139], v[136:137]
	v_pk_fma_f32 v[130:131], v[130:131], v[138:139], v[136:137]
	v_pk_fma_f32 v[132:133], v[132:133], v[138:139], v[136:137]
	v_pk_fma_f32 v[134:135], v[134:135], v[138:139], v[136:137]
	v_pk_mul_f32 v[128:129], v[128:129], v[8:9]
	v_pk_mul_f32 v[130:131], v[130:131], v[10:11]
	v_pk_mul_f32 v[132:133], v[132:133], v[12:13]
	v_pk_mul_f32 v[134:135], v[134:135], v[14:15]
	v_exp_f32_e32 v128, v128
	v_exp_f32_e32 v129, v129
	v_exp_f32_e32 v130, v130
	v_exp_f32_e32 v131, v131
	v_exp_f32_e32 v132, v132
	v_exp_f32_e32 v133, v133
	v_exp_f32_e32 v134, v134
	v_exp_f32_e32 v135, v135
	s_nop 0
	v_pk_add_f32 v[128:129], v[128:129], 1.0 op_sel_hi:[1,0]
	v_pk_add_f32 v[130:131], v[130:131], 1.0 op_sel_hi:[1,0]
	v_pk_add_f32 v[132:133], v[132:133], 1.0 op_sel_hi:[1,0]
	v_pk_add_f32 v[134:135], v[134:135], 1.0 op_sel_hi:[1,0]
	v_rcp_f32_e32 v128, v128
	v_rcp_f32_e32 v129, v129
	v_rcp_f32_e32 v130, v130
	v_rcp_f32_e32 v131, v131
	v_rcp_f32_e32 v132, v132
	v_rcp_f32_e32 v133, v133
	v_rcp_f32_e32 v134, v134
	v_rcp_f32_e32 v135, v135
	s_nop 0
	v_pk_fma_f32 v[8:9], v[8:9], v[128:129], v[8:9] neg_lo:[1,0,0] neg_hi:[1,0,0]
	v_pk_fma_f32 v[10:11], v[10:11], v[130:131], v[10:11] neg_lo:[1,0,0] neg_hi:[1,0,0]
	v_pk_fma_f32 v[12:13], v[12:13], v[132:133], v[12:13] neg_lo:[1,0,0] neg_hi:[1,0,0]
	v_pk_fma_f32 v[14:15], v[14:15], v[134:135], v[14:15] neg_lo:[1,0,0] neg_hi:[1,0,0]
	v_cvt_pk_bf16_f32 v128, v8, v9
	v_cvt_pk_bf16_f32 v129, v10, v11
	ds_write_b64 v140, v[128:129] offset:17120
	v_cvt_pk_bf16_f32 v132, v12, v13
	v_cvt_pk_bf16_f32 v133, v14, v15
	ds_write_b64 v140, v[132:133] offset:17136
	s_waitcnt lgkmcnt(0)
	s_barrier
	ds_read_b128 v[148:151], v141 offset:0
	ds_read_b128 v[152:155], v141 offset:8448
	ds_read_b128 v[156:159], v141 offset:16896
	ds_read_b128 v[160:163], v141 offset:25344
	ds_read_b128 v[164:167], v141 offset:33792
	ds_read_b128 v[172:175], v141 offset:42240
	ds_read_b128 v[176:179], v141 offset:50688
	ds_read_b128 v[180:183], v141 offset:59136
	ds_read_b128 v[184:187], v142 offset:0
	ds_read_b128 v[188:191], v142 offset:8448
	ds_read_b128 v[192:195], v142 offset:16896
	ds_read_b128 v[196:199], v142 offset:25344
	ds_read_b128 v[200:203], v142 offset:33792
	ds_read_b128 v[204:207], v142 offset:42240
	ds_read_b128 v[232:235], v142 offset:50688
	ds_read_b128 v[236:239], v142 offset:59136
	s_waitcnt lgkmcnt(15)
	global_store_dwordx4 v143, v[148:151], s[56:57]
	s_add_u32 s56, s56, 0x8000
	s_addc_u32 s57, s57, 0
	s_waitcnt lgkmcnt(14)
	global_store_dwordx4 v143, v[152:155], s[56:57]
	s_add_u32 s56, s56, 0x8000
	s_addc_u32 s57, s57, 0
	s_waitcnt lgkmcnt(13)
	global_store_dwordx4 v143, v[156:159], s[56:57]
	s_add_u32 s56, s56, 0x8000
	s_addc_u32 s57, s57, 0
	s_waitcnt lgkmcnt(12)
	global_store_dwordx4 v143, v[160:163], s[56:57]
	s_add_u32 s56, s56, 0x8000
	s_addc_u32 s57, s57, 0
	s_waitcnt lgkmcnt(11)
	global_store_dwordx4 v143, v[164:167], s[56:57]
	s_add_u32 s56, s56, 0x8000
	s_addc_u32 s57, s57, 0
	s_waitcnt lgkmcnt(10)
	global_store_dwordx4 v143, v[172:175], s[56:57]
	s_add_u32 s56, s56, 0x8000
	s_addc_u32 s57, s57, 0
	s_waitcnt lgkmcnt(9)
	global_store_dwordx4 v143, v[176:179], s[56:57]
	s_add_u32 s56, s56, 0x8000
	s_addc_u32 s57, s57, 0
	s_waitcnt lgkmcnt(8)
	global_store_dwordx4 v143, v[180:183], s[56:57]
	s_add_u32 s56, s56, 0x8000
	s_addc_u32 s57, s57, 0
	s_waitcnt lgkmcnt(7)
	global_store_dwordx4 v143, v[184:187], s[56:57]
	s_add_u32 s56, s56, 0x8000
	s_addc_u32 s57, s57, 0
	s_waitcnt lgkmcnt(6)
	global_store_dwordx4 v143, v[188:191], s[56:57]
	s_add_u32 s56, s56, 0x8000
	s_addc_u32 s57, s57, 0
	s_waitcnt lgkmcnt(5)
	global_store_dwordx4 v143, v[192:195], s[56:57]
	s_add_u32 s56, s56, 0x8000
	s_addc_u32 s57, s57, 0
	s_waitcnt lgkmcnt(4)
	global_store_dwordx4 v143, v[196:199], s[56:57]
	s_add_u32 s56, s56, 0x8000
	s_addc_u32 s57, s57, 0
	s_waitcnt lgkmcnt(3)
	global_store_dwordx4 v143, v[200:203], s[56:57]
	s_add_u32 s56, s56, 0x8000
	s_addc_u32 s57, s57, 0
	s_waitcnt lgkmcnt(2)
	global_store_dwordx4 v143, v[204:207], s[56:57]
	s_add_u32 s56, s56, 0x8000
	s_addc_u32 s57, s57, 0
	s_waitcnt lgkmcnt(1)
	global_store_dwordx4 v143, v[232:235], s[56:57]
	s_add_u32 s56, s56, 0x8000
	s_addc_u32 s57, s57, 0
	s_waitcnt lgkmcnt(0)
	global_store_dwordx4 v143, v[236:239], s[56:57]
	s_barrier
	s_branch .LBB0_219
.Lepi2_silu:
	s_sub_i32 s55, s36, 14
	s_lshl_b32 s55, s55, 9
	s_add_u32 s55, s55, 0x6c00000
	s_lshl_b64 s[58:59], s[34:35], 20
	s_add_u32 s58, s58, s55
	s_addc_u32 s59, s59, 0
	s_add_u32 s56, s90, s58
	s_addc_u32 s57, s91, s59
	v_lshrrev_b32_e32 v144, 1, v208
	v_and_b32_e32 v144, 0xffffffc0, v144
	v_and_b32_e32 v140, 31, v208
	v_or_b32_e32 v140, v144, v140
	v_mul_u32_u24_e32 v140, 0x210, v140
	v_lshlrev_b32_e32 v144, 2, v208
	v_and_b32_e32 v144, 0x100, v144
	v_add_u32_e32 v140, v140, v144
	v_lshrrev_b32_e32 v144, 2, v208
	v_and_b32_e32 v144, 8, v144
	v_add_u32_e32 v140, v140, v144
	v_lshrrev_b32_e32 v144, 5, v208
	v_and_b32_e32 v143, 31, v208
	v_lshlrev_b32_e32 v143, 4, v143
	v_mul_u32_u24_e32 v141, 0x210, v144
	v_add_u32_e32 v141, v141, v143
	v_add_u32_e32 v142, 0x10800, v141
	v_mul_u32_u24_e32 v144, 0x1000, v144
	v_add_u32_e32 v143, v143, v144
	v_mov_b32_e32 v136, 0xbfb8aa3b
	v_mov_b32_e32 v137, 0xbfb8aa3b
	v_pk_mul_f32 v[128:129], v[112:113], v[136:137]
	v_pk_mul_f32 v[130:131], v[114:115], v[136:137]
	v_pk_mul_f32 v[132:133], v[116:117], v[136:137]
	v_pk_mul_f32 v[134:135], v[118:119], v[136:137]
	v_exp_f32_e32 v128, v128
	v_exp_f32_e32 v129, v129
	v_exp_f32_e32 v130, v130
	v_exp_f32_e32 v131, v131
	v_exp_f32_e32 v132, v132
	v_exp_f32_e32 v133, v133
	v_exp_f32_e32 v134, v134
	v_exp_f32_e32 v135, v135
	s_nop 0
	v_pk_add_f32 v[128:129], v[128:129], 1.0 op_sel_hi:[1,0]
	v_pk_add_f32 v[130:131], v[130:131], 1.0 op_sel_hi:[1,0]
	v_pk_add_f32 v[132:133], v[132:133], 1.0 op_sel_hi:[1,0]
	v_pk_add_f32 v[134:135], v[134:135], 1.0 op_sel_hi:[1,0]
	v_rcp_f32_e32 v128, v128
	v_rcp_f32_e32 v129, v129
	v_rcp_f32_e32 v130, v130
	v_rcp_f32_e32 v131, v131
	v_rcp_f32_e32 v132, v132
	v_rcp_f32_e32 v133, v133
	v_rcp_f32_e32 v134, v134
	v_rcp_f32_e32 v135, v135
	s_nop 0
	v_pk_mul_f32 v[112:113], v[112:113], v[128:129]
	v_pk_mul_f32 v[114:115], v[114:115], v[130:131]
	v_pk_mul_f32 v[116:117], v[116:117], v[132:133]
	v_pk_mul_f32 v[118:119], v[118:119], v[134:135]
	v_cvt_pk_bf16_f32 v128, v112, v113
	v_cvt_pk_bf16_f32 v129, v114, v115
	ds_write_b64 v140, v[128:129] offset:0
	v_cvt_pk_bf16_f32 v132, v116, v117
	v_cvt_pk_bf16_f32 v133, v118, v119
	ds_write_b64 v140, v[132:133] offset:16
	v_pk_mul_f32 v[128:129], v[120:121], v[136:137]
	v_pk_mul_f32 v[130:131], v[122:123], v[136:137]
	v_pk_mul_f32 v[132:133], v[124:125], v[136:137]
	v_pk_mul_f32 v[134:135], v[126:127], v[136:137]
	v_exp_f32_e32 v128, v128
	v_exp_f32_e32 v129, v129
	v_exp_f32_e32 v130, v130
	v_exp_f32_e32 v131, v131
	v_exp_f32_e32 v132, v132
	v_exp_f32_e32 v133, v133
	v_exp_f32_e32 v134, v134
	v_exp_f32_e32 v135, v135
	s_nop 0
	v_pk_add_f32 v[128:129], v[128:129], 1.0 op_sel_hi:[1,0]
	v_pk_add_f32 v[130:131], v[130:131], 1.0 op_sel_hi:[1,0]
	v_pk_add_f32 v[132:133], v[132:133], 1.0 op_sel_hi:[1,0]
	v_pk_add_f32 v[134:135], v[134:135], 1.0 op_sel_hi:[1,0]
	v_rcp_f32_e32 v128, v128
	v_rcp_f32_e32 v129, v129
	v_rcp_f32_e32 v130, v130
	v_rcp_f32_e32 v131, v131
	v_rcp_f32_e32 v132, v132
	v_rcp_f32_e32 v133, v133
	v_rcp_f32_e32 v134, v134
	v_rcp_f32_e32 v135, v135
	s_nop 0
	v_pk_mul_f32 v[120:121], v[120:121], v[128:129]
	v_pk_mul_f32 v[122:123], v[122:123], v[130:131]
	v_pk_mul_f32 v[124:125], v[124:125], v[132:133]
	v_pk_mul_f32 v[126:127], v[126:127], v[134:135]
	v_cvt_pk_bf16_f32 v128, v120, v121
	v_cvt_pk_bf16_f32 v129, v122, v123
	ds_write_b64 v140, v[128:129] offset:32
	v_cvt_pk_bf16_f32 v132, v124, v125
	v_cvt_pk_bf16_f32 v133, v126, v127
	ds_write_b64 v140, v[132:133] offset:48
	v_pk_mul_f32 v[128:129], v[80:81], v[136:137]
	v_pk_mul_f32 v[130:131], v[82:83], v[136:137]
	v_pk_mul_f32 v[132:133], v[84:85], v[136:137]
	v_pk_mul_f32 v[134:135], v[86:87], v[136:137]
	v_exp_f32_e32 v128, v128
	v_exp_f32_e32 v129, v129
	v_exp_f32_e32 v130, v130
	v_exp_f32_e32 v131, v131
	v_exp_f32_e32 v132, v132
	v_exp_f32_e32 v133, v133
	v_exp_f32_e32 v134, v134
	v_exp_f32_e32 v135, v135
	s_nop 0
	v_pk_add_f32 v[128:129], v[128:129], 1.0 op_sel_hi:[1,0]
	v_pk_add_f32 v[130:131], v[130:131], 1.0 op_sel_hi:[1,0]
	v_pk_add_f32 v[132:133], v[132:133], 1.0 op_sel_hi:[1,0]
	v_pk_add_f32 v[134:135], v[134:135], 1.0 op_sel_hi:[1,0]
	v_rcp_f32_e32 v128, v128
	v_rcp_f32_e32 v129, v129
	v_rcp_f32_e32 v130, v130
	v_rcp_f32_e32 v131, v131
	v_rcp_f32_e32 v132, v132
	v_rcp_f32_e32 v133, v133
	v_rcp_f32_e32 v134, v134
	v_rcp_f32_e32 v135, v135
	s_nop 0
	v_pk_mul_f32 v[80:81], v[80:81], v[128:129]
	v_pk_mul_f32 v[82:83], v[82:83], v[130:131]
	v_pk_mul_f32 v[84:85], v[84:85], v[132:133]
	v_pk_mul_f32 v[86:87], v[86:87], v[134:135]
	v_cvt_pk_bf16_f32 v128, v80, v81
	v_cvt_pk_bf16_f32 v129, v82, v83
	ds_write_b64 v140, v[128:129] offset:64
	v_cvt_pk_bf16_f32 v132, v84, v85
	v_cvt_pk_bf16_f32 v133, v86, v87
	ds_write_b64 v140, v[132:133] offset:80
	v_pk_mul_f32 v[128:129], v[88:89], v[136:137]
	v_pk_mul_f32 v[130:131], v[90:91], v[136:137]
	v_pk_mul_f32 v[132:133], v[92:93], v[136:137]
	v_pk_mul_f32 v[134:135], v[94:95], v[136:137]
	v_exp_f32_e32 v128, v128
	v_exp_f32_e32 v129, v129
	v_exp_f32_e32 v130, v130
	v_exp_f32_e32 v131, v131
	v_exp_f32_e32 v132, v132
	v_exp_f32_e32 v133, v133
	v_exp_f32_e32 v134, v134
	v_exp_f32_e32 v135, v135
	s_nop 0
	v_pk_add_f32 v[128:129], v[128:129], 1.0 op_sel_hi:[1,0]
	v_pk_add_f32 v[130:131], v[130:131], 1.0 op_sel_hi:[1,0]
	v_pk_add_f32 v[132:133], v[132:133], 1.0 op_sel_hi:[1,0]
	v_pk_add_f32 v[134:135], v[134:135], 1.0 op_sel_hi:[1,0]
	v_rcp_f32_e32 v128, v128
	v_rcp_f32_e32 v129, v129
	v_rcp_f32_e32 v130, v130
	v_rcp_f32_e32 v131, v131
	v_rcp_f32_e32 v132, v132
	v_rcp_f32_e32 v133, v133
	v_rcp_f32_e32 v134, v134
	v_rcp_f32_e32 v135, v135
	s_nop 0
	v_pk_mul_f32 v[88:89], v[88:89], v[128:129]
	v_pk_mul_f32 v[90:91], v[90:91], v[130:131]
	v_pk_mul_f32 v[92:93], v[92:93], v[132:133]
	v_pk_mul_f32 v[94:95], v[94:95], v[134:135]
	v_cvt_pk_bf16_f32 v128, v88, v89
	v_cvt_pk_bf16_f32 v129, v90, v91
	ds_write_b64 v140, v[128:129] offset:96
	v_cvt_pk_bf16_f32 v132, v92, v93
	v_cvt_pk_bf16_f32 v133, v94, v95
	ds_write_b64 v140, v[132:133] offset:112
	v_pk_mul_f32 v[128:129], v[96:97], v[136:137]
	v_pk_mul_f32 v[130:131], v[98:99], v[136:137]
	v_pk_mul_f32 v[132:133], v[100:101], v[136:137]
	v_pk_mul_f32 v[134:135], v[102:103], v[136:137]
	v_exp_f32_e32 v128, v128
	v_exp_f32_e32 v129, v129
	v_exp_f32_e32 v130, v130
	v_exp_f32_e32 v131, v131
	v_exp_f32_e32 v132, v132
	v_exp_f32_e32 v133, v133
	v_exp_f32_e32 v134, v134
	v_exp_f32_e32 v135, v135
	s_nop 0
	v_pk_add_f32 v[128:129], v[128:129], 1.0 op_sel_hi:[1,0]
	v_pk_add_f32 v[130:131], v[130:131], 1.0 op_sel_hi:[1,0]
	v_pk_add_f32 v[132:133], v[132:133], 1.0 op_sel_hi:[1,0]
	v_pk_add_f32 v[134:135], v[134:135], 1.0 op_sel_hi:[1,0]
	v_rcp_f32_e32 v128, v128
	v_rcp_f32_e32 v129, v129
	v_rcp_f32_e32 v130, v130
	v_rcp_f32_e32 v131, v131
	v_rcp_f32_e32 v132, v132
	v_rcp_f32_e32 v133, v133
	v_rcp_f32_e32 v134, v134
	v_rcp_f32_e32 v135, v135
	s_nop 0
	v_pk_mul_f32 v[96:97], v[96:97], v[128:129]
	v_pk_mul_f32 v[98:99], v[98:99], v[130:131]
	v_pk_mul_f32 v[100:101], v[100:101], v[132:133]
	v_pk_mul_f32 v[102:103], v[102:103], v[134:135]
	v_cvt_pk_bf16_f32 v128, v96, v97
	v_cvt_pk_bf16_f32 v129, v98, v99
	ds_write_b64 v140, v[128:129] offset:128
	v_cvt_pk_bf16_f32 v132, v100, v101
	v_cvt_pk_bf16_f32 v133, v102, v103
	ds_write_b64 v140, v[132:133] offset:144
	v_pk_mul_f32 v[128:129], v[104:105], v[136:137]
	v_pk_mul_f32 v[130:131], v[106:107], v[136:137]
	v_pk_mul_f32 v[132:133], v[108:109], v[136:137]
	v_pk_mul_f32 v[134:135], v[110:111], v[136:137]
	v_exp_f32_e32 v128, v128
	v_exp_f32_e32 v129, v129
	v_exp_f32_e32 v130, v130
	v_exp_f32_e32 v131, v131
	v_exp_f32_e32 v132, v132
	v_exp_f32_e32 v133, v133
	v_exp_f32_e32 v134, v134
	v_exp_f32_e32 v135, v135
	s_nop 0
	v_pk_add_f32 v[128:129], v[128:129], 1.0 op_sel_hi:[1,0]
	v_pk_add_f32 v[130:131], v[130:131], 1.0 op_sel_hi:[1,0]
	v_pk_add_f32 v[132:133], v[132:133], 1.0 op_sel_hi:[1,0]
	v_pk_add_f32 v[134:135], v[134:135], 1.0 op_sel_hi:[1,0]
	v_rcp_f32_e32 v128, v128
	v_rcp_f32_e32 v129, v129
	v_rcp_f32_e32 v130, v130
	v_rcp_f32_e32 v131, v131
	v_rcp_f32_e32 v132, v132
	v_rcp_f32_e32 v133, v133
	v_rcp_f32_e32 v134, v134
	v_rcp_f32_e32 v135, v135
	s_nop 0
	v_pk_mul_f32 v[104:105], v[104:105], v[128:129]
	v_pk_mul_f32 v[106:107], v[106:107], v[130:131]
	v_pk_mul_f32 v[108:109], v[108:109], v[132:133]
	v_pk_mul_f32 v[110:111], v[110:111], v[134:135]
	v_cvt_pk_bf16_f32 v128, v104, v105
	v_cvt_pk_bf16_f32 v129, v106, v107
	ds_write_b64 v140, v[128:129] offset:160
	v_cvt_pk_bf16_f32 v132, v108, v109
	v_cvt_pk_bf16_f32 v133, v110, v111
	ds_write_b64 v140, v[132:133] offset:176
	v_pk_mul_f32 v[128:129], v[64:65], v[136:137]
	v_pk_mul_f32 v[130:131], v[66:67], v[136:137]
	v_pk_mul_f32 v[132:133], v[68:69], v[136:137]
	v_pk_mul_f32 v[134:135], v[70:71], v[136:137]
	v_exp_f32_e32 v128, v128
	v_exp_f32_e32 v129, v129
	v_exp_f32_e32 v130, v130
	v_exp_f32_e32 v131, v131
	v_exp_f32_e32 v132, v132
	v_exp_f32_e32 v133, v133
	v_exp_f32_e32 v134, v134
	v_exp_f32_e32 v135, v135
	s_nop 0
	v_pk_add_f32 v[128:129], v[128:129], 1.0 op_sel_hi:[1,0]
	v_pk_add_f32 v[130:131], v[130:131], 1.0 op_sel_hi:[1,0]
	v_pk_add_f32 v[132:133], v[132:133], 1.0 op_sel_hi:[1,0]
	v_pk_add_f32 v[134:135], v[134:135], 1.0 op_sel_hi:[1,0]
	v_rcp_f32_e32 v128, v128
	v_rcp_f32_e32 v129, v129
	v_rcp_f32_e32 v130, v130
	v_rcp_f32_e32 v131, v131
	v_rcp_f32_e32 v132, v132
	v_rcp_f32_e32 v133, v133
	v_rcp_f32_e32 v134, v134
	v_rcp_f32_e32 v135, v135
	s_nop 0
	v_pk_mul_f32 v[64:65], v[64:65], v[128:129]
	v_pk_mul_f32 v[66:67], v[66:67], v[130:131]
	v_pk_mul_f32 v[68:69], v[68:69], v[132:133]
	v_pk_mul_f32 v[70:71], v[70:71], v[134:135]
	v_cvt_pk_bf16_f32 v128, v64, v65
	v_cvt_pk_bf16_f32 v129, v66, v67
	ds_write_b64 v140, v[128:129] offset:192
	v_cvt_pk_bf16_f32 v132, v68, v69
	v_cvt_pk_bf16_f32 v133, v70, v71
	ds_write_b64 v140, v[132:133] offset:208
	v_pk_mul_f32 v[128:129], v[72:73], v[136:137]
	v_pk_mul_f32 v[130:131], v[74:75], v[136:137]
	v_pk_mul_f32 v[132:133], v[76:77], v[136:137]
	v_pk_mul_f32 v[134:135], v[78:79], v[136:137]
	v_exp_f32_e32 v128, v128
	v_exp_f32_e32 v129, v129
	v_exp_f32_e32 v130, v130
	v_exp_f32_e32 v131, v131
	v_exp_f32_e32 v132, v132
	v_exp_f32_e32 v133, v133
	v_exp_f32_e32 v134, v134
	v_exp_f32_e32 v135, v135
	s_nop 0
	v_pk_add_f32 v[128:129], v[128:129], 1.0 op_sel_hi:[1,0]
	v_pk_add_f32 v[130:131], v[130:131], 1.0 op_sel_hi:[1,0]
	v_pk_add_f32 v[132:133], v[132:133], 1.0 op_sel_hi:[1,0]
	v_pk_add_f32 v[134:135], v[134:135], 1.0 op_sel_hi:[1,0]
	v_rcp_f32_e32 v128, v128
	v_rcp_f32_e32 v129, v129
	v_rcp_f32_e32 v130, v130
	v_rcp_f32_e32 v131, v131
	v_rcp_f32_e32 v132, v132
	v_rcp_f32_e32 v133, v133
	v_rcp_f32_e32 v134, v134
	v_rcp_f32_e32 v135, v135
	s_nop 0
	v_pk_mul_f32 v[72:73], v[72:73], v[128:129]
	v_pk_mul_f32 v[74:75], v[74:75], v[130:131]
	v_pk_mul_f32 v[76:77], v[76:77], v[132:133]
	v_pk_mul_f32 v[78:79], v[78:79], v[134:135]
	v_cvt_pk_bf16_f32 v128, v72, v73
	v_cvt_pk_bf16_f32 v129, v74, v75
	ds_write_b64 v140, v[128:129] offset:224
	v_cvt_pk_bf16_f32 v132, v76, v77
	v_cvt_pk_bf16_f32 v133, v78, v79
	ds_write_b64 v140, v[132:133] offset:240
	v_pk_mul_f32 v[128:129], v[48:49], v[136:137]
	v_pk_mul_f32 v[130:131], v[50:51], v[136:137]
	v_pk_mul_f32 v[132:133], v[52:53], v[136:137]
	v_pk_mul_f32 v[134:135], v[54:55], v[136:137]
	v_exp_f32_e32 v128, v128
	v_exp_f32_e32 v129, v129
	v_exp_f32_e32 v130, v130
	v_exp_f32_e32 v131, v131
	v_exp_f32_e32 v132, v132
	v_exp_f32_e32 v133, v133
	v_exp_f32_e32 v134, v134
	v_exp_f32_e32 v135, v135
	s_nop 0
	v_pk_add_f32 v[128:129], v[128:129], 1.0 op_sel_hi:[1,0]
	v_pk_add_f32 v[130:131], v[130:131], 1.0 op_sel_hi:[1,0]
	v_pk_add_f32 v[132:133], v[132:133], 1.0 op_sel_hi:[1,0]
	v_pk_add_f32 v[134:135], v[134:135], 1.0 op_sel_hi:[1,0]
	v_rcp_f32_e32 v128, v128
	v_rcp_f32_e32 v129, v129
	v_rcp_f32_e32 v130, v130
	v_rcp_f32_e32 v131, v131
	v_rcp_f32_e32 v132, v132
	v_rcp_f32_e32 v133, v133
	v_rcp_f32_e32 v134, v134
	v_rcp_f32_e32 v135, v135
	s_nop 0
	v_pk_mul_f32 v[48:49], v[48:49], v[128:129]
	v_pk_mul_f32 v[50:51], v[50:51], v[130:131]
	v_pk_mul_f32 v[52:53], v[52:53], v[132:133]
	v_pk_mul_f32 v[54:55], v[54:55], v[134:135]
	v_cvt_pk_bf16_f32 v128, v48, v49
	v_cvt_pk_bf16_f32 v129, v50, v51
	ds_write_b64 v140, v[128:129] offset:16896
	v_cvt_pk_bf16_f32 v132, v52, v53
	v_cvt_pk_bf16_f32 v133, v54, v55
	ds_write_b64 v140, v[132:133] offset:16912
	v_pk_mul_f32 v[128:129], v[56:57], v[136:137]
	v_pk_mul_f32 v[130:131], v[58:59], v[136:137]
	v_pk_mul_f32 v[132:133], v[60:61], v[136:137]
	v_pk_mul_f32 v[134:135], v[62:63], v[136:137]
	v_exp_f32_e32 v128, v128
	v_exp_f32_e32 v129, v129
	v_exp_f32_e32 v130, v130
	v_exp_f32_e32 v131, v131
	v_exp_f32_e32 v132, v132
	v_exp_f32_e32 v133, v133
	v_exp_f32_e32 v134, v134
	v_exp_f32_e32 v135, v135
	s_nop 0
	v_pk_add_f32 v[128:129], v[128:129], 1.0 op_sel_hi:[1,0]
	v_pk_add_f32 v[130:131], v[130:131], 1.0 op_sel_hi:[1,0]
	v_pk_add_f32 v[132:133], v[132:133], 1.0 op_sel_hi:[1,0]
	v_pk_add_f32 v[134:135], v[134:135], 1.0 op_sel_hi:[1,0]
	v_rcp_f32_e32 v128, v128
	v_rcp_f32_e32 v129, v129
	v_rcp_f32_e32 v130, v130
	v_rcp_f32_e32 v131, v131
	v_rcp_f32_e32 v132, v132
	v_rcp_f32_e32 v133, v133
	v_rcp_f32_e32 v134, v134
	v_rcp_f32_e32 v135, v135
	s_nop 0
	v_pk_mul_f32 v[56:57], v[56:57], v[128:129]
	v_pk_mul_f32 v[58:59], v[58:59], v[130:131]
	v_pk_mul_f32 v[60:61], v[60:61], v[132:133]
	v_pk_mul_f32 v[62:63], v[62:63], v[134:135]
	v_cvt_pk_bf16_f32 v128, v56, v57
	v_cvt_pk_bf16_f32 v129, v58, v59
	ds_write_b64 v140, v[128:129] offset:16928
	v_cvt_pk_bf16_f32 v132, v60, v61
	v_cvt_pk_bf16_f32 v133, v62, v63
	ds_write_b64 v140, v[132:133] offset:16944
	v_pk_mul_f32 v[128:129], v[16:17], v[136:137]
	v_pk_mul_f32 v[130:131], v[18:19], v[136:137]
	v_pk_mul_f32 v[132:133], v[20:21], v[136:137]
	v_pk_mul_f32 v[134:135], v[22:23], v[136:137]
	v_exp_f32_e32 v128, v128
	v_exp_f32_e32 v129, v129
	v_exp_f32_e32 v130, v130
	v_exp_f32_e32 v131, v131
	v_exp_f32_e32 v132, v132
	v_exp_f32_e32 v133, v133
	v_exp_f32_e32 v134, v134
	v_exp_f32_e32 v135, v135
	s_nop 0
	v_pk_add_f32 v[128:129], v[128:129], 1.0 op_sel_hi:[1,0]
	v_pk_add_f32 v[130:131], v[130:131], 1.0 op_sel_hi:[1,0]
	v_pk_add_f32 v[132:133], v[132:133], 1.0 op_sel_hi:[1,0]
	v_pk_add_f32 v[134:135], v[134:135], 1.0 op_sel_hi:[1,0]
	v_rcp_f32_e32 v128, v128
	v_rcp_f32_e32 v129, v129
	v_rcp_f32_e32 v130, v130
	v_rcp_f32_e32 v131, v131
	v_rcp_f32_e32 v132, v132
	v_rcp_f32_e32 v133, v133
	v_rcp_f32_e32 v134, v134
	v_rcp_f32_e32 v135, v135
	s_nop 0
	v_pk_mul_f32 v[16:17], v[16:17], v[128:129]
	v_pk_mul_f32 v[18:19], v[18:19], v[130:131]
	v_pk_mul_f32 v[20:21], v[20:21], v[132:133]
	v_pk_mul_f32 v[22:23], v[22:23], v[134:135]
	v_cvt_pk_bf16_f32 v128, v16, v17
	v_cvt_pk_bf16_f32 v129, v18, v19
	ds_write_b64 v140, v[128:129] offset:16960
	v_cvt_pk_bf16_f32 v132, v20, v21
	v_cvt_pk_bf16_f32 v133, v22, v23
	ds_write_b64 v140, v[132:133] offset:16976
	v_pk_mul_f32 v[128:129], v[24:25], v[136:137]
	v_pk_mul_f32 v[130:131], v[26:27], v[136:137]
	v_pk_mul_f32 v[132:133], v[28:29], v[136:137]
	v_pk_mul_f32 v[134:135], v[30:31], v[136:137]
	v_exp_f32_e32 v128, v128
	v_exp_f32_e32 v129, v129
	v_exp_f32_e32 v130, v130
	v_exp_f32_e32 v131, v131
	v_exp_f32_e32 v132, v132
	v_exp_f32_e32 v133, v133
	v_exp_f32_e32 v134, v134
	v_exp_f32_e32 v135, v135
	s_nop 0
	v_pk_add_f32 v[128:129], v[128:129], 1.0 op_sel_hi:[1,0]
	v_pk_add_f32 v[130:131], v[130:131], 1.0 op_sel_hi:[1,0]
	v_pk_add_f32 v[132:133], v[132:133], 1.0 op_sel_hi:[1,0]
	v_pk_add_f32 v[134:135], v[134:135], 1.0 op_sel_hi:[1,0]
	v_rcp_f32_e32 v128, v128
	v_rcp_f32_e32 v129, v129
	v_rcp_f32_e32 v130, v130
	v_rcp_f32_e32 v131, v131
	v_rcp_f32_e32 v132, v132
	v_rcp_f32_e32 v133, v133
	v_rcp_f32_e32 v134, v134
	v_rcp_f32_e32 v135, v135
	s_nop 0
	v_pk_mul_f32 v[24:25], v[24:25], v[128:129]
	v_pk_mul_f32 v[26:27], v[26:27], v[130:131]
	v_pk_mul_f32 v[28:29], v[28:29], v[132:133]
	v_pk_mul_f32 v[30:31], v[30:31], v[134:135]
	v_cvt_pk_bf16_f32 v128, v24, v25
	v_cvt_pk_bf16_f32 v129, v26, v27
	ds_write_b64 v140, v[128:129] offset:16992
	v_cvt_pk_bf16_f32 v132, v28, v29
	v_cvt_pk_bf16_f32 v133, v30, v31
	ds_write_b64 v140, v[132:133] offset:17008
	v_pk_mul_f32 v[128:129], v[32:33], v[136:137]
	v_pk_mul_f32 v[130:131], v[34:35], v[136:137]
	v_pk_mul_f32 v[132:133], v[36:37], v[136:137]
	v_pk_mul_f32 v[134:135], v[38:39], v[136:137]
	v_exp_f32_e32 v128, v128
	v_exp_f32_e32 v129, v129
	v_exp_f32_e32 v130, v130
	v_exp_f32_e32 v131, v131
	v_exp_f32_e32 v132, v132
	v_exp_f32_e32 v133, v133
	v_exp_f32_e32 v134, v134
	v_exp_f32_e32 v135, v135
	s_nop 0
	v_pk_add_f32 v[128:129], v[128:129], 1.0 op_sel_hi:[1,0]
	v_pk_add_f32 v[130:131], v[130:131], 1.0 op_sel_hi:[1,0]
	v_pk_add_f32 v[132:133], v[132:133], 1.0 op_sel_hi:[1,0]
	v_pk_add_f32 v[134:135], v[134:135], 1.0 op_sel_hi:[1,0]
	v_rcp_f32_e32 v128, v128
	v_rcp_f32_e32 v129, v129
	v_rcp_f32_e32 v130, v130
	v_rcp_f32_e32 v131, v131
	v_rcp_f32_e32 v132, v132
	v_rcp_f32_e32 v133, v133
	v_rcp_f32_e32 v134, v134
	v_rcp_f32_e32 v135, v135
	s_nop 0
	v_pk_mul_f32 v[32:33], v[32:33], v[128:129]
	v_pk_mul_f32 v[34:35], v[34:35], v[130:131]
	v_pk_mul_f32 v[36:37], v[36:37], v[132:133]
	v_pk_mul_f32 v[38:39], v[38:39], v[134:135]
	v_cvt_pk_bf16_f32 v128, v32, v33
	v_cvt_pk_bf16_f32 v129, v34, v35
	ds_write_b64 v140, v[128:129] offset:17024
	v_cvt_pk_bf16_f32 v132, v36, v37
	v_cvt_pk_bf16_f32 v133, v38, v39
	ds_write_b64 v140, v[132:133] offset:17040
	v_pk_mul_f32 v[128:129], v[40:41], v[136:137]
	v_pk_mul_f32 v[130:131], v[42:43], v[136:137]
	v_pk_mul_f32 v[132:133], v[44:45], v[136:137]
	v_pk_mul_f32 v[134:135], v[46:47], v[136:137]
	v_exp_f32_e32 v128, v128
	v_exp_f32_e32 v129, v129
	v_exp_f32_e32 v130, v130
	v_exp_f32_e32 v131, v131
	v_exp_f32_e32 v132, v132
	v_exp_f32_e32 v133, v133
	v_exp_f32_e32 v134, v134
	v_exp_f32_e32 v135, v135
	s_nop 0
	v_pk_add_f32 v[128:129], v[128:129], 1.0 op_sel_hi:[1,0]
	v_pk_add_f32 v[130:131], v[130:131], 1.0 op_sel_hi:[1,0]
	v_pk_add_f32 v[132:133], v[132:133], 1.0 op_sel_hi:[1,0]
	v_pk_add_f32 v[134:135], v[134:135], 1.0 op_sel_hi:[1,0]
	v_rcp_f32_e32 v128, v128
	v_rcp_f32_e32 v129, v129
	v_rcp_f32_e32 v130, v130
	v_rcp_f32_e32 v131, v131
	v_rcp_f32_e32 v132, v132
	v_rcp_f32_e32 v133, v133
	v_rcp_f32_e32 v134, v134
	v_rcp_f32_e32 v135, v135
	s_nop 0
	v_pk_mul_f32 v[40:41], v[40:41], v[128:129]
	v_pk_mul_f32 v[42:43], v[42:43], v[130:131]
	v_pk_mul_f32 v[44:45], v[44:45], v[132:133]
	v_pk_mul_f32 v[46:47], v[46:47], v[134:135]
	v_cvt_pk_bf16_f32 v128, v40, v41
	v_cvt_pk_bf16_f32 v129, v42, v43
	ds_write_b64 v140, v[128:129] offset:17056
	v_cvt_pk_bf16_f32 v132, v44, v45
	v_cvt_pk_bf16_f32 v133, v46, v47
	ds_write_b64 v140, v[132:133] offset:17072
	v_pk_mul_f32 v[128:129], v[0:1], v[136:137]
	v_pk_mul_f32 v[130:131], v[2:3], v[136:137]
	v_pk_mul_f32 v[132:133], v[4:5], v[136:137]
	v_pk_mul_f32 v[134:135], v[6:7], v[136:137]
	v_exp_f32_e32 v128, v128
	v_exp_f32_e32 v129, v129
	v_exp_f32_e32 v130, v130
	v_exp_f32_e32 v131, v131
	v_exp_f32_e32 v132, v132
	v_exp_f32_e32 v133, v133
	v_exp_f32_e32 v134, v134
	v_exp_f32_e32 v135, v135
	s_nop 0
	v_pk_add_f32 v[128:129], v[128:129], 1.0 op_sel_hi:[1,0]
	v_pk_add_f32 v[130:131], v[130:131], 1.0 op_sel_hi:[1,0]
	v_pk_add_f32 v[132:133], v[132:133], 1.0 op_sel_hi:[1,0]
	v_pk_add_f32 v[134:135], v[134:135], 1.0 op_sel_hi:[1,0]
	v_rcp_f32_e32 v128, v128
	v_rcp_f32_e32 v129, v129
	v_rcp_f32_e32 v130, v130
	v_rcp_f32_e32 v131, v131
	v_rcp_f32_e32 v132, v132
	v_rcp_f32_e32 v133, v133
	v_rcp_f32_e32 v134, v134
	v_rcp_f32_e32 v135, v135
	s_nop 0
	v_pk_mul_f32 v[0:1], v[0:1], v[128:129]
	v_pk_mul_f32 v[2:3], v[2:3], v[130:131]
	v_pk_mul_f32 v[4:5], v[4:5], v[132:133]
	v_pk_mul_f32 v[6:7], v[6:7], v[134:135]
	v_cvt_pk_bf16_f32 v128, v0, v1
	v_cvt_pk_bf16_f32 v129, v2, v3
	ds_write_b64 v140, v[128:129] offset:17088
	v_cvt_pk_bf16_f32 v132, v4, v5
	v_cvt_pk_bf16_f32 v133, v6, v7
	ds_write_b64 v140, v[132:133] offset:17104
	v_pk_mul_f32 v[128:129], v[8:9], v[136:137]
	v_pk_mul_f32 v[130:131], v[10:11], v[136:137]
	v_pk_mul_f32 v[132:133], v[12:13], v[136:137]
	v_pk_mul_f32 v[134:135], v[14:15], v[136:137]
	v_exp_f32_e32 v128, v128
	v_exp_f32_e32 v129, v129
	v_exp_f32_e32 v130, v130
	v_exp_f32_e32 v131, v131
	v_exp_f32_e32 v132, v132
	v_exp_f32_e32 v133, v133
	v_exp_f32_e32 v134, v134
	v_exp_f32_e32 v135, v135
	s_nop 0
	v_pk_add_f32 v[128:129], v[128:129], 1.0 op_sel_hi:[1,0]
	v_pk_add_f32 v[130:131], v[130:131], 1.0 op_sel_hi:[1,0]
	v_pk_add_f32 v[132:133], v[132:133], 1.0 op_sel_hi:[1,0]
	v_pk_add_f32 v[134:135], v[134:135], 1.0 op_sel_hi:[1,0]
	v_rcp_f32_e32 v128, v128
	v_rcp_f32_e32 v129, v129
	v_rcp_f32_e32 v130, v130
	v_rcp_f32_e32 v131, v131
	v_rcp_f32_e32 v132, v132
	v_rcp_f32_e32 v133, v133
	v_rcp_f32_e32 v134, v134
	v_rcp_f32_e32 v135, v135
	s_nop 0
	v_pk_mul_f32 v[8:9], v[8:9], v[128:129]
	v_pk_mul_f32 v[10:11], v[10:11], v[130:131]
	v_pk_mul_f32 v[12:13], v[12:13], v[132:133]
	v_pk_mul_f32 v[14:15], v[14:15], v[134:135]
	v_cvt_pk_bf16_f32 v128, v8, v9
	v_cvt_pk_bf16_f32 v129, v10, v11
	ds_write_b64 v140, v[128:129] offset:17120
	v_cvt_pk_bf16_f32 v132, v12, v13
	v_cvt_pk_bf16_f32 v133, v14, v15
	ds_write_b64 v140, v[132:133] offset:17136
	s_waitcnt lgkmcnt(0)
	s_barrier
	ds_read_b128 v[148:151], v141 offset:0
	ds_read_b128 v[152:155], v141 offset:8448
	ds_read_b128 v[156:159], v141 offset:16896
	ds_read_b128 v[160:163], v141 offset:25344
	ds_read_b128 v[164:167], v141 offset:33792
	ds_read_b128 v[172:175], v141 offset:42240
	ds_read_b128 v[176:179], v141 offset:50688
	ds_read_b128 v[180:183], v141 offset:59136
	ds_read_b128 v[184:187], v142 offset:0
	ds_read_b128 v[188:191], v142 offset:8448
	ds_read_b128 v[192:195], v142 offset:16896
	ds_read_b128 v[196:199], v142 offset:25344
	ds_read_b128 v[200:203], v142 offset:33792
	ds_read_b128 v[204:207], v142 offset:42240
	ds_read_b128 v[232:235], v142 offset:50688
	ds_read_b128 v[236:239], v142 offset:59136
	s_waitcnt lgkmcnt(15)
	global_store_dwordx4 v143, v[148:151], s[56:57]
	s_add_u32 s56, s56, 0x10000
	s_addc_u32 s57, s57, 0
	s_waitcnt lgkmcnt(14)
	global_store_dwordx4 v143, v[152:155], s[56:57]
	s_add_u32 s56, s56, 0x10000
	s_addc_u32 s57, s57, 0
	s_waitcnt lgkmcnt(13)
	global_store_dwordx4 v143, v[156:159], s[56:57]
	s_add_u32 s56, s56, 0x10000
	s_addc_u32 s57, s57, 0
	s_waitcnt lgkmcnt(12)
	global_store_dwordx4 v143, v[160:163], s[56:57]
	s_add_u32 s56, s56, 0x10000
	s_addc_u32 s57, s57, 0
	s_waitcnt lgkmcnt(11)
	global_store_dwordx4 v143, v[164:167], s[56:57]
	s_add_u32 s56, s56, 0x10000
	s_addc_u32 s57, s57, 0
	s_waitcnt lgkmcnt(10)
	global_store_dwordx4 v143, v[172:175], s[56:57]
	s_add_u32 s56, s56, 0x10000
	s_addc_u32 s57, s57, 0
	s_waitcnt lgkmcnt(9)
	global_store_dwordx4 v143, v[176:179], s[56:57]
	s_add_u32 s56, s56, 0x10000
	s_addc_u32 s57, s57, 0
	s_waitcnt lgkmcnt(8)
	global_store_dwordx4 v143, v[180:183], s[56:57]
	s_add_u32 s56, s56, 0x10000
	s_addc_u32 s57, s57, 0
	s_waitcnt lgkmcnt(7)
	global_store_dwordx4 v143, v[184:187], s[56:57]
	s_add_u32 s56, s56, 0x10000
	s_addc_u32 s57, s57, 0
	s_waitcnt lgkmcnt(6)
	global_store_dwordx4 v143, v[188:191], s[56:57]
	s_add_u32 s56, s56, 0x10000
	s_addc_u32 s57, s57, 0
	s_waitcnt lgkmcnt(5)
	global_store_dwordx4 v143, v[192:195], s[56:57]
	s_add_u32 s56, s56, 0x10000
	s_addc_u32 s57, s57, 0
	s_waitcnt lgkmcnt(4)
	global_store_dwordx4 v143, v[196:199], s[56:57]
	s_add_u32 s56, s56, 0x10000
	s_addc_u32 s57, s57, 0
	s_waitcnt lgkmcnt(3)
	global_store_dwordx4 v143, v[200:203], s[56:57]
	s_add_u32 s56, s56, 0x10000
	s_addc_u32 s57, s57, 0
	s_waitcnt lgkmcnt(2)
	global_store_dwordx4 v143, v[204:207], s[56:57]
	s_add_u32 s56, s56, 0x10000
	s_addc_u32 s57, s57, 0
	s_waitcnt lgkmcnt(1)
	global_store_dwordx4 v143, v[232:235], s[56:57]
	s_add_u32 s56, s56, 0x10000
	s_addc_u32 s57, s57, 0
	s_waitcnt lgkmcnt(0)
	global_store_dwordx4 v143, v[236:239], s[56:57]
	s_barrier
	s_branch .LBB0_219
.Lepi2_orig:
	s_cmp_gt_i32 s36, 4
	s_mov_b64 s[2:3], -1
	s_cbranch_scc0 .LBB0_240
	s_cmp_lg_u32 s36, 5
	s_cbranch_scc0 .LBB0_233
	s_cmp_gt_u32 s36, 13
	s_cbranch_scc0 .LBB0_230
	s_waitcnt vmcnt(1)
	v_mov_b32_e32 v128, v208
	v_mul_f32_e32 v131, 0xbfb8aa3b, v115
	v_and_b32_e32 v129, 31, v128
	v_lshrrev_b32_e32 v130, 1, v128
	s_waitcnt vmcnt(0)
	v_and_or_b32 v132, v130, s45, v129
	v_mul_f32_e32 v129, 0xbfb8aa3b, v112
	v_mul_f32_e32 v130, 0xbfb8aa3b, v113
	v_exp_f32_e32 v129, v129
	v_exp_f32_e32 v130, v130
	v_lshlrev_b32_e32 v133, 1, v128
	v_lshrrev_b32_e32 v128, 3, v128
	v_and_b32_e32 v134, 4, v128
	v_add_f32_e32 v128, 1.0, v129
	v_add_f32_e32 v129, 1.0, v130
	v_rcp_f32_e32 v128, v128
	v_rcp_f32_e32 v129, v129
	v_mul_lo_u32 v139, v132, s43
	v_mul_f32_e32 v132, 0xbfb8aa3b, v116
	v_and_or_b32 v138, v133, s46, v134
	v_exp_f32_e32 v133, v132
	v_pk_mul_f32 v[128:129], v[112:113], v[128:129]
	v_mul_f32_e32 v132, 0xbfb8aa3b, v117
	v_mul_f32_e32 v130, 0xbfb8aa3b, v114
	v_exp_f32_e32 v135, v132
	v_cvt_pk_bf16_f32 v132, v128, v129
	v_mul_f32_e32 v129, 0xbfb8aa3b, v118
	v_exp_f32_e32 v130, v130
	v_exp_f32_e32 v131, v131
	v_add_f32_e32 v128, 1.0, v133
	v_exp_f32_e32 v129, v129
	v_mul_f32_e32 v133, 0xbfb8aa3b, v119
	v_exp_f32_e32 v133, v133
	v_rcp_f32_e32 v134, v128
	v_add_f32_e32 v128, 1.0, v135
	v_add_f32_e32 v130, 1.0, v130
	v_add_f32_e32 v131, 1.0, v131
	v_rcp_f32_e32 v135, v128
	v_add_f32_e32 v128, 1.0, v129
	v_rcp_f32_e32 v130, v130
	v_rcp_f32_e32 v131, v131
	v_rcp_f32_e32 v136, v128
	v_add_f32_e32 v128, 1.0, v133
	v_rcp_f32_e32 v137, v128
	v_pk_mul_f32 v[130:131], v[114:115], v[130:131]
	v_mul_f32_e32 v129, 0xbfb8aa3b, v120
	v_cvt_pk_bf16_f32 v133, v130, v131
	v_pk_mul_f32 v[130:131], v[116:117], v[134:135]
	v_pk_mul_f32 v[134:135], v[118:119], v[136:137]
	v_cvt_pk_bf16_f32 v130, v130, v131
	v_cvt_pk_bf16_f32 v131, v134, v135
	v_exp_f32_e32 v129, v129
	v_mul_f32_e32 v134, 0xbfb8aa3b, v121
	v_exp_f32_e32 v134, v134
	v_lshl_add_u32 v128, v138, 1, v139
	v_add_f32_e32 v129, 1.0, v129
	ds_write2_b64 v128, v[132:133], v[130:131] offset1:2
	v_rcp_f32_e32 v130, v129
	v_add_f32_e32 v129, 1.0, v134
	v_rcp_f32_e32 v131, v129
	v_mul_f32_e32 v129, 0xbfb8aa3b, v122
	v_exp_f32_e32 v129, v129
	v_mul_f32_e32 v132, 0xbfb8aa3b, v123
	v_exp_f32_e32 v133, v132
	v_mul_f32_e32 v134, 0xbfb8aa3b, v125
	v_add_f32_e32 v129, 1.0, v129
	v_rcp_f32_e32 v132, v129
	v_add_f32_e32 v129, 1.0, v133
	v_rcp_f32_e32 v133, v129
	v_mul_f32_e32 v129, 0xbfb8aa3b, v124
	v_exp_f32_e32 v129, v129
	v_exp_f32_e32 v135, v134
	v_pk_mul_f32 v[130:131], v[120:121], v[130:131]
	v_pk_mul_f32 v[132:133], v[122:123], v[132:133]
	v_add_f32_e32 v129, 1.0, v129
	v_rcp_f32_e32 v134, v129
	v_add_f32_e32 v129, 1.0, v135
	v_mul_f32_e32 v135, 0xbfb8aa3b, v126
	v_exp_f32_e32 v136, v135
	v_mul_f32_e32 v135, 0xbfb8aa3b, v127
	v_exp_f32_e32 v137, v135
	v_rcp_f32_e32 v135, v129
	v_add_f32_e32 v129, 1.0, v136
	v_rcp_f32_e32 v136, v129
	v_add_f32_e32 v129, 1.0, v137
	v_rcp_f32_e32 v137, v129
	v_cvt_pk_bf16_f32 v130, v130, v131
	v_cvt_pk_bf16_f32 v131, v132, v133
	v_pk_mul_f32 v[132:133], v[124:125], v[134:135]
	v_pk_mul_f32 v[134:135], v[126:127], v[136:137]
	v_mul_f32_e32 v129, 0xbfb8aa3b, v80
	v_cvt_pk_bf16_f32 v132, v132, v133
	v_cvt_pk_bf16_f32 v133, v134, v135
	v_exp_f32_e32 v129, v129
	v_mul_f32_e32 v134, 0xbfb8aa3b, v81
	v_exp_f32_e32 v134, v134
	ds_write2_b64 v128, v[130:131], v[132:133] offset0:4 offset1:6
	v_add_f32_e32 v129, 1.0, v129
	v_rcp_f32_e32 v130, v129
	v_add_f32_e32 v129, 1.0, v134
	v_rcp_f32_e32 v131, v129
	v_mul_f32_e32 v129, 0xbfb8aa3b, v82
	v_exp_f32_e32 v129, v129
	v_mul_f32_e32 v132, 0xbfb8aa3b, v83
	v_exp_f32_e32 v133, v132
	v_mul_f32_e32 v134, 0xbfb8aa3b, v85
	v_add_f32_e32 v129, 1.0, v129
	v_rcp_f32_e32 v132, v129
	v_add_f32_e32 v129, 1.0, v133
	v_rcp_f32_e32 v133, v129
	v_mul_f32_e32 v129, 0xbfb8aa3b, v84
	v_exp_f32_e32 v129, v129
	v_exp_f32_e32 v135, v134
	v_pk_mul_f32 v[130:131], v[80:81], v[130:131]
	v_pk_mul_f32 v[132:133], v[82:83], v[132:133]
	v_add_f32_e32 v129, 1.0, v129
	v_rcp_f32_e32 v134, v129
	v_add_f32_e32 v129, 1.0, v135
	v_mul_f32_e32 v135, 0xbfb8aa3b, v86
	v_exp_f32_e32 v136, v135
	v_mul_f32_e32 v135, 0xbfb8aa3b, v87
	v_exp_f32_e32 v137, v135
	v_rcp_f32_e32 v135, v129
	v_add_f32_e32 v129, 1.0, v136
	v_rcp_f32_e32 v136, v129
	v_add_f32_e32 v129, 1.0, v137
	v_rcp_f32_e32 v137, v129
	v_cvt_pk_bf16_f32 v130, v130, v131
	v_cvt_pk_bf16_f32 v131, v132, v133
	v_pk_mul_f32 v[132:133], v[84:85], v[134:135]
	v_pk_mul_f32 v[134:135], v[86:87], v[136:137]
	v_mul_f32_e32 v129, 0xbfb8aa3b, v88
	v_cvt_pk_bf16_f32 v132, v132, v133
	v_cvt_pk_bf16_f32 v133, v134, v135
	v_exp_f32_e32 v129, v129
	v_mul_f32_e32 v134, 0xbfb8aa3b, v89
	v_exp_f32_e32 v134, v134
	ds_write2_b64 v128, v[130:131], v[132:133] offset0:8 offset1:10
	v_add_f32_e32 v129, 1.0, v129
	v_rcp_f32_e32 v130, v129
	v_add_f32_e32 v129, 1.0, v134
	v_rcp_f32_e32 v131, v129
	v_mul_f32_e32 v129, 0xbfb8aa3b, v90
	v_exp_f32_e32 v129, v129
	v_mul_f32_e32 v132, 0xbfb8aa3b, v91
	v_exp_f32_e32 v133, v132
	v_mul_f32_e32 v134, 0xbfb8aa3b, v93
	v_add_f32_e32 v129, 1.0, v129
	v_rcp_f32_e32 v132, v129
	v_add_f32_e32 v129, 1.0, v133
	v_rcp_f32_e32 v133, v129
	v_mul_f32_e32 v129, 0xbfb8aa3b, v92
	v_exp_f32_e32 v129, v129
	v_exp_f32_e32 v135, v134
	v_pk_mul_f32 v[130:131], v[88:89], v[130:131]
	v_pk_mul_f32 v[132:133], v[90:91], v[132:133]
	v_add_f32_e32 v129, 1.0, v129
	v_rcp_f32_e32 v134, v129
	v_add_f32_e32 v129, 1.0, v135
	v_mul_f32_e32 v135, 0xbfb8aa3b, v94
	v_exp_f32_e32 v136, v135
	v_mul_f32_e32 v135, 0xbfb8aa3b, v95
	v_exp_f32_e32 v137, v135
	v_rcp_f32_e32 v135, v129
	v_add_f32_e32 v129, 1.0, v136
	v_rcp_f32_e32 v136, v129
	v_add_f32_e32 v129, 1.0, v137
	v_rcp_f32_e32 v137, v129
	v_cvt_pk_bf16_f32 v130, v130, v131
	v_cvt_pk_bf16_f32 v131, v132, v133
	v_pk_mul_f32 v[132:133], v[92:93], v[134:135]
	v_pk_mul_f32 v[134:135], v[94:95], v[136:137]
	v_mul_f32_e32 v129, 0xbfb8aa3b, v96
	v_cvt_pk_bf16_f32 v132, v132, v133
	v_cvt_pk_bf16_f32 v133, v134, v135
	v_exp_f32_e32 v129, v129
	v_mul_f32_e32 v134, 0xbfb8aa3b, v97
	v_exp_f32_e32 v134, v134
	ds_write2_b64 v128, v[130:131], v[132:133] offset0:12 offset1:14
	v_add_f32_e32 v129, 1.0, v129
	v_rcp_f32_e32 v130, v129
	v_add_f32_e32 v129, 1.0, v134
	v_rcp_f32_e32 v131, v129
	v_mul_f32_e32 v129, 0xbfb8aa3b, v98
	v_exp_f32_e32 v129, v129
	v_mul_f32_e32 v132, 0xbfb8aa3b, v99
	v_exp_f32_e32 v133, v132
	v_mul_f32_e32 v134, 0xbfb8aa3b, v101
	v_add_f32_e32 v129, 1.0, v129
	v_rcp_f32_e32 v132, v129
	v_add_f32_e32 v129, 1.0, v133
	v_rcp_f32_e32 v133, v129
	v_mul_f32_e32 v129, 0xbfb8aa3b, v100
	v_exp_f32_e32 v129, v129
	v_exp_f32_e32 v135, v134
	v_pk_mul_f32 v[130:131], v[96:97], v[130:131]
	v_pk_mul_f32 v[132:133], v[98:99], v[132:133]
	v_add_f32_e32 v129, 1.0, v129
	v_rcp_f32_e32 v134, v129
	v_add_f32_e32 v129, 1.0, v135
	v_mul_f32_e32 v135, 0xbfb8aa3b, v102
	v_exp_f32_e32 v136, v135
	v_mul_f32_e32 v135, 0xbfb8aa3b, v103
	v_exp_f32_e32 v137, v135
	v_rcp_f32_e32 v135, v129
	v_add_f32_e32 v129, 1.0, v136
	v_rcp_f32_e32 v136, v129
	v_add_f32_e32 v129, 1.0, v137
	v_rcp_f32_e32 v137, v129
	v_cvt_pk_bf16_f32 v130, v130, v131
	v_cvt_pk_bf16_f32 v131, v132, v133
	v_pk_mul_f32 v[132:133], v[100:101], v[134:135]
	v_pk_mul_f32 v[134:135], v[102:103], v[136:137]
	v_mul_f32_e32 v129, 0xbfb8aa3b, v104
	v_cvt_pk_bf16_f32 v132, v132, v133
	v_cvt_pk_bf16_f32 v133, v134, v135
	v_exp_f32_e32 v129, v129
	v_mul_f32_e32 v134, 0xbfb8aa3b, v105
	v_exp_f32_e32 v134, v134
	ds_write2_b64 v128, v[130:131], v[132:133] offset0:16 offset1:18
	v_add_f32_e32 v129, 1.0, v129
	v_rcp_f32_e32 v130, v129
	v_add_f32_e32 v129, 1.0, v134
	v_rcp_f32_e32 v131, v129
	v_mul_f32_e32 v129, 0xbfb8aa3b, v106
	v_exp_f32_e32 v129, v129
	v_mul_f32_e32 v132, 0xbfb8aa3b, v107
	v_exp_f32_e32 v133, v132
	v_mul_f32_e32 v134, 0xbfb8aa3b, v109
	v_add_f32_e32 v129, 1.0, v129
	v_rcp_f32_e32 v132, v129
	v_add_f32_e32 v129, 1.0, v133
	v_rcp_f32_e32 v133, v129
	v_mul_f32_e32 v129, 0xbfb8aa3b, v108
	v_exp_f32_e32 v129, v129
	v_exp_f32_e32 v135, v134
	v_pk_mul_f32 v[130:131], v[104:105], v[130:131]
	v_pk_mul_f32 v[132:133], v[106:107], v[132:133]
	v_add_f32_e32 v129, 1.0, v129
	v_rcp_f32_e32 v134, v129
	v_add_f32_e32 v129, 1.0, v135
	v_mul_f32_e32 v135, 0xbfb8aa3b, v110
	v_exp_f32_e32 v136, v135
	v_mul_f32_e32 v135, 0xbfb8aa3b, v111
	v_exp_f32_e32 v137, v135
	v_rcp_f32_e32 v135, v129
	v_add_f32_e32 v129, 1.0, v136
	v_rcp_f32_e32 v136, v129
	v_add_f32_e32 v129, 1.0, v137
	v_rcp_f32_e32 v137, v129
	v_cvt_pk_bf16_f32 v130, v130, v131
	v_cvt_pk_bf16_f32 v131, v132, v133
	v_pk_mul_f32 v[132:133], v[108:109], v[134:135]
	v_pk_mul_f32 v[134:135], v[110:111], v[136:137]
	v_mul_f32_e32 v129, 0xbfb8aa3b, v64
	v_cvt_pk_bf16_f32 v132, v132, v133
	v_cvt_pk_bf16_f32 v133, v134, v135
	v_exp_f32_e32 v129, v129
	v_mul_f32_e32 v134, 0xbfb8aa3b, v65
	v_exp_f32_e32 v134, v134
	ds_write2_b64 v128, v[130:131], v[132:133] offset0:20 offset1:22
	v_add_f32_e32 v129, 1.0, v129
	v_rcp_f32_e32 v130, v129
	v_add_f32_e32 v129, 1.0, v134
	v_rcp_f32_e32 v131, v129
	v_mul_f32_e32 v129, 0xbfb8aa3b, v66
	v_exp_f32_e32 v129, v129
	v_mul_f32_e32 v132, 0xbfb8aa3b, v67
	v_exp_f32_e32 v133, v132
	v_mul_f32_e32 v134, 0xbfb8aa3b, v69
	v_add_f32_e32 v129, 1.0, v129
	v_rcp_f32_e32 v132, v129
	v_add_f32_e32 v129, 1.0, v133
	v_rcp_f32_e32 v133, v129
	v_mul_f32_e32 v129, 0xbfb8aa3b, v68
	v_exp_f32_e32 v129, v129
	v_exp_f32_e32 v135, v134
	v_pk_mul_f32 v[130:131], v[64:65], v[130:131]
	v_pk_mul_f32 v[132:133], v[66:67], v[132:133]
	v_add_f32_e32 v129, 1.0, v129
	v_rcp_f32_e32 v134, v129
	v_add_f32_e32 v129, 1.0, v135
	v_mul_f32_e32 v135, 0xbfb8aa3b, v70
	v_exp_f32_e32 v136, v135
	v_mul_f32_e32 v135, 0xbfb8aa3b, v71
	v_exp_f32_e32 v137, v135
	v_rcp_f32_e32 v135, v129
	v_add_f32_e32 v129, 1.0, v136
	v_rcp_f32_e32 v136, v129
	v_add_f32_e32 v129, 1.0, v137
	v_rcp_f32_e32 v137, v129
	v_cvt_pk_bf16_f32 v130, v130, v131
	v_cvt_pk_bf16_f32 v131, v132, v133
	v_pk_mul_f32 v[132:133], v[68:69], v[134:135]
	v_pk_mul_f32 v[134:135], v[70:71], v[136:137]
	v_mul_f32_e32 v129, 0xbfb8aa3b, v72
	v_cvt_pk_bf16_f32 v132, v132, v133
	v_cvt_pk_bf16_f32 v133, v134, v135
	v_exp_f32_e32 v129, v129
	v_mul_f32_e32 v134, 0xbfb8aa3b, v73
	v_exp_f32_e32 v134, v134
	ds_write2_b64 v128, v[130:131], v[132:133] offset0:24 offset1:26
	v_add_f32_e32 v129, 1.0, v129
	v_rcp_f32_e32 v130, v129
	v_add_f32_e32 v129, 1.0, v134
	v_rcp_f32_e32 v131, v129
	v_mul_f32_e32 v129, 0xbfb8aa3b, v74
	v_exp_f32_e32 v129, v129
	v_mul_f32_e32 v132, 0xbfb8aa3b, v75
	v_exp_f32_e32 v133, v132
	v_mul_f32_e32 v134, 0xbfb8aa3b, v77
	v_add_f32_e32 v129, 1.0, v129
	v_rcp_f32_e32 v132, v129
	v_add_f32_e32 v129, 1.0, v133
	v_rcp_f32_e32 v133, v129
	v_mul_f32_e32 v129, 0xbfb8aa3b, v76
	v_exp_f32_e32 v129, v129
	v_exp_f32_e32 v135, v134
	v_pk_mul_f32 v[130:131], v[72:73], v[130:131]
	v_pk_mul_f32 v[132:133], v[74:75], v[132:133]
	v_add_f32_e32 v129, 1.0, v129
	v_rcp_f32_e32 v134, v129
	v_add_f32_e32 v129, 1.0, v135
	v_mul_f32_e32 v135, 0xbfb8aa3b, v78
	v_exp_f32_e32 v136, v135
	v_mul_f32_e32 v135, 0xbfb8aa3b, v79
	v_exp_f32_e32 v137, v135
	v_rcp_f32_e32 v135, v129
	v_add_f32_e32 v129, 1.0, v136
	v_rcp_f32_e32 v136, v129
	v_add_f32_e32 v129, 1.0, v137
	v_rcp_f32_e32 v137, v129
	v_cvt_pk_bf16_f32 v130, v130, v131
	v_cvt_pk_bf16_f32 v131, v132, v133
	v_pk_mul_f32 v[132:133], v[76:77], v[134:135]
	v_pk_mul_f32 v[134:135], v[78:79], v[136:137]
	v_mul_f32_e32 v129, 0xbfb8aa3b, v48
	v_cvt_pk_bf16_f32 v132, v132, v133
	v_cvt_pk_bf16_f32 v133, v134, v135
	v_exp_f32_e32 v129, v129
	v_mul_f32_e32 v134, 0xbfb8aa3b, v49
	v_exp_f32_e32 v134, v134
	ds_write2_b64 v128, v[130:131], v[132:133] offset0:28 offset1:30
	v_add_f32_e32 v129, 1.0, v129
	v_rcp_f32_e32 v130, v129
	v_add_f32_e32 v129, 1.0, v134
	v_rcp_f32_e32 v131, v129
	v_mul_f32_e32 v129, 0xbfb8aa3b, v50
	v_exp_f32_e32 v129, v129
	v_mul_f32_e32 v132, 0xbfb8aa3b, v51
	v_exp_f32_e32 v133, v132
	v_mul_f32_e32 v134, 0xbfb8aa3b, v53
	v_add_f32_e32 v129, 1.0, v129
	v_rcp_f32_e32 v132, v129
	v_add_f32_e32 v129, 1.0, v133
	v_rcp_f32_e32 v133, v129
	v_mul_f32_e32 v129, 0xbfb8aa3b, v52
	v_exp_f32_e32 v129, v129
	v_exp_f32_e32 v135, v134
	v_pk_mul_f32 v[130:131], v[48:49], v[130:131]
	v_pk_mul_f32 v[132:133], v[50:51], v[132:133]
	v_add_f32_e32 v129, 1.0, v129
	v_rcp_f32_e32 v134, v129
	v_add_f32_e32 v129, 1.0, v135
	v_mul_f32_e32 v135, 0xbfb8aa3b, v54
	v_exp_f32_e32 v136, v135
	v_mul_f32_e32 v135, 0xbfb8aa3b, v55
	v_exp_f32_e32 v137, v135
	v_rcp_f32_e32 v135, v129
	v_add_f32_e32 v129, 1.0, v136
	v_rcp_f32_e32 v136, v129
	v_add_f32_e32 v129, 1.0, v137
	v_rcp_f32_e32 v137, v129
	v_cvt_pk_bf16_f32 v130, v130, v131
	v_cvt_pk_bf16_f32 v131, v132, v133
	v_pk_mul_f32 v[132:133], v[52:53], v[134:135]
	v_pk_mul_f32 v[134:135], v[54:55], v[136:137]
	v_mul_f32_e32 v129, 0xbfb8aa3b, v56
	v_cvt_pk_bf16_f32 v132, v132, v133
	v_cvt_pk_bf16_f32 v133, v134, v135
	v_exp_f32_e32 v129, v129
	v_mul_f32_e32 v134, 0xbfb8aa3b, v57
	v_exp_f32_e32 v134, v134
	v_add_u32_e32 v128, 0x4000, v128
	v_add_f32_e32 v129, 1.0, v129
	ds_write2_b64 v128, v[130:131], v[132:133] offset0:64 offset1:66
	v_rcp_f32_e32 v130, v129
	v_add_f32_e32 v129, 1.0, v134
	v_rcp_f32_e32 v131, v129
	v_mul_f32_e32 v129, 0xbfb8aa3b, v58
	v_exp_f32_e32 v129, v129
	v_mul_f32_e32 v132, 0xbfb8aa3b, v59
	v_exp_f32_e32 v133, v132
	v_mul_f32_e32 v134, 0xbfb8aa3b, v61
	v_add_f32_e32 v129, 1.0, v129
	v_rcp_f32_e32 v132, v129
	v_add_f32_e32 v129, 1.0, v133
	v_rcp_f32_e32 v133, v129
	v_mul_f32_e32 v129, 0xbfb8aa3b, v60
	v_exp_f32_e32 v129, v129
	v_exp_f32_e32 v135, v134
	v_pk_mul_f32 v[130:131], v[56:57], v[130:131]
	v_pk_mul_f32 v[132:133], v[58:59], v[132:133]
	v_add_f32_e32 v129, 1.0, v129
	v_rcp_f32_e32 v134, v129
	v_add_f32_e32 v129, 1.0, v135
	v_mul_f32_e32 v135, 0xbfb8aa3b, v62
	v_exp_f32_e32 v136, v135
	v_mul_f32_e32 v135, 0xbfb8aa3b, v63
	v_exp_f32_e32 v137, v135
	v_rcp_f32_e32 v135, v129
	v_add_f32_e32 v129, 1.0, v136
	v_rcp_f32_e32 v136, v129
	v_add_f32_e32 v129, 1.0, v137
	v_rcp_f32_e32 v137, v129
	v_cvt_pk_bf16_f32 v130, v130, v131
	v_cvt_pk_bf16_f32 v131, v132, v133
	v_pk_mul_f32 v[132:133], v[60:61], v[134:135]
	v_pk_mul_f32 v[134:135], v[62:63], v[136:137]
	v_mul_f32_e32 v129, 0xbfb8aa3b, v16
	v_cvt_pk_bf16_f32 v132, v132, v133
	v_cvt_pk_bf16_f32 v133, v134, v135
	v_exp_f32_e32 v129, v129
	v_mul_f32_e32 v134, 0xbfb8aa3b, v17
	v_exp_f32_e32 v134, v134
	ds_write2_b64 v128, v[130:131], v[132:133] offset0:68 offset1:70
	v_add_f32_e32 v129, 1.0, v129
	v_rcp_f32_e32 v130, v129
	v_add_f32_e32 v129, 1.0, v134
	v_rcp_f32_e32 v131, v129
	v_mul_f32_e32 v129, 0xbfb8aa3b, v18
	v_exp_f32_e32 v129, v129
	v_mul_f32_e32 v132, 0xbfb8aa3b, v19
	v_exp_f32_e32 v133, v132
	v_mul_f32_e32 v134, 0xbfb8aa3b, v21
	v_add_f32_e32 v129, 1.0, v129
	v_rcp_f32_e32 v132, v129
	v_add_f32_e32 v129, 1.0, v133
	v_rcp_f32_e32 v133, v129
	v_mul_f32_e32 v129, 0xbfb8aa3b, v20
	v_exp_f32_e32 v129, v129
	v_exp_f32_e32 v135, v134
	v_pk_mul_f32 v[130:131], v[16:17], v[130:131]
	v_pk_mul_f32 v[132:133], v[18:19], v[132:133]
	v_add_f32_e32 v129, 1.0, v129
	v_rcp_f32_e32 v134, v129
	v_add_f32_e32 v129, 1.0, v135
	v_mul_f32_e32 v135, 0xbfb8aa3b, v22
	v_exp_f32_e32 v136, v135
	v_mul_f32_e32 v135, 0xbfb8aa3b, v23
	v_exp_f32_e32 v137, v135
	v_rcp_f32_e32 v135, v129
	v_add_f32_e32 v129, 1.0, v136
	v_rcp_f32_e32 v136, v129
	v_add_f32_e32 v129, 1.0, v137
	v_rcp_f32_e32 v137, v129
	v_cvt_pk_bf16_f32 v130, v130, v131
	v_cvt_pk_bf16_f32 v131, v132, v133
	v_pk_mul_f32 v[132:133], v[20:21], v[134:135]
	v_pk_mul_f32 v[134:135], v[22:23], v[136:137]
	v_mul_f32_e32 v129, 0xbfb8aa3b, v24
	v_cvt_pk_bf16_f32 v132, v132, v133
	v_cvt_pk_bf16_f32 v133, v134, v135
	v_exp_f32_e32 v129, v129
	v_mul_f32_e32 v134, 0xbfb8aa3b, v25
	v_exp_f32_e32 v134, v134
	ds_write2_b64 v128, v[130:131], v[132:133] offset0:72 offset1:74
	v_add_f32_e32 v129, 1.0, v129
	v_rcp_f32_e32 v130, v129
	v_add_f32_e32 v129, 1.0, v134
	v_rcp_f32_e32 v131, v129
	v_mul_f32_e32 v129, 0xbfb8aa3b, v26
	v_exp_f32_e32 v129, v129
	v_mul_f32_e32 v132, 0xbfb8aa3b, v27
	v_exp_f32_e32 v133, v132
	v_mul_f32_e32 v134, 0xbfb8aa3b, v29
	v_add_f32_e32 v129, 1.0, v129
	v_rcp_f32_e32 v132, v129
	v_add_f32_e32 v129, 1.0, v133
	v_rcp_f32_e32 v133, v129
	v_mul_f32_e32 v129, 0xbfb8aa3b, v28
	v_exp_f32_e32 v129, v129
	v_exp_f32_e32 v135, v134
	v_pk_mul_f32 v[130:131], v[24:25], v[130:131]
	v_pk_mul_f32 v[132:133], v[26:27], v[132:133]
	v_add_f32_e32 v129, 1.0, v129
	v_rcp_f32_e32 v134, v129
	v_add_f32_e32 v129, 1.0, v135
	v_mul_f32_e32 v135, 0xbfb8aa3b, v30
	v_exp_f32_e32 v136, v135
	v_mul_f32_e32 v135, 0xbfb8aa3b, v31
	v_exp_f32_e32 v137, v135
	v_rcp_f32_e32 v135, v129
	v_add_f32_e32 v129, 1.0, v136
	v_rcp_f32_e32 v136, v129
	v_add_f32_e32 v129, 1.0, v137
	v_rcp_f32_e32 v137, v129
	v_cvt_pk_bf16_f32 v130, v130, v131
	v_cvt_pk_bf16_f32 v131, v132, v133
	v_pk_mul_f32 v[132:133], v[28:29], v[134:135]
	v_pk_mul_f32 v[134:135], v[30:31], v[136:137]
	v_mul_f32_e32 v129, 0xbfb8aa3b, v32
	v_cvt_pk_bf16_f32 v132, v132, v133
	v_cvt_pk_bf16_f32 v133, v134, v135
	v_exp_f32_e32 v129, v129
	v_mul_f32_e32 v134, 0xbfb8aa3b, v33
	v_exp_f32_e32 v134, v134
	ds_write2_b64 v128, v[130:131], v[132:133] offset0:76 offset1:78
	v_add_f32_e32 v129, 1.0, v129
	v_rcp_f32_e32 v130, v129
	v_add_f32_e32 v129, 1.0, v134
	v_rcp_f32_e32 v131, v129
	v_mul_f32_e32 v129, 0xbfb8aa3b, v34
	v_exp_f32_e32 v129, v129
	v_mul_f32_e32 v132, 0xbfb8aa3b, v35
	v_exp_f32_e32 v133, v132
	v_mul_f32_e32 v134, 0xbfb8aa3b, v37
	v_add_f32_e32 v129, 1.0, v129
	v_rcp_f32_e32 v132, v129
	v_add_f32_e32 v129, 1.0, v133
	v_rcp_f32_e32 v133, v129
	v_mul_f32_e32 v129, 0xbfb8aa3b, v36
	v_exp_f32_e32 v129, v129
	v_exp_f32_e32 v135, v134
	v_pk_mul_f32 v[130:131], v[32:33], v[130:131]
	v_pk_mul_f32 v[132:133], v[34:35], v[132:133]
	v_add_f32_e32 v129, 1.0, v129
	v_rcp_f32_e32 v134, v129
	v_add_f32_e32 v129, 1.0, v135
	v_mul_f32_e32 v135, 0xbfb8aa3b, v38
	v_exp_f32_e32 v136, v135
	v_mul_f32_e32 v135, 0xbfb8aa3b, v39
	v_exp_f32_e32 v137, v135
	v_rcp_f32_e32 v135, v129
	v_add_f32_e32 v129, 1.0, v136
	v_rcp_f32_e32 v136, v129
	v_add_f32_e32 v129, 1.0, v137
	v_rcp_f32_e32 v137, v129
	v_cvt_pk_bf16_f32 v130, v130, v131
	v_cvt_pk_bf16_f32 v131, v132, v133
	v_pk_mul_f32 v[132:133], v[36:37], v[134:135]
	v_pk_mul_f32 v[134:135], v[38:39], v[136:137]
	v_mul_f32_e32 v129, 0xbfb8aa3b, v40
	v_cvt_pk_bf16_f32 v132, v132, v133
	v_cvt_pk_bf16_f32 v133, v134, v135
	v_exp_f32_e32 v129, v129
	v_mul_f32_e32 v134, 0xbfb8aa3b, v41
	v_exp_f32_e32 v134, v134
	ds_write2_b64 v128, v[130:131], v[132:133] offset0:80 offset1:82
	v_add_f32_e32 v129, 1.0, v129
	v_rcp_f32_e32 v130, v129
	v_add_f32_e32 v129, 1.0, v134
	v_rcp_f32_e32 v131, v129
	v_mul_f32_e32 v129, 0xbfb8aa3b, v42
	v_exp_f32_e32 v129, v129
	v_mul_f32_e32 v132, 0xbfb8aa3b, v43
	v_exp_f32_e32 v133, v132
	v_mul_f32_e32 v134, 0xbfb8aa3b, v45
	v_add_f32_e32 v129, 1.0, v129
	v_rcp_f32_e32 v132, v129
	v_add_f32_e32 v129, 1.0, v133
	v_rcp_f32_e32 v133, v129
	v_mul_f32_e32 v129, 0xbfb8aa3b, v44
	v_exp_f32_e32 v129, v129
	v_exp_f32_e32 v135, v134
	v_pk_mul_f32 v[130:131], v[40:41], v[130:131]
	v_pk_mul_f32 v[132:133], v[42:43], v[132:133]
	v_add_f32_e32 v129, 1.0, v129
	v_rcp_f32_e32 v134, v129
	v_add_f32_e32 v129, 1.0, v135
	v_mul_f32_e32 v135, 0xbfb8aa3b, v46
	v_exp_f32_e32 v136, v135
	v_mul_f32_e32 v135, 0xbfb8aa3b, v47
	v_exp_f32_e32 v137, v135
	v_rcp_f32_e32 v135, v129
	v_add_f32_e32 v129, 1.0, v136
	v_rcp_f32_e32 v136, v129
	v_add_f32_e32 v129, 1.0, v137
	v_rcp_f32_e32 v137, v129
	v_cvt_pk_bf16_f32 v130, v130, v131
	v_cvt_pk_bf16_f32 v131, v132, v133
	v_pk_mul_f32 v[132:133], v[44:45], v[134:135]
	v_pk_mul_f32 v[134:135], v[46:47], v[136:137]
	v_mul_f32_e32 v129, 0xbfb8aa3b, v0
	v_cvt_pk_bf16_f32 v132, v132, v133
	v_cvt_pk_bf16_f32 v133, v134, v135
	v_exp_f32_e32 v129, v129
	v_mul_f32_e32 v134, 0xbfb8aa3b, v1
	v_exp_f32_e32 v134, v134
	ds_write2_b64 v128, v[130:131], v[132:133] offset0:84 offset1:86
	v_add_f32_e32 v129, 1.0, v129
	v_rcp_f32_e32 v130, v129
	v_add_f32_e32 v129, 1.0, v134
	v_rcp_f32_e32 v131, v129
	v_mul_f32_e32 v129, 0xbfb8aa3b, v2
	v_exp_f32_e32 v129, v129
	v_mul_f32_e32 v132, 0xbfb8aa3b, v3
	v_exp_f32_e32 v133, v132
	v_mul_f32_e32 v134, 0xbfb8aa3b, v5
	v_add_f32_e32 v129, 1.0, v129
	v_rcp_f32_e32 v132, v129
	v_add_f32_e32 v129, 1.0, v133
	v_rcp_f32_e32 v133, v129
	v_mul_f32_e32 v129, 0xbfb8aa3b, v4
	v_exp_f32_e32 v129, v129
	v_exp_f32_e32 v135, v134
	v_pk_mul_f32 v[130:131], v[0:1], v[130:131]
	v_pk_mul_f32 v[132:133], v[2:3], v[132:133]
	v_add_f32_e32 v129, 1.0, v129
	v_rcp_f32_e32 v134, v129
	v_add_f32_e32 v129, 1.0, v135
	v_mul_f32_e32 v135, 0xbfb8aa3b, v6
	v_exp_f32_e32 v136, v135
	v_mul_f32_e32 v135, 0xbfb8aa3b, v7
	v_exp_f32_e32 v137, v135
	v_rcp_f32_e32 v135, v129
	v_add_f32_e32 v129, 1.0, v136
	v_rcp_f32_e32 v136, v129
	v_add_f32_e32 v129, 1.0, v137
	v_rcp_f32_e32 v137, v129
	v_cvt_pk_bf16_f32 v130, v130, v131
	v_cvt_pk_bf16_f32 v131, v132, v133
	v_pk_mul_f32 v[132:133], v[4:5], v[134:135]
	v_pk_mul_f32 v[134:135], v[6:7], v[136:137]
	v_mul_f32_e32 v129, 0xbfb8aa3b, v8
	v_cvt_pk_bf16_f32 v132, v132, v133
	v_cvt_pk_bf16_f32 v133, v134, v135
	v_exp_f32_e32 v129, v129
	v_mul_f32_e32 v134, 0xbfb8aa3b, v9
	v_exp_f32_e32 v134, v134
	ds_write2_b64 v128, v[130:131], v[132:133] offset0:88 offset1:90
	v_add_f32_e32 v129, 1.0, v129
	v_rcp_f32_e32 v130, v129
	v_add_f32_e32 v129, 1.0, v134
	v_rcp_f32_e32 v131, v129
	v_mul_f32_e32 v129, 0xbfb8aa3b, v10
	v_exp_f32_e32 v129, v129
	v_mul_f32_e32 v132, 0xbfb8aa3b, v11
	v_exp_f32_e32 v133, v132
	v_mul_f32_e32 v134, 0xbfb8aa3b, v13
	v_add_f32_e32 v129, 1.0, v129
	v_rcp_f32_e32 v132, v129
	v_add_f32_e32 v129, 1.0, v133
	v_rcp_f32_e32 v133, v129
	v_mul_f32_e32 v129, 0xbfb8aa3b, v12
	v_exp_f32_e32 v129, v129
	v_exp_f32_e32 v135, v134
	s_add_i32 s12, s36, -14
	s_lshl_b64 s[2:3], s[12:13], 9
	v_add_f32_e32 v129, 1.0, v129
	v_rcp_f32_e32 v134, v129
	v_add_f32_e32 v129, 1.0, v135
	v_mul_f32_e32 v135, 0xbfb8aa3b, v14
	v_exp_f32_e32 v136, v135
	v_mul_f32_e32 v135, 0xbfb8aa3b, v15
	v_exp_f32_e32 v137, v135
	v_rcp_f32_e32 v135, v129
	v_add_f32_e32 v129, 1.0, v136
	v_rcp_f32_e32 v136, v129
	v_add_f32_e32 v129, 1.0, v137
	v_rcp_f32_e32 v137, v129
	v_pk_mul_f32 v[130:131], v[8:9], v[130:131]
	v_pk_mul_f32 v[132:133], v[10:11], v[132:133]
	s_add_u32 s12, s61, s2
	v_cvt_pk_bf16_f32 v130, v130, v131
	v_cvt_pk_bf16_f32 v131, v132, v133
	v_pk_mul_f32 v[132:133], v[12:13], v[134:135]
	v_pk_mul_f32 v[134:135], v[14:15], v[136:137]
	s_addc_u32 s37, s62, s3
	s_lshl_b64 s[2:3], s[34:35], 20
	v_cvt_pk_bf16_f32 v132, v132, v133
	v_cvt_pk_bf16_f32 v133, v134, v135
	v_mov_b32_e32 v142, v208
	s_add_u32 s2, s12, s2
	ds_write2_b64 v128, v[130:131], v[132:133] offset0:92 offset1:94
	s_addc_u32 s3, s37, s3
	v_lshlrev_b32_e32 v128, 4, v142
	v_ashrrev_i32_e32 v132, 5, v142
	v_and_b32_e32 v170, 0x1f0, v128
	v_ashrrev_i32_e32 v133, 31, v132
	v_lshl_add_u64 v[136:137], s[2:3], 0, v[170:171]
	v_mad_u64_u32 v[128:129], s[2:3], v132, s43, v[170:171]
	v_lshlrev_b64 v[132:133], 12, v[132:133]
	v_lshl_add_u64 v[138:139], v[136:137], 0, v[132:133]
	v_add_u32_e32 v132, 0x200, v142
	s_waitcnt lgkmcnt(0)
	s_barrier
	ds_read_b128 v[128:131], v128
	v_ashrrev_i32_e32 v140, 5, v132
	v_mad_u64_u32 v[132:133], s[2:3], v140, s43, v[170:171]
	ds_read_b128 v[132:135], v132
	v_ashrrev_i32_e32 v141, 31, v140
	s_waitcnt lgkmcnt(1)
	global_store_dwordx4 v[138:139], v[128:131], off
	s_nop 1
	v_lshlrev_b64 v[128:129], 12, v[140:141]
	v_lshl_add_u64 v[128:129], v[136:137], 0, v[128:129]
	s_waitcnt lgkmcnt(0)
	global_store_dwordx4 v[128:129], v[132:135], off
	v_add_u32_e32 v128, 0x400, v142
	s_nop 0
	v_ashrrev_i32_e32 v132, 5, v128
	v_ashrrev_i32_e32 v133, 31, v132
	v_mad_u64_u32 v[128:129], s[2:3], v132, s43, v[170:171]
	v_lshlrev_b64 v[132:133], 12, v[132:133]
	v_lshl_add_u64 v[138:139], v[136:137], 0, v[132:133]
	v_add_u32_e32 v132, 0x600, v142
	ds_read_b128 v[128:131], v128
	v_ashrrev_i32_e32 v140, 5, v132
	v_mad_u64_u32 v[132:133], s[2:3], v140, s43, v[170:171]
	ds_read_b128 v[132:135], v132
	v_ashrrev_i32_e32 v141, 31, v140
	s_waitcnt lgkmcnt(1)
	global_store_dwordx4 v[138:139], v[128:131], off
	s_nop 1
	v_lshlrev_b64 v[128:129], 12, v[140:141]
	v_lshl_add_u64 v[128:129], v[136:137], 0, v[128:129]
	s_waitcnt lgkmcnt(0)
	global_store_dwordx4 v[128:129], v[132:135], off
	v_add_u32_e32 v128, 0x800, v142
	s_nop 0
	v_ashrrev_i32_e32 v132, 5, v128
	v_ashrrev_i32_e32 v133, 31, v132
	v_mad_u64_u32 v[128:129], s[2:3], v132, s43, v[170:171]
	v_lshlrev_b64 v[132:133], 12, v[132:133]
	v_lshl_add_u64 v[138:139], v[136:137], 0, v[132:133]
	v_add_u32_e32 v132, 0xa00, v142
	ds_read_b128 v[128:131], v128
	v_ashrrev_i32_e32 v140, 5, v132
	v_mad_u64_u32 v[132:133], s[2:3], v140, s43, v[170:171]
	ds_read_b128 v[132:135], v132
	v_ashrrev_i32_e32 v141, 31, v140
	s_waitcnt lgkmcnt(1)
	global_store_dwordx4 v[138:139], v[128:131], off
	s_nop 1
	v_lshlrev_b64 v[128:129], 12, v[140:141]
	v_lshl_add_u64 v[128:129], v[136:137], 0, v[128:129]
	s_waitcnt lgkmcnt(0)
	global_store_dwordx4 v[128:129], v[132:135], off
	v_add_u32_e32 v128, 0xc00, v142
	s_nop 0
	v_ashrrev_i32_e32 v132, 5, v128
	v_ashrrev_i32_e32 v133, 31, v132
	v_mad_u64_u32 v[128:129], s[2:3], v132, s43, v[170:171]
	v_lshlrev_b64 v[132:133], 12, v[132:133]
	v_lshl_add_u64 v[138:139], v[136:137], 0, v[132:133]
	v_add_u32_e32 v132, 0xe00, v142
	ds_read_b128 v[128:131], v128
	v_ashrrev_i32_e32 v140, 5, v132
	v_mad_u64_u32 v[132:133], s[2:3], v140, s43, v[170:171]
	ds_read_b128 v[132:135], v132
	v_ashrrev_i32_e32 v141, 31, v140
	s_waitcnt lgkmcnt(1)
	global_store_dwordx4 v[138:139], v[128:131], off
	s_nop 1
	v_lshlrev_b64 v[128:129], 12, v[140:141]
	v_lshl_add_u64 v[128:129], v[136:137], 0, v[128:129]
	s_waitcnt lgkmcnt(0)
	global_store_dwordx4 v[128:129], v[132:135], off
	v_add_u32_e32 v128, 0x1000, v142
	s_nop 0
	v_ashrrev_i32_e32 v132, 5, v128
	v_ashrrev_i32_e32 v133, 31, v132
	v_mad_u64_u32 v[128:129], s[2:3], v132, s43, v[170:171]
	v_lshlrev_b64 v[132:133], 12, v[132:133]
	v_lshl_add_u64 v[138:139], v[136:137], 0, v[132:133]
	v_add_u32_e32 v132, 0x1200, v142
	ds_read_b128 v[128:131], v128
	v_ashrrev_i32_e32 v140, 5, v132
	v_mad_u64_u32 v[132:133], s[2:3], v140, s43, v[170:171]
	ds_read_b128 v[132:135], v132
	v_ashrrev_i32_e32 v141, 31, v140
	s_waitcnt lgkmcnt(1)
	global_store_dwordx4 v[138:139], v[128:131], off
	s_nop 1
	v_lshlrev_b64 v[128:129], 12, v[140:141]
	v_lshl_add_u64 v[128:129], v[136:137], 0, v[128:129]
	s_waitcnt lgkmcnt(0)
	global_store_dwordx4 v[128:129], v[132:135], off
	v_add_u32_e32 v128, 0x1400, v142
	s_nop 0
	v_ashrrev_i32_e32 v132, 5, v128
	v_ashrrev_i32_e32 v133, 31, v132
	v_mad_u64_u32 v[128:129], s[2:3], v132, s43, v[170:171]
	v_lshlrev_b64 v[132:133], 12, v[132:133]
	v_lshl_add_u64 v[138:139], v[136:137], 0, v[132:133]
	v_add_u32_e32 v132, 0x1600, v142
	ds_read_b128 v[128:131], v128
	v_ashrrev_i32_e32 v140, 5, v132
	v_mad_u64_u32 v[132:133], s[2:3], v140, s43, v[170:171]
	ds_read_b128 v[132:135], v132
	v_ashrrev_i32_e32 v141, 31, v140
	s_waitcnt lgkmcnt(1)
	global_store_dwordx4 v[138:139], v[128:131], off
	s_nop 1
	v_lshlrev_b64 v[128:129], 12, v[140:141]
	v_lshl_add_u64 v[128:129], v[136:137], 0, v[128:129]
	s_waitcnt lgkmcnt(0)
	global_store_dwordx4 v[128:129], v[132:135], off
	v_add_u32_e32 v128, 0x1800, v142
	s_nop 0
	v_ashrrev_i32_e32 v132, 5, v128
	v_ashrrev_i32_e32 v133, 31, v132
	v_mad_u64_u32 v[128:129], s[2:3], v132, s43, v[170:171]
	v_lshlrev_b64 v[132:133], 12, v[132:133]
	v_lshl_add_u64 v[138:139], v[136:137], 0, v[132:133]
	v_add_u32_e32 v132, 0x1a00, v142
	ds_read_b128 v[128:131], v128
	v_ashrrev_i32_e32 v140, 5, v132
	v_mad_u64_u32 v[132:133], s[2:3], v140, s43, v[170:171]
	ds_read_b128 v[132:135], v132
	v_ashrrev_i32_e32 v141, 31, v140
	s_waitcnt lgkmcnt(1)
	global_store_dwordx4 v[138:139], v[128:131], off
	s_nop 1
	v_lshlrev_b64 v[128:129], 12, v[140:141]
	v_lshl_add_u64 v[128:129], v[136:137], 0, v[128:129]
	s_waitcnt lgkmcnt(0)
	global_store_dwordx4 v[128:129], v[132:135], off
	v_add_u32_e32 v128, 0x1c00, v142
	s_nop 0
	v_ashrrev_i32_e32 v132, 5, v128
	v_ashrrev_i32_e32 v133, 31, v132
	v_mad_u64_u32 v[128:129], s[2:3], v132, s43, v[170:171]
	v_lshlrev_b64 v[132:133], 12, v[132:133]
	v_lshl_add_u64 v[138:139], v[136:137], 0, v[132:133]
	v_add_u32_e32 v132, 0x1e00, v142
	ds_read_b128 v[128:131], v128
	v_ashrrev_i32_e32 v140, 5, v132
	v_mad_u64_u32 v[132:133], s[2:3], v140, s43, v[170:171]
	ds_read_b128 v[132:135], v132
	v_ashrrev_i32_e32 v141, 31, v140
	s_waitcnt lgkmcnt(1)
	global_store_dwordx4 v[138:139], v[128:131], off
	s_mov_b64 s[2:3], 0
	s_nop 0
	v_lshlrev_b64 v[128:129], 12, v[140:141]
	v_lshl_add_u64 v[128:129], v[136:137], 0, v[128:129]
	s_waitcnt lgkmcnt(0)
	global_store_dwordx4 v[128:129], v[132:135], off
	s_barrier

.Lg8_p6g_eg1:
	s_nop 7
	s_nop 7
	v_permlane16_swap_b32_e32 v112, v116
	v_permlane16_swap_b32_e32 v113, v117
	v_permlane16_swap_b32_e32 v114, v118
	v_permlane16_swap_b32_e32 v115, v119
	v_permlane16_swap_b32_e32 v120, v124
	v_permlane16_swap_b32_e32 v121, v125
	v_permlane16_swap_b32_e32 v122, v126
	v_permlane16_swap_b32_e32 v123, v127
	v_permlane16_swap_b32_e32 v96, v100
	v_permlane16_swap_b32_e32 v97, v101
	v_permlane16_swap_b32_e32 v98, v102
	v_permlane16_swap_b32_e32 v99, v103
	v_permlane16_swap_b32_e32 v104, v108
	v_permlane16_swap_b32_e32 v105, v109
	v_permlane16_swap_b32_e32 v106, v110
	v_permlane16_swap_b32_e32 v107, v111
	v_permlane16_swap_b32_e32 v80, v84
	v_permlane16_swap_b32_e32 v81, v85
	v_permlane16_swap_b32_e32 v82, v86
	v_permlane16_swap_b32_e32 v83, v87
	v_permlane16_swap_b32_e32 v88, v92
	v_permlane16_swap_b32_e32 v89, v93
	v_permlane16_swap_b32_e32 v90, v94
	v_permlane16_swap_b32_e32 v91, v95
	v_permlane16_swap_b32_e32 v64, v68
	v_permlane16_swap_b32_e32 v65, v69
	v_permlane16_swap_b32_e32 v66, v70
	v_permlane16_swap_b32_e32 v67, v71
	v_permlane16_swap_b32_e32 v72, v76
	v_permlane16_swap_b32_e32 v73, v77
	v_permlane16_swap_b32_e32 v74, v78
	v_permlane16_swap_b32_e32 v75, v79
	v_permlane16_swap_b32_e32 v48, v52
	v_permlane16_swap_b32_e32 v49, v53
	v_permlane16_swap_b32_e32 v50, v54
	v_permlane16_swap_b32_e32 v51, v55
	v_permlane16_swap_b32_e32 v56, v60
	v_permlane16_swap_b32_e32 v57, v61
	v_permlane16_swap_b32_e32 v58, v62
	v_permlane16_swap_b32_e32 v59, v63
	v_permlane16_swap_b32_e32 v32, v36
	v_permlane16_swap_b32_e32 v33, v37
	v_permlane16_swap_b32_e32 v34, v38
	v_permlane16_swap_b32_e32 v35, v39
	v_permlane16_swap_b32_e32 v40, v44
	v_permlane16_swap_b32_e32 v41, v45
	v_permlane16_swap_b32_e32 v42, v46
	v_permlane16_swap_b32_e32 v43, v47
	v_permlane16_swap_b32_e32 v16, v20
	v_permlane16_swap_b32_e32 v17, v21
	v_permlane16_swap_b32_e32 v18, v22
	v_permlane16_swap_b32_e32 v19, v23
	v_permlane16_swap_b32_e32 v24, v28
	v_permlane16_swap_b32_e32 v25, v29
	v_permlane16_swap_b32_e32 v26, v30
	v_permlane16_swap_b32_e32 v27, v31
	v_permlane16_swap_b32_e32 v0, v4
	v_permlane16_swap_b32_e32 v1, v5
	v_permlane16_swap_b32_e32 v2, v6
	v_permlane16_swap_b32_e32 v3, v7
	v_permlane16_swap_b32_e32 v8, v12
	v_permlane16_swap_b32_e32 v9, v13
	v_permlane16_swap_b32_e32 v10, v14
	v_permlane16_swap_b32_e32 v11, v15
	s_nop 1
	s_lshl_b32 s14, s6, 1
	s_add_u32 s14, s14, 0x6c00000
	s_lshl_b64 s[58:59], s[2:3], 20
	s_add_u32 s58, s58, s14
	s_addc_u32 s59, s59, 0
	s_add_u32 s56, s90, s58
	s_addc_u32 s57, s91, s59
	v_lshrrev_b32_e32 v144, 1, v208
	v_and_b32_e32 v144, 0xffffffc0, v144
	v_and_b32_e32 v140, 31, v208
	v_or_b32_e32 v140, v144, v140
	v_mul_u32_u24_e32 v140, 0x210, v140
	v_lshlrev_b32_e32 v144, 2, v208
	v_and_b32_e32 v144, 0x100, v144
	v_add_u32_e32 v140, v140, v144
	v_lshrrev_b32_e32 v144, 2, v208
	v_and_b32_e32 v144, 8, v144
	v_add_u32_e32 v140, v140, v144
	v_lshrrev_b32_e32 v144, 5, v208
	v_and_b32_e32 v143, 31, v208
	v_lshlrev_b32_e32 v143, 4, v143
	v_mul_u32_u24_e32 v141, 0x210, v144
	v_add_u32_e32 v141, v141, v143
	v_add_u32_e32 v142, 0x10800, v141
	v_mul_u32_u24_e32 v144, 0x1000, v144
	v_add_u32_e32 v143, v143, v144
	v_mov_b32_e32 v136, 0xbfb8aa3b
	v_mov_b32_e32 v137, 0xbfb8aa3b
	v_pk_mul_f32 v[128:129], v[112:113], v[136:137]
	v_pk_mul_f32 v[130:131], v[114:115], v[136:137]
	v_pk_mul_f32 v[132:133], v[116:117], v[136:137]
	v_pk_mul_f32 v[134:135], v[118:119], v[136:137]
	v_exp_f32_e32 v128, v128
	v_exp_f32_e32 v129, v129
	v_exp_f32_e32 v130, v130
	v_exp_f32_e32 v131, v131
	v_exp_f32_e32 v132, v132
	v_exp_f32_e32 v133, v133
	v_exp_f32_e32 v134, v134
	v_exp_f32_e32 v135, v135
	s_nop 0
	v_pk_add_f32 v[128:129], v[128:129], 1.0 op_sel_hi:[1,0]
	v_pk_add_f32 v[130:131], v[130:131], 1.0 op_sel_hi:[1,0]
	v_pk_add_f32 v[132:133], v[132:133], 1.0 op_sel_hi:[1,0]
	v_pk_add_f32 v[134:135], v[134:135], 1.0 op_sel_hi:[1,0]
	v_rcp_f32_e32 v128, v128
	v_rcp_f32_e32 v129, v129
	v_rcp_f32_e32 v130, v130
	v_rcp_f32_e32 v131, v131
	v_rcp_f32_e32 v132, v132
	v_rcp_f32_e32 v133, v133
	v_rcp_f32_e32 v134, v134
	v_rcp_f32_e32 v135, v135
	s_nop 0
	v_pk_mul_f32 v[112:113], v[112:113], v[128:129]
	v_pk_mul_f32 v[114:115], v[114:115], v[130:131]
	v_pk_mul_f32 v[116:117], v[116:117], v[132:133]
	v_pk_mul_f32 v[118:119], v[118:119], v[134:135]
	v_cvt_pk_bf16_f32 v128, v112, v113
	v_cvt_pk_bf16_f32 v129, v114, v115
	ds_write_b64 v140, v[128:129] offset:0
	v_cvt_pk_bf16_f32 v132, v116, v117
	v_cvt_pk_bf16_f32 v133, v118, v119
	ds_write_b64 v140, v[132:133] offset:16
	v_pk_mul_f32 v[128:129], v[120:121], v[136:137]
	v_pk_mul_f32 v[130:131], v[122:123], v[136:137]
	v_pk_mul_f32 v[132:133], v[124:125], v[136:137]
	v_pk_mul_f32 v[134:135], v[126:127], v[136:137]
	v_exp_f32_e32 v128, v128
	v_exp_f32_e32 v129, v129
	v_exp_f32_e32 v130, v130
	v_exp_f32_e32 v131, v131
	v_exp_f32_e32 v132, v132
	v_exp_f32_e32 v133, v133
	v_exp_f32_e32 v134, v134
	v_exp_f32_e32 v135, v135
	s_nop 0
	v_pk_add_f32 v[128:129], v[128:129], 1.0 op_sel_hi:[1,0]
	v_pk_add_f32 v[130:131], v[130:131], 1.0 op_sel_hi:[1,0]
	v_pk_add_f32 v[132:133], v[132:133], 1.0 op_sel_hi:[1,0]
	v_pk_add_f32 v[134:135], v[134:135], 1.0 op_sel_hi:[1,0]
	v_rcp_f32_e32 v128, v128
	v_rcp_f32_e32 v129, v129
	v_rcp_f32_e32 v130, v130
	v_rcp_f32_e32 v131, v131
	v_rcp_f32_e32 v132, v132
	v_rcp_f32_e32 v133, v133
	v_rcp_f32_e32 v134, v134
	v_rcp_f32_e32 v135, v135
	s_nop 0
	v_pk_mul_f32 v[120:121], v[120:121], v[128:129]
	v_pk_mul_f32 v[122:123], v[122:123], v[130:131]
	v_pk_mul_f32 v[124:125], v[124:125], v[132:133]
	v_pk_mul_f32 v[126:127], v[126:127], v[134:135]
	v_cvt_pk_bf16_f32 v128, v120, v121
	v_cvt_pk_bf16_f32 v129, v122, v123
	ds_write_b64 v140, v[128:129] offset:32
	v_cvt_pk_bf16_f32 v132, v124, v125
	v_cvt_pk_bf16_f32 v133, v126, v127
	ds_write_b64 v140, v[132:133] offset:48
	v_pk_mul_f32 v[128:129], v[96:97], v[136:137]
	v_pk_mul_f32 v[130:131], v[98:99], v[136:137]
	v_pk_mul_f32 v[132:133], v[100:101], v[136:137]
	v_pk_mul_f32 v[134:135], v[102:103], v[136:137]
	v_exp_f32_e32 v128, v128
	v_exp_f32_e32 v129, v129
	v_exp_f32_e32 v130, v130
	v_exp_f32_e32 v131, v131
	v_exp_f32_e32 v132, v132
	v_exp_f32_e32 v133, v133
	v_exp_f32_e32 v134, v134
	v_exp_f32_e32 v135, v135
	s_nop 0
	v_pk_add_f32 v[128:129], v[128:129], 1.0 op_sel_hi:[1,0]
	v_pk_add_f32 v[130:131], v[130:131], 1.0 op_sel_hi:[1,0]
	v_pk_add_f32 v[132:133], v[132:133], 1.0 op_sel_hi:[1,0]
	v_pk_add_f32 v[134:135], v[134:135], 1.0 op_sel_hi:[1,0]
	v_rcp_f32_e32 v128, v128
	v_rcp_f32_e32 v129, v129
	v_rcp_f32_e32 v130, v130
	v_rcp_f32_e32 v131, v131
	v_rcp_f32_e32 v132, v132
	v_rcp_f32_e32 v133, v133
	v_rcp_f32_e32 v134, v134
	v_rcp_f32_e32 v135, v135
	s_nop 0
	v_pk_mul_f32 v[96:97], v[96:97], v[128:129]
	v_pk_mul_f32 v[98:99], v[98:99], v[130:131]
	v_pk_mul_f32 v[100:101], v[100:101], v[132:133]
	v_pk_mul_f32 v[102:103], v[102:103], v[134:135]
	v_cvt_pk_bf16_f32 v128, v96, v97
	v_cvt_pk_bf16_f32 v129, v98, v99
	ds_write_b64 v140, v[128:129] offset:64
	v_cvt_pk_bf16_f32 v132, v100, v101
	v_cvt_pk_bf16_f32 v133, v102, v103
	ds_write_b64 v140, v[132:133] offset:80
	v_pk_mul_f32 v[128:129], v[104:105], v[136:137]
	v_pk_mul_f32 v[130:131], v[106:107], v[136:137]
	v_pk_mul_f32 v[132:133], v[108:109], v[136:137]
	v_pk_mul_f32 v[134:135], v[110:111], v[136:137]
	v_exp_f32_e32 v128, v128
	v_exp_f32_e32 v129, v129
	v_exp_f32_e32 v130, v130
	v_exp_f32_e32 v131, v131
	v_exp_f32_e32 v132, v132
	v_exp_f32_e32 v133, v133
	v_exp_f32_e32 v134, v134
	v_exp_f32_e32 v135, v135
	s_nop 0
	v_pk_add_f32 v[128:129], v[128:129], 1.0 op_sel_hi:[1,0]
	v_pk_add_f32 v[130:131], v[130:131], 1.0 op_sel_hi:[1,0]
	v_pk_add_f32 v[132:133], v[132:133], 1.0 op_sel_hi:[1,0]
	v_pk_add_f32 v[134:135], v[134:135], 1.0 op_sel_hi:[1,0]
	v_rcp_f32_e32 v128, v128
	v_rcp_f32_e32 v129, v129
	v_rcp_f32_e32 v130, v130
	v_rcp_f32_e32 v131, v131
	v_rcp_f32_e32 v132, v132
	v_rcp_f32_e32 v133, v133
	v_rcp_f32_e32 v134, v134
	v_rcp_f32_e32 v135, v135
	s_nop 0
	v_pk_mul_f32 v[104:105], v[104:105], v[128:129]
	v_pk_mul_f32 v[106:107], v[106:107], v[130:131]
	v_pk_mul_f32 v[108:109], v[108:109], v[132:133]
	v_pk_mul_f32 v[110:111], v[110:111], v[134:135]
	v_cvt_pk_bf16_f32 v128, v104, v105
	v_cvt_pk_bf16_f32 v129, v106, v107
	ds_write_b64 v140, v[128:129] offset:96
	v_cvt_pk_bf16_f32 v132, v108, v109
	v_cvt_pk_bf16_f32 v133, v110, v111
	ds_write_b64 v140, v[132:133] offset:112
	v_pk_mul_f32 v[128:129], v[80:81], v[136:137]
	v_pk_mul_f32 v[130:131], v[82:83], v[136:137]
	v_pk_mul_f32 v[132:133], v[84:85], v[136:137]
	v_pk_mul_f32 v[134:135], v[86:87], v[136:137]
	v_exp_f32_e32 v128, v128
	v_exp_f32_e32 v129, v129
	v_exp_f32_e32 v130, v130
	v_exp_f32_e32 v131, v131
	v_exp_f32_e32 v132, v132
	v_exp_f32_e32 v133, v133
	v_exp_f32_e32 v134, v134
	v_exp_f32_e32 v135, v135
	s_nop 0
	v_pk_add_f32 v[128:129], v[128:129], 1.0 op_sel_hi:[1,0]
	v_pk_add_f32 v[130:131], v[130:131], 1.0 op_sel_hi:[1,0]
	v_pk_add_f32 v[132:133], v[132:133], 1.0 op_sel_hi:[1,0]
	v_pk_add_f32 v[134:135], v[134:135], 1.0 op_sel_hi:[1,0]
	v_rcp_f32_e32 v128, v128
	v_rcp_f32_e32 v129, v129
	v_rcp_f32_e32 v130, v130
	v_rcp_f32_e32 v131, v131
	v_rcp_f32_e32 v132, v132
	v_rcp_f32_e32 v133, v133
	v_rcp_f32_e32 v134, v134
	v_rcp_f32_e32 v135, v135
	s_nop 0
	v_pk_mul_f32 v[80:81], v[80:81], v[128:129]
	v_pk_mul_f32 v[82:83], v[82:83], v[130:131]
	v_pk_mul_f32 v[84:85], v[84:85], v[132:133]
	v_pk_mul_f32 v[86:87], v[86:87], v[134:135]
	v_cvt_pk_bf16_f32 v128, v80, v81
	v_cvt_pk_bf16_f32 v129, v82, v83
	ds_write_b64 v140, v[128:129] offset:128
	v_cvt_pk_bf16_f32 v132, v84, v85
	v_cvt_pk_bf16_f32 v133, v86, v87
	ds_write_b64 v140, v[132:133] offset:144
	v_pk_mul_f32 v[128:129], v[88:89], v[136:137]
	v_pk_mul_f32 v[130:131], v[90:91], v[136:137]
	v_pk_mul_f32 v[132:133], v[92:93], v[136:137]
	v_pk_mul_f32 v[134:135], v[94:95], v[136:137]
	v_exp_f32_e32 v128, v128
	v_exp_f32_e32 v129, v129
	v_exp_f32_e32 v130, v130
	v_exp_f32_e32 v131, v131
	v_exp_f32_e32 v132, v132
	v_exp_f32_e32 v133, v133
	v_exp_f32_e32 v134, v134
	v_exp_f32_e32 v135, v135
	s_nop 0
	v_pk_add_f32 v[128:129], v[128:129], 1.0 op_sel_hi:[1,0]
	v_pk_add_f32 v[130:131], v[130:131], 1.0 op_sel_hi:[1,0]
	v_pk_add_f32 v[132:133], v[132:133], 1.0 op_sel_hi:[1,0]
	v_pk_add_f32 v[134:135], v[134:135], 1.0 op_sel_hi:[1,0]
	v_rcp_f32_e32 v128, v128
	v_rcp_f32_e32 v129, v129
	v_rcp_f32_e32 v130, v130
	v_rcp_f32_e32 v131, v131
	v_rcp_f32_e32 v132, v132
	v_rcp_f32_e32 v133, v133
	v_rcp_f32_e32 v134, v134
	v_rcp_f32_e32 v135, v135
	s_nop 0
	v_pk_mul_f32 v[88:89], v[88:89], v[128:129]
	v_pk_mul_f32 v[90:91], v[90:91], v[130:131]
	v_pk_mul_f32 v[92:93], v[92:93], v[132:133]
	v_pk_mul_f32 v[94:95], v[94:95], v[134:135]
	v_cvt_pk_bf16_f32 v128, v88, v89
	v_cvt_pk_bf16_f32 v129, v90, v91
	ds_write_b64 v140, v[128:129] offset:160
	v_cvt_pk_bf16_f32 v132, v92, v93
	v_cvt_pk_bf16_f32 v133, v94, v95
	ds_write_b64 v140, v[132:133] offset:176
	v_pk_mul_f32 v[128:129], v[64:65], v[136:137]
	v_pk_mul_f32 v[130:131], v[66:67], v[136:137]
	v_pk_mul_f32 v[132:133], v[68:69], v[136:137]
	v_pk_mul_f32 v[134:135], v[70:71], v[136:137]
	v_exp_f32_e32 v128, v128
	v_exp_f32_e32 v129, v129
	v_exp_f32_e32 v130, v130
	v_exp_f32_e32 v131, v131
	v_exp_f32_e32 v132, v132
	v_exp_f32_e32 v133, v133
	v_exp_f32_e32 v134, v134
	v_exp_f32_e32 v135, v135
	s_nop 0
	v_pk_add_f32 v[128:129], v[128:129], 1.0 op_sel_hi:[1,0]
	v_pk_add_f32 v[130:131], v[130:131], 1.0 op_sel_hi:[1,0]
	v_pk_add_f32 v[132:133], v[132:133], 1.0 op_sel_hi:[1,0]
	v_pk_add_f32 v[134:135], v[134:135], 1.0 op_sel_hi:[1,0]
	v_rcp_f32_e32 v128, v128
	v_rcp_f32_e32 v129, v129
	v_rcp_f32_e32 v130, v130
	v_rcp_f32_e32 v131, v131
	v_rcp_f32_e32 v132, v132
	v_rcp_f32_e32 v133, v133
	v_rcp_f32_e32 v134, v134
	v_rcp_f32_e32 v135, v135
	s_nop 0
	v_pk_mul_f32 v[64:65], v[64:65], v[128:129]
	v_pk_mul_f32 v[66:67], v[66:67], v[130:131]
	v_pk_mul_f32 v[68:69], v[68:69], v[132:133]
	v_pk_mul_f32 v[70:71], v[70:71], v[134:135]
	v_cvt_pk_bf16_f32 v128, v64, v65
	v_cvt_pk_bf16_f32 v129, v66, v67
	ds_write_b64 v140, v[128:129] offset:192
	v_cvt_pk_bf16_f32 v132, v68, v69
	v_cvt_pk_bf16_f32 v133, v70, v71
	ds_write_b64 v140, v[132:133] offset:208
	v_pk_mul_f32 v[128:129], v[72:73], v[136:137]
	v_pk_mul_f32 v[130:131], v[74:75], v[136:137]
	v_pk_mul_f32 v[132:133], v[76:77], v[136:137]
	v_pk_mul_f32 v[134:135], v[78:79], v[136:137]
	v_exp_f32_e32 v128, v128
	v_exp_f32_e32 v129, v129
	v_exp_f32_e32 v130, v130
	v_exp_f32_e32 v131, v131
	v_exp_f32_e32 v132, v132
	v_exp_f32_e32 v133, v133
	v_exp_f32_e32 v134, v134
	v_exp_f32_e32 v135, v135
	s_nop 0
	v_pk_add_f32 v[128:129], v[128:129], 1.0 op_sel_hi:[1,0]
	v_pk_add_f32 v[130:131], v[130:131], 1.0 op_sel_hi:[1,0]
	v_pk_add_f32 v[132:133], v[132:133], 1.0 op_sel_hi:[1,0]
	v_pk_add_f32 v[134:135], v[134:135], 1.0 op_sel_hi:[1,0]
	v_rcp_f32_e32 v128, v128
	v_rcp_f32_e32 v129, v129
	v_rcp_f32_e32 v130, v130
	v_rcp_f32_e32 v131, v131
	v_rcp_f32_e32 v132, v132
	v_rcp_f32_e32 v133, v133
	v_rcp_f32_e32 v134, v134
	v_rcp_f32_e32 v135, v135
	s_nop 0
	v_pk_mul_f32 v[72:73], v[72:73], v[128:129]
	v_pk_mul_f32 v[74:75], v[74:75], v[130:131]
	v_pk_mul_f32 v[76:77], v[76:77], v[132:133]
	v_pk_mul_f32 v[78:79], v[78:79], v[134:135]
	v_cvt_pk_bf16_f32 v128, v72, v73
	v_cvt_pk_bf16_f32 v129, v74, v75
	ds_write_b64 v140, v[128:129] offset:224
	v_cvt_pk_bf16_f32 v132, v76, v77
	v_cvt_pk_bf16_f32 v133, v78, v79
	ds_write_b64 v140, v[132:133] offset:240
	v_pk_mul_f32 v[128:129], v[48:49], v[136:137]
	v_pk_mul_f32 v[130:131], v[50:51], v[136:137]
	v_pk_mul_f32 v[132:133], v[52:53], v[136:137]
	v_pk_mul_f32 v[134:135], v[54:55], v[136:137]
	v_exp_f32_e32 v128, v128
	v_exp_f32_e32 v129, v129
	v_exp_f32_e32 v130, v130
	v_exp_f32_e32 v131, v131
	v_exp_f32_e32 v132, v132
	v_exp_f32_e32 v133, v133
	v_exp_f32_e32 v134, v134
	v_exp_f32_e32 v135, v135
	s_nop 0
	v_pk_add_f32 v[128:129], v[128:129], 1.0 op_sel_hi:[1,0]
	v_pk_add_f32 v[130:131], v[130:131], 1.0 op_sel_hi:[1,0]
	v_pk_add_f32 v[132:133], v[132:133], 1.0 op_sel_hi:[1,0]
	v_pk_add_f32 v[134:135], v[134:135], 1.0 op_sel_hi:[1,0]
	v_rcp_f32_e32 v128, v128
	v_rcp_f32_e32 v129, v129
	v_rcp_f32_e32 v130, v130
	v_rcp_f32_e32 v131, v131
	v_rcp_f32_e32 v132, v132
	v_rcp_f32_e32 v133, v133
	v_rcp_f32_e32 v134, v134
	v_rcp_f32_e32 v135, v135
	s_nop 0
	v_pk_mul_f32 v[48:49], v[48:49], v[128:129]
	v_pk_mul_f32 v[50:51], v[50:51], v[130:131]
	v_pk_mul_f32 v[52:53], v[52:53], v[132:133]
	v_pk_mul_f32 v[54:55], v[54:55], v[134:135]
	v_cvt_pk_bf16_f32 v128, v48, v49
	v_cvt_pk_bf16_f32 v129, v50, v51
	ds_write_b64 v140, v[128:129] offset:16896
	v_cvt_pk_bf16_f32 v132, v52, v53
	v_cvt_pk_bf16_f32 v133, v54, v55
	ds_write_b64 v140, v[132:133] offset:16912
	v_pk_mul_f32 v[128:129], v[56:57], v[136:137]
	v_pk_mul_f32 v[130:131], v[58:59], v[136:137]
	v_pk_mul_f32 v[132:133], v[60:61], v[136:137]
	v_pk_mul_f32 v[134:135], v[62:63], v[136:137]
	v_exp_f32_e32 v128, v128
	v_exp_f32_e32 v129, v129
	v_exp_f32_e32 v130, v130
	v_exp_f32_e32 v131, v131
	v_exp_f32_e32 v132, v132
	v_exp_f32_e32 v133, v133
	v_exp_f32_e32 v134, v134
	v_exp_f32_e32 v135, v135
	s_nop 0
	v_pk_add_f32 v[128:129], v[128:129], 1.0 op_sel_hi:[1,0]
	v_pk_add_f32 v[130:131], v[130:131], 1.0 op_sel_hi:[1,0]
	v_pk_add_f32 v[132:133], v[132:133], 1.0 op_sel_hi:[1,0]
	v_pk_add_f32 v[134:135], v[134:135], 1.0 op_sel_hi:[1,0]
	v_rcp_f32_e32 v128, v128
	v_rcp_f32_e32 v129, v129
	v_rcp_f32_e32 v130, v130
	v_rcp_f32_e32 v131, v131
	v_rcp_f32_e32 v132, v132
	v_rcp_f32_e32 v133, v133
	v_rcp_f32_e32 v134, v134
	v_rcp_f32_e32 v135, v135
	s_nop 0
	v_pk_mul_f32 v[56:57], v[56:57], v[128:129]
	v_pk_mul_f32 v[58:59], v[58:59], v[130:131]
	v_pk_mul_f32 v[60:61], v[60:61], v[132:133]
	v_pk_mul_f32 v[62:63], v[62:63], v[134:135]
	v_cvt_pk_bf16_f32 v128, v56, v57
	v_cvt_pk_bf16_f32 v129, v58, v59
	ds_write_b64 v140, v[128:129] offset:16928
	v_cvt_pk_bf16_f32 v132, v60, v61
	v_cvt_pk_bf16_f32 v133, v62, v63
	ds_write_b64 v140, v[132:133] offset:16944
	v_pk_mul_f32 v[128:129], v[32:33], v[136:137]
	v_pk_mul_f32 v[130:131], v[34:35], v[136:137]
	v_pk_mul_f32 v[132:133], v[36:37], v[136:137]
	v_pk_mul_f32 v[134:135], v[38:39], v[136:137]
	v_exp_f32_e32 v128, v128
	v_exp_f32_e32 v129, v129
	v_exp_f32_e32 v130, v130
	v_exp_f32_e32 v131, v131
	v_exp_f32_e32 v132, v132
	v_exp_f32_e32 v133, v133
	v_exp_f32_e32 v134, v134
	v_exp_f32_e32 v135, v135
	s_nop 0
	v_pk_add_f32 v[128:129], v[128:129], 1.0 op_sel_hi:[1,0]
	v_pk_add_f32 v[130:131], v[130:131], 1.0 op_sel_hi:[1,0]
	v_pk_add_f32 v[132:133], v[132:133], 1.0 op_sel_hi:[1,0]
	v_pk_add_f32 v[134:135], v[134:135], 1.0 op_sel_hi:[1,0]
	v_rcp_f32_e32 v128, v128
	v_rcp_f32_e32 v129, v129
	v_rcp_f32_e32 v130, v130
	v_rcp_f32_e32 v131, v131
	v_rcp_f32_e32 v132, v132
	v_rcp_f32_e32 v133, v133
	v_rcp_f32_e32 v134, v134
	v_rcp_f32_e32 v135, v135
	s_nop 0
	v_pk_mul_f32 v[32:33], v[32:33], v[128:129]
	v_pk_mul_f32 v[34:35], v[34:35], v[130:131]
	v_pk_mul_f32 v[36:37], v[36:37], v[132:133]
	v_pk_mul_f32 v[38:39], v[38:39], v[134:135]
	v_cvt_pk_bf16_f32 v128, v32, v33
	v_cvt_pk_bf16_f32 v129, v34, v35
	ds_write_b64 v140, v[128:129] offset:16960
	v_cvt_pk_bf16_f32 v132, v36, v37
	v_cvt_pk_bf16_f32 v133, v38, v39
	ds_write_b64 v140, v[132:133] offset:16976
	v_pk_mul_f32 v[128:129], v[40:41], v[136:137]
	v_pk_mul_f32 v[130:131], v[42:43], v[136:137]
	v_pk_mul_f32 v[132:133], v[44:45], v[136:137]
	v_pk_mul_f32 v[134:135], v[46:47], v[136:137]
	v_exp_f32_e32 v128, v128
	v_exp_f32_e32 v129, v129
	v_exp_f32_e32 v130, v130
	v_exp_f32_e32 v131, v131
	v_exp_f32_e32 v132, v132
	v_exp_f32_e32 v133, v133
	v_exp_f32_e32 v134, v134
	v_exp_f32_e32 v135, v135
	s_nop 0
	v_pk_add_f32 v[128:129], v[128:129], 1.0 op_sel_hi:[1,0]
	v_pk_add_f32 v[130:131], v[130:131], 1.0 op_sel_hi:[1,0]
	v_pk_add_f32 v[132:133], v[132:133], 1.0 op_sel_hi:[1,0]
	v_pk_add_f32 v[134:135], v[134:135], 1.0 op_sel_hi:[1,0]
	v_rcp_f32_e32 v128, v128
	v_rcp_f32_e32 v129, v129
	v_rcp_f32_e32 v130, v130
	v_rcp_f32_e32 v131, v131
	v_rcp_f32_e32 v132, v132
	v_rcp_f32_e32 v133, v133
	v_rcp_f32_e32 v134, v134
	v_rcp_f32_e32 v135, v135
	s_nop 0
	v_pk_mul_f32 v[40:41], v[40:41], v[128:129]
	v_pk_mul_f32 v[42:43], v[42:43], v[130:131]
	v_pk_mul_f32 v[44:45], v[44:45], v[132:133]
	v_pk_mul_f32 v[46:47], v[46:47], v[134:135]
	v_cvt_pk_bf16_f32 v128, v40, v41
	v_cvt_pk_bf16_f32 v129, v42, v43
	ds_write_b64 v140, v[128:129] offset:16992
	v_cvt_pk_bf16_f32 v132, v44, v45
	v_cvt_pk_bf16_f32 v133, v46, v47
	ds_write_b64 v140, v[132:133] offset:17008
	v_pk_mul_f32 v[128:129], v[16:17], v[136:137]
	v_pk_mul_f32 v[130:131], v[18:19], v[136:137]
	v_pk_mul_f32 v[132:133], v[20:21], v[136:137]
	v_pk_mul_f32 v[134:135], v[22:23], v[136:137]
	v_exp_f32_e32 v128, v128
	v_exp_f32_e32 v129, v129
	v_exp_f32_e32 v130, v130
	v_exp_f32_e32 v131, v131
	v_exp_f32_e32 v132, v132
	v_exp_f32_e32 v133, v133
	v_exp_f32_e32 v134, v134
	v_exp_f32_e32 v135, v135
	s_nop 0
	v_pk_add_f32 v[128:129], v[128:129], 1.0 op_sel_hi:[1,0]
	v_pk_add_f32 v[130:131], v[130:131], 1.0 op_sel_hi:[1,0]
	v_pk_add_f32 v[132:133], v[132:133], 1.0 op_sel_hi:[1,0]
	v_pk_add_f32 v[134:135], v[134:135], 1.0 op_sel_hi:[1,0]
	v_rcp_f32_e32 v128, v128
	v_rcp_f32_e32 v129, v129
	v_rcp_f32_e32 v130, v130
	v_rcp_f32_e32 v131, v131
	v_rcp_f32_e32 v132, v132
	v_rcp_f32_e32 v133, v133
	v_rcp_f32_e32 v134, v134
	v_rcp_f32_e32 v135, v135
	s_nop 0
	v_pk_mul_f32 v[16:17], v[16:17], v[128:129]
	v_pk_mul_f32 v[18:19], v[18:19], v[130:131]
	v_pk_mul_f32 v[20:21], v[20:21], v[132:133]
	v_pk_mul_f32 v[22:23], v[22:23], v[134:135]
	v_cvt_pk_bf16_f32 v128, v16, v17
	v_cvt_pk_bf16_f32 v129, v18, v19
	ds_write_b64 v140, v[128:129] offset:17024
	v_cvt_pk_bf16_f32 v132, v20, v21
	v_cvt_pk_bf16_f32 v133, v22, v23
	ds_write_b64 v140, v[132:133] offset:17040
	v_pk_mul_f32 v[128:129], v[24:25], v[136:137]
	v_pk_mul_f32 v[130:131], v[26:27], v[136:137]
	v_pk_mul_f32 v[132:133], v[28:29], v[136:137]
	v_pk_mul_f32 v[134:135], v[30:31], v[136:137]
	v_exp_f32_e32 v128, v128
	v_exp_f32_e32 v129, v129
	v_exp_f32_e32 v130, v130
	v_exp_f32_e32 v131, v131
	v_exp_f32_e32 v132, v132
	v_exp_f32_e32 v133, v133
	v_exp_f32_e32 v134, v134
	v_exp_f32_e32 v135, v135
	s_nop 0
	v_pk_add_f32 v[128:129], v[128:129], 1.0 op_sel_hi:[1,0]
	v_pk_add_f32 v[130:131], v[130:131], 1.0 op_sel_hi:[1,0]
	v_pk_add_f32 v[132:133], v[132:133], 1.0 op_sel_hi:[1,0]
	v_pk_add_f32 v[134:135], v[134:135], 1.0 op_sel_hi:[1,0]
	v_rcp_f32_e32 v128, v128
	v_rcp_f32_e32 v129, v129
	v_rcp_f32_e32 v130, v130
	v_rcp_f32_e32 v131, v131
	v_rcp_f32_e32 v132, v132
	v_rcp_f32_e32 v133, v133
	v_rcp_f32_e32 v134, v134
	v_rcp_f32_e32 v135, v135
	s_nop 0
	v_pk_mul_f32 v[24:25], v[24:25], v[128:129]
	v_pk_mul_f32 v[26:27], v[26:27], v[130:131]
	v_pk_mul_f32 v[28:29], v[28:29], v[132:133]
	v_pk_mul_f32 v[30:31], v[30:31], v[134:135]
	v_cvt_pk_bf16_f32 v128, v24, v25
	v_cvt_pk_bf16_f32 v129, v26, v27
	ds_write_b64 v140, v[128:129] offset:17056
	v_cvt_pk_bf16_f32 v132, v28, v29
	v_cvt_pk_bf16_f32 v133, v30, v31
	ds_write_b64 v140, v[132:133] offset:17072
	v_pk_mul_f32 v[128:129], v[0:1], v[136:137]
	v_pk_mul_f32 v[130:131], v[2:3], v[136:137]
	v_pk_mul_f32 v[132:133], v[4:5], v[136:137]
	v_pk_mul_f32 v[134:135], v[6:7], v[136:137]
	v_exp_f32_e32 v128, v128
	v_exp_f32_e32 v129, v129
	v_exp_f32_e32 v130, v130
	v_exp_f32_e32 v131, v131
	v_exp_f32_e32 v132, v132
	v_exp_f32_e32 v133, v133
	v_exp_f32_e32 v134, v134
	v_exp_f32_e32 v135, v135
	s_nop 0
	v_pk_add_f32 v[128:129], v[128:129], 1.0 op_sel_hi:[1,0]
	v_pk_add_f32 v[130:131], v[130:131], 1.0 op_sel_hi:[1,0]
	v_pk_add_f32 v[132:133], v[132:133], 1.0 op_sel_hi:[1,0]
	v_pk_add_f32 v[134:135], v[134:135], 1.0 op_sel_hi:[1,0]
	v_rcp_f32_e32 v128, v128
	v_rcp_f32_e32 v129, v129
	v_rcp_f32_e32 v130, v130
	v_rcp_f32_e32 v131, v131
	v_rcp_f32_e32 v132, v132
	v_rcp_f32_e32 v133, v133
	v_rcp_f32_e32 v134, v134
	v_rcp_f32_e32 v135, v135
	s_nop 0
	v_pk_mul_f32 v[0:1], v[0:1], v[128:129]
	v_pk_mul_f32 v[2:3], v[2:3], v[130:131]
	v_pk_mul_f32 v[4:5], v[4:5], v[132:133]
	v_pk_mul_f32 v[6:7], v[6:7], v[134:135]
	v_cvt_pk_bf16_f32 v128, v0, v1
	v_cvt_pk_bf16_f32 v129, v2, v3
	ds_write_b64 v140, v[128:129] offset:17088
	v_cvt_pk_bf16_f32 v132, v4, v5
	v_cvt_pk_bf16_f32 v133, v6, v7
	ds_write_b64 v140, v[132:133] offset:17104
	v_pk_mul_f32 v[128:129], v[8:9], v[136:137]
	v_pk_mul_f32 v[130:131], v[10:11], v[136:137]
	v_pk_mul_f32 v[132:133], v[12:13], v[136:137]
	v_pk_mul_f32 v[134:135], v[14:15], v[136:137]
	v_exp_f32_e32 v128, v128
	v_exp_f32_e32 v129, v129
	v_exp_f32_e32 v130, v130
	v_exp_f32_e32 v131, v131
	v_exp_f32_e32 v132, v132
	v_exp_f32_e32 v133, v133
	v_exp_f32_e32 v134, v134
	v_exp_f32_e32 v135, v135
	s_nop 0
	v_pk_add_f32 v[128:129], v[128:129], 1.0 op_sel_hi:[1,0]
	v_pk_add_f32 v[130:131], v[130:131], 1.0 op_sel_hi:[1,0]
	v_pk_add_f32 v[132:133], v[132:133], 1.0 op_sel_hi:[1,0]
	v_pk_add_f32 v[134:135], v[134:135], 1.0 op_sel_hi:[1,0]
	v_rcp_f32_e32 v128, v128
	v_rcp_f32_e32 v129, v129
	v_rcp_f32_e32 v130, v130
	v_rcp_f32_e32 v131, v131
	v_rcp_f32_e32 v132, v132
	v_rcp_f32_e32 v133, v133
	v_rcp_f32_e32 v134, v134
	v_rcp_f32_e32 v135, v135
	s_nop 0
	v_pk_mul_f32 v[8:9], v[8:9], v[128:129]
	v_pk_mul_f32 v[10:11], v[10:11], v[130:131]
	v_pk_mul_f32 v[12:13], v[12:13], v[132:133]
	v_pk_mul_f32 v[14:15], v[14:15], v[134:135]
	v_cvt_pk_bf16_f32 v128, v8, v9
	v_cvt_pk_bf16_f32 v129, v10, v11
	ds_write_b64 v140, v[128:129] offset:17120
	v_cvt_pk_bf16_f32 v132, v12, v13
	v_cvt_pk_bf16_f32 v133, v14, v15
	ds_write_b64 v140, v[132:133] offset:17136
	s_waitcnt lgkmcnt(0)
	s_barrier
	ds_read_b128 v[148:151], v141 offset:0
	ds_read_b128 v[152:155], v141 offset:8448
	ds_read_b128 v[156:159], v141 offset:16896
	ds_read_b128 v[160:163], v141 offset:25344
	ds_read_b128 v[164:167], v141 offset:33792
	ds_read_b128 v[172:175], v141 offset:42240
	ds_read_b128 v[176:179], v141 offset:50688
	ds_read_b128 v[180:183], v141 offset:59136
	ds_read_b128 v[184:187], v142 offset:0
	ds_read_b128 v[188:191], v142 offset:8448
	ds_read_b128 v[192:195], v142 offset:16896
	ds_read_b128 v[196:199], v142 offset:25344
	ds_read_b128 v[200:203], v142 offset:33792
	ds_read_b128 v[212:215], v142 offset:42240
	ds_read_b128 v[216:219], v142 offset:50688
	ds_read_b128 v[220:223], v142 offset:59136
	s_waitcnt lgkmcnt(15)
	global_store_dwordx4 v143, v[148:151], s[56:57]
	s_add_u32 s56, s56, 0x10000
	s_addc_u32 s57, s57, 0
	s_waitcnt lgkmcnt(14)
	global_store_dwordx4 v143, v[152:155], s[56:57]
	s_add_u32 s56, s56, 0x10000
	s_addc_u32 s57, s57, 0
	s_waitcnt lgkmcnt(13)
	global_store_dwordx4 v143, v[156:159], s[56:57]
	s_add_u32 s56, s56, 0x10000
	s_addc_u32 s57, s57, 0
	s_waitcnt lgkmcnt(12)
	global_store_dwordx4 v143, v[160:163], s[56:57]
	s_add_u32 s56, s56, 0x10000
	s_addc_u32 s57, s57, 0
	s_waitcnt lgkmcnt(11)
	global_store_dwordx4 v143, v[164:167], s[56:57]
	s_add_u32 s56, s56, 0x10000
	s_addc_u32 s57, s57, 0
	s_waitcnt lgkmcnt(10)
	global_store_dwordx4 v143, v[172:175], s[56:57]
	s_add_u32 s56, s56, 0x10000
	s_addc_u32 s57, s57, 0
	s_waitcnt lgkmcnt(9)
	global_store_dwordx4 v143, v[176:179], s[56:57]
	s_add_u32 s56, s56, 0x10000
	s_addc_u32 s57, s57, 0
	s_waitcnt lgkmcnt(8)
	global_store_dwordx4 v143, v[180:183], s[56:57]
	s_add_u32 s56, s56, 0x10000
	s_addc_u32 s57, s57, 0
	s_waitcnt lgkmcnt(7)
	global_store_dwordx4 v143, v[184:187], s[56:57]
	s_add_u32 s56, s56, 0x10000
	s_addc_u32 s57, s57, 0
	s_waitcnt lgkmcnt(6)
	global_store_dwordx4 v143, v[188:191], s[56:57]
	s_add_u32 s56, s56, 0x10000
	s_addc_u32 s57, s57, 0
	s_waitcnt lgkmcnt(5)
	global_store_dwordx4 v143, v[192:195], s[56:57]
	s_add_u32 s56, s56, 0x10000
	s_addc_u32 s57, s57, 0
	s_waitcnt lgkmcnt(4)
	global_store_dwordx4 v143, v[196:199], s[56:57]
	s_add_u32 s56, s56, 0x10000
	s_addc_u32 s57, s57, 0
	s_waitcnt lgkmcnt(3)
	global_store_dwordx4 v143, v[200:203], s[56:57]
	s_add_u32 s56, s56, 0x10000
	s_addc_u32 s57, s57, 0
	s_waitcnt lgkmcnt(2)
	global_store_dwordx4 v143, v[212:215], s[56:57]
	s_add_u32 s56, s56, 0x10000
	s_addc_u32 s57, s57, 0
	s_waitcnt lgkmcnt(1)
	global_store_dwordx4 v143, v[216:219], s[56:57]
	s_add_u32 s56, s56, 0x10000
	s_addc_u32 s57, s57, 0
	s_waitcnt lgkmcnt(0)
	global_store_dwordx4 v143, v[220:223], s[56:57]
	s_barrier
	s_mov_b64 s[2:3], 0

.LBB0_831:
	s_mov_b32 s44, s75
	s_cmp_lt_i32 s44, 2
	s_cselect_b32 s2, s89, s25
	s_cselect_b32 s3, s88, s24
	s_lshl_b32 s27, s27, 10
	s_lshl_b32 s26, s26, 9
	s_bfe_u32 s18, s56, 0x10008
	s_or_b32 s26, s27, s26
	s_or_b32 s18, s26, s18
	s_lshl_b32 s18, s18, 12
	s_add_u32 s3, s3, s18
	s_addc_u32 s18, s2, 0
	s_lshl_b32 s2, s45, 1
	v_cvt_pk_bf16_f32 v2, v2, v3
	v_cvt_pk_bf16_f32 v3, v0, v1
	v_mov_b32_e32 v14, v208
	s_add_u32 s2, s3, s2
	ds_write_b64 v70, v[2:3] offset:16896
	s_addc_u32 s3, s18, 0
	v_lshlrev_b32_e32 v0, 4, v14
	v_ashrrev_i32_e32 v4, 5, v14
	v_and_b32_e32 v168, 0x1f0, v0
	v_ashrrev_i32_e32 v5, 31, v4
	v_lshl_add_u64 v[8:9], s[2:3], 0, v[168:169]
	v_mad_u64_u32 v[0:1], s[2:3], v4, s55, v[168:169]
	v_lshlrev_b64 v[4:5], 13, v[4:5]
	v_lshl_add_u64 v[10:11], v[8:9], 0, v[4:5]
	v_add_u32_e32 v4, 0x200, v14
	s_waitcnt lgkmcnt(0)
	s_barrier
	ds_read_b128 v[0:3], v0
	v_ashrrev_i32_e32 v12, 5, v4
	v_mad_u64_u32 v[4:5], s[2:3], v12, s55, v[168:169]
	ds_read_b128 v[4:7], v4
	v_ashrrev_i32_e32 v13, 31, v12
	s_waitcnt lgkmcnt(1)
	global_store_dwordx4 v[10:11], v[0:3], off
	s_nop 1
	v_lshlrev_b64 v[0:1], 13, v[12:13]
	v_lshl_add_u64 v[0:1], v[8:9], 0, v[0:1]
	s_waitcnt lgkmcnt(0)
	global_store_dwordx4 v[0:1], v[4:7], off
	v_add_u32_e32 v0, 0x400, v14
	s_nop 0
	v_ashrrev_i32_e32 v4, 5, v0
	v_ashrrev_i32_e32 v5, 31, v4
	v_mad_u64_u32 v[0:1], s[2:3], v4, s55, v[168:169]
	v_lshlrev_b64 v[4:5], 13, v[4:5]
	v_lshl_add_u64 v[10:11], v[8:9], 0, v[4:5]
	v_add_u32_e32 v4, 0x600, v14
	ds_read_b128 v[0:3], v0
	v_ashrrev_i32_e32 v12, 5, v4
	v_mad_u64_u32 v[4:5], s[2:3], v12, s55, v[168:169]
	ds_read_b128 v[4:7], v4
	v_ashrrev_i32_e32 v13, 31, v12
	s_waitcnt lgkmcnt(1)
	global_store_dwordx4 v[10:11], v[0:3], off
	s_nop 1
	v_lshlrev_b64 v[0:1], 13, v[12:13]
	v_lshl_add_u64 v[0:1], v[8:9], 0, v[0:1]
	s_waitcnt lgkmcnt(0)
	global_store_dwordx4 v[0:1], v[4:7], off
	v_add_u32_e32 v0, 0x800, v14
	s_nop 0
	v_ashrrev_i32_e32 v4, 5, v0
	v_ashrrev_i32_e32 v5, 31, v4
	v_mad_u64_u32 v[0:1], s[2:3], v4, s55, v[168:169]
	v_lshlrev_b64 v[4:5], 13, v[4:5]
	v_lshl_add_u64 v[10:11], v[8:9], 0, v[4:5]
	v_add_u32_e32 v4, 0xa00, v14
	ds_read_b128 v[0:3], v0
	v_ashrrev_i32_e32 v12, 5, v4
	v_mad_u64_u32 v[4:5], s[2:3], v12, s55, v[168:169]
	ds_read_b128 v[4:7], v4
	v_ashrrev_i32_e32 v13, 31, v12
	s_waitcnt lgkmcnt(1)
	global_store_dwordx4 v[10:11], v[0:3], off
	s_nop 1
	v_lshlrev_b64 v[0:1], 13, v[12:13]
	v_lshl_add_u64 v[0:1], v[8:9], 0, v[0:1]
	s_waitcnt lgkmcnt(0)
	global_store_dwordx4 v[0:1], v[4:7], off
	v_add_u32_e32 v0, 0xc00, v14
	s_nop 0
	v_ashrrev_i32_e32 v4, 5, v0
	v_ashrrev_i32_e32 v5, 31, v4
	v_mad_u64_u32 v[0:1], s[2:3], v4, s55, v[168:169]
	v_lshlrev_b64 v[4:5], 13, v[4:5]
	v_lshl_add_u64 v[10:11], v[8:9], 0, v[4:5]
	v_add_u32_e32 v4, 0xe00, v14
	ds_read_b128 v[0:3], v0
	v_ashrrev_i32_e32 v12, 5, v4
	v_mad_u64_u32 v[4:5], s[2:3], v12, s55, v[168:169]
	ds_read_b128 v[4:7], v4
	v_ashrrev_i32_e32 v13, 31, v12
	s_waitcnt lgkmcnt(1)
	global_store_dwordx4 v[10:11], v[0:3], off
	s_nop 1
	v_lshlrev_b64 v[0:1], 13, v[12:13]
	v_lshl_add_u64 v[0:1], v[8:9], 0, v[0:1]
	s_waitcnt lgkmcnt(0)
	global_store_dwordx4 v[0:1], v[4:7], off
	v_add_u32_e32 v0, 0x1000, v14
	s_nop 0
	v_ashrrev_i32_e32 v4, 5, v0
	v_ashrrev_i32_e32 v5, 31, v4
	v_mad_u64_u32 v[0:1], s[2:3], v4, s55, v[168:169]
	v_lshlrev_b64 v[4:5], 13, v[4:5]
	v_lshl_add_u64 v[10:11], v[8:9], 0, v[4:5]
	v_add_u32_e32 v4, 0x1200, v14
	ds_read_b128 v[0:3], v0
	v_ashrrev_i32_e32 v12, 5, v4
	v_mad_u64_u32 v[4:5], s[2:3], v12, s55, v[168:169]
	ds_read_b128 v[4:7], v4
	v_ashrrev_i32_e32 v13, 31, v12
	s_waitcnt lgkmcnt(1)
	global_store_dwordx4 v[10:11], v[0:3], off
	s_nop 1
	v_lshlrev_b64 v[0:1], 13, v[12:13]
	v_lshl_add_u64 v[0:1], v[8:9], 0, v[0:1]
	s_waitcnt lgkmcnt(0)
	global_store_dwordx4 v[0:1], v[4:7], off
	v_add_u32_e32 v0, 0x1400, v14
	s_nop 0
	v_ashrrev_i32_e32 v4, 5, v0
	v_ashrrev_i32_e32 v5, 31, v4
	v_mad_u64_u32 v[0:1], s[2:3], v4, s55, v[168:169]
	v_lshlrev_b64 v[4:5], 13, v[4:5]
	v_lshl_add_u64 v[10:11], v[8:9], 0, v[4:5]
	v_add_u32_e32 v4, 0x1600, v14
	ds_read_b128 v[0:3], v0
	v_ashrrev_i32_e32 v12, 5, v4
	v_mad_u64_u32 v[4:5], s[2:3], v12, s55, v[168:169]
	ds_read_b128 v[4:7], v4
	v_ashrrev_i32_e32 v13, 31, v12
	s_waitcnt lgkmcnt(1)
	global_store_dwordx4 v[10:11], v[0:3], off
	s_nop 1
	v_lshlrev_b64 v[0:1], 13, v[12:13]
	v_lshl_add_u64 v[0:1], v[8:9], 0, v[0:1]
	s_waitcnt lgkmcnt(0)
	global_store_dwordx4 v[0:1], v[4:7], off
	v_add_u32_e32 v0, 0x1800, v14
	s_nop 0
	v_ashrrev_i32_e32 v4, 5, v0
	v_ashrrev_i32_e32 v5, 31, v4
	v_mad_u64_u32 v[0:1], s[2:3], v4, s55, v[168:169]
	v_lshlrev_b64 v[4:5], 13, v[4:5]
	v_lshl_add_u64 v[10:11], v[8:9], 0, v[4:5]
	v_add_u32_e32 v4, 0x1a00, v14
	ds_read_b128 v[0:3], v0
	v_ashrrev_i32_e32 v12, 5, v4
	v_mad_u64_u32 v[4:5], s[2:3], v12, s55, v[168:169]
	ds_read_b128 v[4:7], v4
	v_ashrrev_i32_e32 v13, 31, v12
	s_waitcnt lgkmcnt(1)
	global_store_dwordx4 v[10:11], v[0:3], off
	s_nop 1
	v_lshlrev_b64 v[0:1], 13, v[12:13]
	v_lshl_add_u64 v[0:1], v[8:9], 0, v[0:1]
	s_waitcnt lgkmcnt(0)
	global_store_dwordx4 v[0:1], v[4:7], off
	v_add_u32_e32 v0, 0x1c00, v14
	s_nop 0
	v_ashrrev_i32_e32 v4, 5, v0
	v_ashrrev_i32_e32 v5, 31, v4
	v_mad_u64_u32 v[0:1], s[2:3], v4, s55, v[168:169]
	v_lshlrev_b64 v[4:5], 13, v[4:5]
	v_lshl_add_u64 v[10:11], v[8:9], 0, v[4:5]
	v_add_u32_e32 v4, 0x1e00, v14
	ds_read_b128 v[0:3], v0
	v_ashrrev_i32_e32 v12, 5, v4
	v_mad_u64_u32 v[4:5], s[2:3], v12, s55, v[168:169]
	ds_read_b128 v[4:7], v4
	v_ashrrev_i32_e32 v13, 31, v12
	v_readlane_b32 s2, v255, 6
	s_waitcnt lgkmcnt(1)
	global_store_dwordx4 v[10:11], v[0:3], off
	s_add_i32 s56, s56, s2
	s_cmpk_gt_i32 s56, 0x3ff
	v_lshlrev_b64 v[0:1], 13, v[12:13]
	v_lshl_add_u64 v[0:1], v[8:9], 0, v[0:1]
	s_waitcnt lgkmcnt(0)
	global_store_dwordx4 v[0:1], v[4:7], off
	s_barrier
	v_readlane_b32 s3, v255, 7
	s_cbranch_scc1 .LBB0_1257

.Lg8_p7_eg1:
	s_nop 7
	s_nop 7
	v_permlane16_swap_b32_e32 v112, v116
	v_permlane16_swap_b32_e32 v113, v117
	v_permlane16_swap_b32_e32 v114, v118
	v_permlane16_swap_b32_e32 v115, v119
	v_permlane16_swap_b32_e32 v120, v124
	v_permlane16_swap_b32_e32 v121, v125
	v_permlane16_swap_b32_e32 v122, v126
	v_permlane16_swap_b32_e32 v123, v127
	v_permlane16_swap_b32_e32 v96, v100
	v_permlane16_swap_b32_e32 v97, v101
	v_permlane16_swap_b32_e32 v98, v102
	v_permlane16_swap_b32_e32 v99, v103
	v_permlane16_swap_b32_e32 v104, v108
	v_permlane16_swap_b32_e32 v105, v109
	v_permlane16_swap_b32_e32 v106, v110
	v_permlane16_swap_b32_e32 v107, v111
	v_permlane16_swap_b32_e32 v80, v84
	v_permlane16_swap_b32_e32 v81, v85
	v_permlane16_swap_b32_e32 v82, v86
	v_permlane16_swap_b32_e32 v83, v87
	v_permlane16_swap_b32_e32 v88, v92
	v_permlane16_swap_b32_e32 v89, v93
	v_permlane16_swap_b32_e32 v90, v94
	v_permlane16_swap_b32_e32 v91, v95
	v_permlane16_swap_b32_e32 v64, v68
	v_permlane16_swap_b32_e32 v65, v69
	v_permlane16_swap_b32_e32 v66, v70
	v_permlane16_swap_b32_e32 v67, v71
	v_permlane16_swap_b32_e32 v72, v76
	v_permlane16_swap_b32_e32 v73, v77
	v_permlane16_swap_b32_e32 v74, v78
	v_permlane16_swap_b32_e32 v75, v79
	v_permlane16_swap_b32_e32 v48, v52
	v_permlane16_swap_b32_e32 v49, v53
	v_permlane16_swap_b32_e32 v50, v54
	v_permlane16_swap_b32_e32 v51, v55
	v_permlane16_swap_b32_e32 v56, v60
	v_permlane16_swap_b32_e32 v57, v61
	v_permlane16_swap_b32_e32 v58, v62
	v_permlane16_swap_b32_e32 v59, v63
	v_permlane16_swap_b32_e32 v32, v36
	v_permlane16_swap_b32_e32 v33, v37
	v_permlane16_swap_b32_e32 v34, v38
	v_permlane16_swap_b32_e32 v35, v39
	v_permlane16_swap_b32_e32 v40, v44
	v_permlane16_swap_b32_e32 v41, v45
	v_permlane16_swap_b32_e32 v42, v46
	v_permlane16_swap_b32_e32 v43, v47
	v_permlane16_swap_b32_e32 v16, v20
	v_permlane16_swap_b32_e32 v17, v21
	v_permlane16_swap_b32_e32 v18, v22
	v_permlane16_swap_b32_e32 v19, v23
	v_permlane16_swap_b32_e32 v24, v28
	v_permlane16_swap_b32_e32 v25, v29
	v_permlane16_swap_b32_e32 v26, v30
	v_permlane16_swap_b32_e32 v27, v31
	v_permlane16_swap_b32_e32 v0, v4
	v_permlane16_swap_b32_e32 v1, v5
	v_permlane16_swap_b32_e32 v2, v6
	v_permlane16_swap_b32_e32 v3, v7
	v_permlane16_swap_b32_e32 v8, v12
	v_permlane16_swap_b32_e32 v9, v13
	v_permlane16_swap_b32_e32 v10, v14
	v_permlane16_swap_b32_e32 v11, v15
	s_nop 1
	s_cmp_eq_u32 s44, 2
	s_cbranch_scc1 .Lfix7_done
	v_lshlrev_b32_e32 v168, 1, v208
	v_and_b32_e32 v168, 0x80, v168
	v_lshrrev_b32_e32 v170, 3, v208
	v_and_b32_e32 v170, 4, v170
	v_or_b32_e32 v168, v168, v170
	s_lshl_b32 s74, s27, 11
	s_or_b32 s74, s74, s45
	v_or_b32_e32 v168, s74, v168
	v_lshlrev_b32_e32 v196, 2, v168
	v_lshlrev_b32_e32 v197, 1, v168
	v_and_b32_e32 v170, 1, v208
	v_cmp_eq_u32_e32 vcc, 0, v170
	s_nop 1
	v_cndmask_b32_e64 v171, -1.0, 1.0, vcc
	s_cmp_eq_u32 s44, 0
	s_cbranch_scc1 .Lfix7_ty0
	s_cmp_eq_u32 s44, 1
	s_cbranch_scc1 .Lfix7_ty1
	global_load_dwordx4 v[128:131], v196, s[16:17] offset:0
	global_load_dwordx4 v[132:135], v196, s[16:17] offset:32
	global_load_dwordx4 v[136:139], v196, s[16:17] offset:64
	global_load_dwordx4 v[140:143], v196, s[16:17] offset:96
	global_load_dwordx4 v[144:147], v196, s[16:17] offset:128
	global_load_dwordx4 v[148:151], v196, s[16:17] offset:160
	global_load_dwordx4 v[152:155], v196, s[16:17] offset:192
	global_load_dwordx4 v[156:159], v196, s[16:17] offset:224
	global_load_dwordx4 v[160:163], v196, s[16:17] offset:256
	global_load_dwordx4 v[164:167], v196, s[16:17] offset:288
	global_load_dwordx4 v[172:175], v196, s[16:17] offset:320
	global_load_dwordx4 v[176:179], v196, s[16:17] offset:352
	global_load_dwordx4 v[180:183], v196, s[16:17] offset:384
	global_load_dwordx4 v[184:187], v196, s[16:17] offset:416
	global_load_dwordx4 v[188:191], v196, s[16:17] offset:448
	global_load_dwordx4 v[192:195], v196, s[16:17] offset:480
	s_waitcnt vmcnt(15)
	v_fma_f32 v112, v171, v128, v112
	v_fma_f32 v113, v171, v129, v113
	v_fma_f32 v114, v171, v130, v114
	v_fma_f32 v115, v171, v131, v115
	v_fma_f32 v48, v171, v128, v48
	v_fma_f32 v49, v171, v129, v49
	v_fma_f32 v50, v171, v130, v50
	v_fma_f32 v51, v171, v131, v51
	s_waitcnt vmcnt(14)
	v_fma_f32 v116, v171, v132, v116
	v_fma_f32 v117, v171, v133, v117
	v_fma_f32 v118, v171, v134, v118
	v_fma_f32 v119, v171, v135, v119
	v_fma_f32 v52, v171, v132, v52
	v_fma_f32 v53, v171, v133, v53
	v_fma_f32 v54, v171, v134, v54
	v_fma_f32 v55, v171, v135, v55
	s_waitcnt vmcnt(13)
	v_fma_f32 v120, v171, v136, v120
	v_fma_f32 v121, v171, v137, v121
	v_fma_f32 v122, v171, v138, v122
	v_fma_f32 v123, v171, v139, v123
	v_fma_f32 v56, v171, v136, v56
	v_fma_f32 v57, v171, v137, v57
	v_fma_f32 v58, v171, v138, v58
	v_fma_f32 v59, v171, v139, v59
	s_waitcnt vmcnt(12)
	v_fma_f32 v124, v171, v140, v124
	v_fma_f32 v125, v171, v141, v125
	v_fma_f32 v126, v171, v142, v126
	v_fma_f32 v127, v171, v143, v127
	v_fma_f32 v60, v171, v140, v60
	v_fma_f32 v61, v171, v141, v61
	v_fma_f32 v62, v171, v142, v62
	v_fma_f32 v63, v171, v143, v63
	s_waitcnt vmcnt(11)
	v_fma_f32 v96, v171, v144, v96
	v_fma_f32 v97, v171, v145, v97
	v_fma_f32 v98, v171, v146, v98
	v_fma_f32 v99, v171, v147, v99
	v_fma_f32 v32, v171, v144, v32
	v_fma_f32 v33, v171, v145, v33
	v_fma_f32 v34, v171, v146, v34
	v_fma_f32 v35, v171, v147, v35
	s_waitcnt vmcnt(10)
	v_fma_f32 v100, v171, v148, v100
	v_fma_f32 v101, v171, v149, v101
	v_fma_f32 v102, v171, v150, v102
	v_fma_f32 v103, v171, v151, v103
	v_fma_f32 v36, v171, v148, v36
	v_fma_f32 v37, v171, v149, v37
	v_fma_f32 v38, v171, v150, v38
	v_fma_f32 v39, v171, v151, v39
	s_waitcnt vmcnt(9)
	v_fma_f32 v104, v171, v152, v104
	v_fma_f32 v105, v171, v153, v105
	v_fma_f32 v106, v171, v154, v106
	v_fma_f32 v107, v171, v155, v107
	v_fma_f32 v40, v171, v152, v40
	v_fma_f32 v41, v171, v153, v41
	v_fma_f32 v42, v171, v154, v42
	v_fma_f32 v43, v171, v155, v43
	s_waitcnt vmcnt(8)
	v_fma_f32 v108, v171, v156, v108
	v_fma_f32 v109, v171, v157, v109
	v_fma_f32 v110, v171, v158, v110
	v_fma_f32 v111, v171, v159, v111
	v_fma_f32 v44, v171, v156, v44
	v_fma_f32 v45, v171, v157, v45
	v_fma_f32 v46, v171, v158, v46
	v_fma_f32 v47, v171, v159, v47
	s_waitcnt vmcnt(7)
	v_fma_f32 v80, v171, v160, v80
	v_fma_f32 v81, v171, v161, v81
	v_fma_f32 v82, v171, v162, v82
	v_fma_f32 v83, v171, v163, v83
	v_fma_f32 v16, v171, v160, v16
	v_fma_f32 v17, v171, v161, v17
	v_fma_f32 v18, v171, v162, v18
	v_fma_f32 v19, v171, v163, v19
	s_waitcnt vmcnt(6)
	v_fma_f32 v84, v171, v164, v84
	v_fma_f32 v85, v171, v165, v85
	v_fma_f32 v86, v171, v166, v86
	v_fma_f32 v87, v171, v167, v87
	v_fma_f32 v20, v171, v164, v20
	v_fma_f32 v21, v171, v165, v21
	v_fma_f32 v22, v171, v166, v22
	v_fma_f32 v23, v171, v167, v23
	s_waitcnt vmcnt(5)
	v_fma_f32 v88, v171, v172, v88
	v_fma_f32 v89, v171, v173, v89
	v_fma_f32 v90, v171, v174, v90
	v_fma_f32 v91, v171, v175, v91
	v_fma_f32 v24, v171, v172, v24
	v_fma_f32 v25, v171, v173, v25
	v_fma_f32 v26, v171, v174, v26
	v_fma_f32 v27, v171, v175, v27
	s_waitcnt vmcnt(4)
	v_fma_f32 v92, v171, v176, v92
	v_fma_f32 v93, v171, v177, v93
	v_fma_f32 v94, v171, v178, v94
	v_fma_f32 v95, v171, v179, v95
	v_fma_f32 v28, v171, v176, v28
	v_fma_f32 v29, v171, v177, v29
	v_fma_f32 v30, v171, v178, v30
	v_fma_f32 v31, v171, v179, v31
	s_waitcnt vmcnt(3)
	v_fma_f32 v64, v171, v180, v64
	v_fma_f32 v65, v171, v181, v65
	v_fma_f32 v66, v171, v182, v66
	v_fma_f32 v67, v171, v183, v67
	v_fma_f32 v0, v171, v180, v0
	v_fma_f32 v1, v171, v181, v1
	v_fma_f32 v2, v171, v182, v2
	v_fma_f32 v3, v171, v183, v3
	s_waitcnt vmcnt(2)
	v_fma_f32 v68, v171, v184, v68
	v_fma_f32 v69, v171, v185, v69
	v_fma_f32 v70, v171, v186, v70
	v_fma_f32 v71, v171, v187, v71
	v_fma_f32 v4, v171, v184, v4
	v_fma_f32 v5, v171, v185, v5
	v_fma_f32 v6, v171, v186, v6
	v_fma_f32 v7, v171, v187, v7
	s_waitcnt vmcnt(1)
	v_fma_f32 v72, v171, v188, v72
	v_fma_f32 v73, v171, v189, v73
	v_fma_f32 v74, v171, v190, v74
	v_fma_f32 v75, v171, v191, v75
	v_fma_f32 v8, v171, v188, v8
	v_fma_f32 v9, v171, v189, v9
	v_fma_f32 v10, v171, v190, v10
	v_fma_f32 v11, v171, v191, v11
	s_waitcnt vmcnt(0)
	v_fma_f32 v76, v171, v192, v76
	v_fma_f32 v77, v171, v193, v77
	v_fma_f32 v78, v171, v194, v78
	v_fma_f32 v79, v171, v195, v79
	v_fma_f32 v12, v171, v192, v12
	v_fma_f32 v13, v171, v193, v13
	v_fma_f32 v14, v171, v194, v14
	v_fma_f32 v15, v171, v195, v15
	s_branch .Lfix7_done
.Lfix7_ty1:
	global_load_dwordx2 v[128:129], v197, s[12:13] offset:0
	global_load_dwordx2 v[132:133], v197, s[12:13] offset:16
	global_load_dwordx2 v[136:137], v197, s[12:13] offset:32
	global_load_dwordx2 v[140:141], v197, s[12:13] offset:48
	global_load_dwordx2 v[144:145], v197, s[12:13] offset:64
	global_load_dwordx2 v[148:149], v197, s[12:13] offset:80
	global_load_dwordx2 v[152:153], v197, s[12:13] offset:96
	global_load_dwordx2 v[156:157], v197, s[12:13] offset:112
	global_load_dwordx2 v[160:161], v197, s[12:13] offset:128
	global_load_dwordx2 v[164:165], v197, s[12:13] offset:144
	global_load_dwordx2 v[172:173], v197, s[12:13] offset:160
	global_load_dwordx2 v[176:177], v197, s[12:13] offset:176
	global_load_dwordx2 v[180:181], v197, s[12:13] offset:192
	global_load_dwordx2 v[184:185], v197, s[12:13] offset:208
	global_load_dwordx2 v[188:189], v197, s[12:13] offset:224
	global_load_dwordx2 v[192:193], v197, s[12:13] offset:240
	s_waitcnt vmcnt(15)
	v_lshlrev_b32_e32 v198, 16, v128
	v_and_b32_e32 v199, 0xffff0000, v128
	v_lshlrev_b32_e32 v200, 16, v129
	v_and_b32_e32 v201, 0xffff0000, v129
	v_sub_f32_e32 v112, v112, v198
	v_sub_f32_e32 v113, v113, v199
	v_sub_f32_e32 v114, v114, v200
	v_sub_f32_e32 v115, v115, v201
	v_sub_f32_e32 v48, v48, v198
	v_sub_f32_e32 v49, v49, v199
	v_sub_f32_e32 v50, v50, v200
	v_sub_f32_e32 v51, v51, v201
	s_waitcnt vmcnt(14)
	v_lshlrev_b32_e32 v198, 16, v132
	v_and_b32_e32 v199, 0xffff0000, v132
	v_lshlrev_b32_e32 v200, 16, v133
	v_and_b32_e32 v201, 0xffff0000, v133
	v_sub_f32_e32 v116, v116, v198
	v_sub_f32_e32 v117, v117, v199
	v_sub_f32_e32 v118, v118, v200
	v_sub_f32_e32 v119, v119, v201
	v_sub_f32_e32 v52, v52, v198
	v_sub_f32_e32 v53, v53, v199
	v_sub_f32_e32 v54, v54, v200
	v_sub_f32_e32 v55, v55, v201
	s_waitcnt vmcnt(13)
	v_lshlrev_b32_e32 v198, 16, v136
	v_and_b32_e32 v199, 0xffff0000, v136
	v_lshlrev_b32_e32 v200, 16, v137
	v_and_b32_e32 v201, 0xffff0000, v137
	v_sub_f32_e32 v120, v120, v198
	v_sub_f32_e32 v121, v121, v199
	v_sub_f32_e32 v122, v122, v200
	v_sub_f32_e32 v123, v123, v201
	v_sub_f32_e32 v56, v56, v198
	v_sub_f32_e32 v57, v57, v199
	v_sub_f32_e32 v58, v58, v200
	v_sub_f32_e32 v59, v59, v201
	s_waitcnt vmcnt(12)
	v_lshlrev_b32_e32 v198, 16, v140
	v_and_b32_e32 v199, 0xffff0000, v140
	v_lshlrev_b32_e32 v200, 16, v141
	v_and_b32_e32 v201, 0xffff0000, v141
	v_sub_f32_e32 v124, v124, v198
	v_sub_f32_e32 v125, v125, v199
	v_sub_f32_e32 v126, v126, v200
	v_sub_f32_e32 v127, v127, v201
	v_sub_f32_e32 v60, v60, v198
	v_sub_f32_e32 v61, v61, v199
	v_sub_f32_e32 v62, v62, v200
	v_sub_f32_e32 v63, v63, v201
	s_waitcnt vmcnt(11)
	v_lshlrev_b32_e32 v198, 16, v144
	v_and_b32_e32 v199, 0xffff0000, v144
	v_lshlrev_b32_e32 v200, 16, v145
	v_and_b32_e32 v201, 0xffff0000, v145
	v_sub_f32_e32 v96, v96, v198
	v_sub_f32_e32 v97, v97, v199
	v_sub_f32_e32 v98, v98, v200
	v_sub_f32_e32 v99, v99, v201
	v_sub_f32_e32 v32, v32, v198
	v_sub_f32_e32 v33, v33, v199
	v_sub_f32_e32 v34, v34, v200
	v_sub_f32_e32 v35, v35, v201
	s_waitcnt vmcnt(10)
	v_lshlrev_b32_e32 v198, 16, v148
	v_and_b32_e32 v199, 0xffff0000, v148
	v_lshlrev_b32_e32 v200, 16, v149
	v_and_b32_e32 v201, 0xffff0000, v149
	v_sub_f32_e32 v100, v100, v198
	v_sub_f32_e32 v101, v101, v199
	v_sub_f32_e32 v102, v102, v200
	v_sub_f32_e32 v103, v103, v201
	v_sub_f32_e32 v36, v36, v198
	v_sub_f32_e32 v37, v37, v199
	v_sub_f32_e32 v38, v38, v200
	v_sub_f32_e32 v39, v39, v201
	s_waitcnt vmcnt(9)
	v_lshlrev_b32_e32 v198, 16, v152
	v_and_b32_e32 v199, 0xffff0000, v152
	v_lshlrev_b32_e32 v200, 16, v153
	v_and_b32_e32 v201, 0xffff0000, v153
	v_sub_f32_e32 v104, v104, v198
	v_sub_f32_e32 v105, v105, v199
	v_sub_f32_e32 v106, v106, v200
	v_sub_f32_e32 v107, v107, v201
	v_sub_f32_e32 v40, v40, v198
	v_sub_f32_e32 v41, v41, v199
	v_sub_f32_e32 v42, v42, v200
	v_sub_f32_e32 v43, v43, v201
	s_waitcnt vmcnt(8)
	v_lshlrev_b32_e32 v198, 16, v156
	v_and_b32_e32 v199, 0xffff0000, v156
	v_lshlrev_b32_e32 v200, 16, v157
	v_and_b32_e32 v201, 0xffff0000, v157
	v_sub_f32_e32 v108, v108, v198
	v_sub_f32_e32 v109, v109, v199
	v_sub_f32_e32 v110, v110, v200
	v_sub_f32_e32 v111, v111, v201
	v_sub_f32_e32 v44, v44, v198
	v_sub_f32_e32 v45, v45, v199
	v_sub_f32_e32 v46, v46, v200
	v_sub_f32_e32 v47, v47, v201
	s_waitcnt vmcnt(7)
	v_lshlrev_b32_e32 v198, 16, v160
	v_and_b32_e32 v199, 0xffff0000, v160
	v_lshlrev_b32_e32 v200, 16, v161
	v_and_b32_e32 v201, 0xffff0000, v161
	v_sub_f32_e32 v80, v80, v198
	v_sub_f32_e32 v81, v81, v199
	v_sub_f32_e32 v82, v82, v200
	v_sub_f32_e32 v83, v83, v201
	v_sub_f32_e32 v16, v16, v198
	v_sub_f32_e32 v17, v17, v199
	v_sub_f32_e32 v18, v18, v200
	v_sub_f32_e32 v19, v19, v201
	s_waitcnt vmcnt(6)
	v_lshlrev_b32_e32 v198, 16, v164
	v_and_b32_e32 v199, 0xffff0000, v164
	v_lshlrev_b32_e32 v200, 16, v165
	v_and_b32_e32 v201, 0xffff0000, v165
	v_sub_f32_e32 v84, v84, v198
	v_sub_f32_e32 v85, v85, v199
	v_sub_f32_e32 v86, v86, v200
	v_sub_f32_e32 v87, v87, v201
	v_sub_f32_e32 v20, v20, v198
	v_sub_f32_e32 v21, v21, v199
	v_sub_f32_e32 v22, v22, v200
	v_sub_f32_e32 v23, v23, v201
	s_waitcnt vmcnt(5)
	v_lshlrev_b32_e32 v198, 16, v172
	v_and_b32_e32 v199, 0xffff0000, v172
	v_lshlrev_b32_e32 v200, 16, v173
	v_and_b32_e32 v201, 0xffff0000, v173
	v_sub_f32_e32 v88, v88, v198
	v_sub_f32_e32 v89, v89, v199
	v_sub_f32_e32 v90, v90, v200
	v_sub_f32_e32 v91, v91, v201
	v_sub_f32_e32 v24, v24, v198
	v_sub_f32_e32 v25, v25, v199
	v_sub_f32_e32 v26, v26, v200
	v_sub_f32_e32 v27, v27, v201
	s_waitcnt vmcnt(4)
	v_lshlrev_b32_e32 v198, 16, v176
	v_and_b32_e32 v199, 0xffff0000, v176
	v_lshlrev_b32_e32 v200, 16, v177
	v_and_b32_e32 v201, 0xffff0000, v177
	v_sub_f32_e32 v92, v92, v198
	v_sub_f32_e32 v93, v93, v199
	v_sub_f32_e32 v94, v94, v200
	v_sub_f32_e32 v95, v95, v201
	v_sub_f32_e32 v28, v28, v198
	v_sub_f32_e32 v29, v29, v199
	v_sub_f32_e32 v30, v30, v200
	v_sub_f32_e32 v31, v31, v201
	s_waitcnt vmcnt(3)
	v_lshlrev_b32_e32 v198, 16, v180
	v_and_b32_e32 v199, 0xffff0000, v180
	v_lshlrev_b32_e32 v200, 16, v181
	v_and_b32_e32 v201, 0xffff0000, v181
	v_sub_f32_e32 v64, v64, v198
	v_sub_f32_e32 v65, v65, v199
	v_sub_f32_e32 v66, v66, v200
	v_sub_f32_e32 v67, v67, v201
	v_sub_f32_e32 v0, v0, v198
	v_sub_f32_e32 v1, v1, v199
	v_sub_f32_e32 v2, v2, v200
	v_sub_f32_e32 v3, v3, v201
	s_waitcnt vmcnt(2)
	v_lshlrev_b32_e32 v198, 16, v184
	v_and_b32_e32 v199, 0xffff0000, v184
	v_lshlrev_b32_e32 v200, 16, v185
	v_and_b32_e32 v201, 0xffff0000, v185
	v_sub_f32_e32 v68, v68, v198
	v_sub_f32_e32 v69, v69, v199
	v_sub_f32_e32 v70, v70, v200
	v_sub_f32_e32 v71, v71, v201
	v_sub_f32_e32 v4, v4, v198
	v_sub_f32_e32 v5, v5, v199
	v_sub_f32_e32 v6, v6, v200
	v_sub_f32_e32 v7, v7, v201
	s_waitcnt vmcnt(1)
	v_lshlrev_b32_e32 v198, 16, v188
	v_and_b32_e32 v199, 0xffff0000, v188
	v_lshlrev_b32_e32 v200, 16, v189
	v_and_b32_e32 v201, 0xffff0000, v189
	v_sub_f32_e32 v72, v72, v198
	v_sub_f32_e32 v73, v73, v199
	v_sub_f32_e32 v74, v74, v200
	v_sub_f32_e32 v75, v75, v201
	v_sub_f32_e32 v8, v8, v198
	v_sub_f32_e32 v9, v9, v199
	v_sub_f32_e32 v10, v10, v200
	v_sub_f32_e32 v11, v11, v201
	s_waitcnt vmcnt(0)
	v_lshlrev_b32_e32 v198, 16, v192
	v_and_b32_e32 v199, 0xffff0000, v192
	v_lshlrev_b32_e32 v200, 16, v193
	v_and_b32_e32 v201, 0xffff0000, v193
	v_sub_f32_e32 v76, v76, v198
	v_sub_f32_e32 v77, v77, v199
	v_sub_f32_e32 v78, v78, v200
	v_sub_f32_e32 v79, v79, v201
	v_sub_f32_e32 v12, v12, v198
	v_sub_f32_e32 v13, v13, v199
	v_sub_f32_e32 v14, v14, v200
	v_sub_f32_e32 v15, v15, v201
	s_branch .Lfix7_done
.Lfix7_ty0:
	global_load_dwordx4 v[128:131], v196, s[14:15] offset:0
	global_load_dwordx2 v[160:161], v197, s[12:13] offset:0
	global_load_dwordx4 v[132:135], v196, s[14:15] offset:32
	global_load_dwordx2 v[164:165], v197, s[12:13] offset:16
	global_load_dwordx4 v[136:139], v196, s[14:15] offset:64
	global_load_dwordx2 v[172:173], v197, s[12:13] offset:32
	global_load_dwordx4 v[140:143], v196, s[14:15] offset:96
	global_load_dwordx2 v[176:177], v197, s[12:13] offset:48
	global_load_dwordx4 v[144:147], v196, s[14:15] offset:128
	global_load_dwordx2 v[180:181], v197, s[12:13] offset:64
	global_load_dwordx4 v[148:151], v196, s[14:15] offset:160
	global_load_dwordx2 v[184:185], v197, s[12:13] offset:80
	global_load_dwordx4 v[152:155], v196, s[14:15] offset:192
	global_load_dwordx2 v[188:189], v197, s[12:13] offset:96
	global_load_dwordx4 v[156:159], v196, s[14:15] offset:224
	global_load_dwordx2 v[192:193], v197, s[12:13] offset:112
	s_waitcnt vmcnt(14)
	v_lshlrev_b32_e32 v198, 16, v160
	v_and_b32_e32 v199, 0xffff0000, v160
	v_lshlrev_b32_e32 v200, 16, v161
	v_and_b32_e32 v201, 0xffff0000, v161
	v_fma_f32 v202, v171, v128, v198
	v_fma_f32 v203, v171, v129, v199
	v_fma_f32 v204, v171, v130, v200
	v_fma_f32 v205, v171, v131, v201
	v_add_f32_e32 v112, v112, v202
	v_add_f32_e32 v113, v113, v203
	v_add_f32_e32 v114, v114, v204
	v_add_f32_e32 v115, v115, v205
	v_add_f32_e32 v48, v48, v202
	v_add_f32_e32 v49, v49, v203
	v_add_f32_e32 v50, v50, v204
	v_add_f32_e32 v51, v51, v205
	s_waitcnt vmcnt(12)
	v_lshlrev_b32_e32 v198, 16, v164
	v_and_b32_e32 v199, 0xffff0000, v164
	v_lshlrev_b32_e32 v200, 16, v165
	v_and_b32_e32 v201, 0xffff0000, v165
	v_fma_f32 v202, v171, v132, v198
	v_fma_f32 v203, v171, v133, v199
	v_fma_f32 v204, v171, v134, v200
	v_fma_f32 v205, v171, v135, v201
	v_add_f32_e32 v116, v116, v202
	v_add_f32_e32 v117, v117, v203
	v_add_f32_e32 v118, v118, v204
	v_add_f32_e32 v119, v119, v205
	v_add_f32_e32 v52, v52, v202
	v_add_f32_e32 v53, v53, v203
	v_add_f32_e32 v54, v54, v204
	v_add_f32_e32 v55, v55, v205
	s_waitcnt vmcnt(10)
	v_lshlrev_b32_e32 v198, 16, v172
	v_and_b32_e32 v199, 0xffff0000, v172
	v_lshlrev_b32_e32 v200, 16, v173
	v_and_b32_e32 v201, 0xffff0000, v173
	v_fma_f32 v202, v171, v136, v198
	v_fma_f32 v203, v171, v137, v199
	v_fma_f32 v204, v171, v138, v200
	v_fma_f32 v205, v171, v139, v201
	v_add_f32_e32 v120, v120, v202
	v_add_f32_e32 v121, v121, v203
	v_add_f32_e32 v122, v122, v204
	v_add_f32_e32 v123, v123, v205
	v_add_f32_e32 v56, v56, v202
	v_add_f32_e32 v57, v57, v203
	v_add_f32_e32 v58, v58, v204
	v_add_f32_e32 v59, v59, v205
	s_waitcnt vmcnt(8)
	v_lshlrev_b32_e32 v198, 16, v176
	v_and_b32_e32 v199, 0xffff0000, v176
	v_lshlrev_b32_e32 v200, 16, v177
	v_and_b32_e32 v201, 0xffff0000, v177
	v_fma_f32 v202, v171, v140, v198
	v_fma_f32 v203, v171, v141, v199
	v_fma_f32 v204, v171, v142, v200
	v_fma_f32 v205, v171, v143, v201
	v_add_f32_e32 v124, v124, v202
	v_add_f32_e32 v125, v125, v203
	v_add_f32_e32 v126, v126, v204
	v_add_f32_e32 v127, v127, v205
	v_add_f32_e32 v60, v60, v202
	v_add_f32_e32 v61, v61, v203
	v_add_f32_e32 v62, v62, v204
	v_add_f32_e32 v63, v63, v205
	s_waitcnt vmcnt(6)
	v_lshlrev_b32_e32 v198, 16, v180
	v_and_b32_e32 v199, 0xffff0000, v180
	v_lshlrev_b32_e32 v200, 16, v181
	v_and_b32_e32 v201, 0xffff0000, v181
	v_fma_f32 v202, v171, v144, v198
	v_fma_f32 v203, v171, v145, v199
	v_fma_f32 v204, v171, v146, v200
	v_fma_f32 v205, v171, v147, v201
	v_add_f32_e32 v96, v96, v202
	v_add_f32_e32 v97, v97, v203
	v_add_f32_e32 v98, v98, v204
	v_add_f32_e32 v99, v99, v205
	v_add_f32_e32 v32, v32, v202
	v_add_f32_e32 v33, v33, v203
	v_add_f32_e32 v34, v34, v204
	v_add_f32_e32 v35, v35, v205
	s_waitcnt vmcnt(4)
	v_lshlrev_b32_e32 v198, 16, v184
	v_and_b32_e32 v199, 0xffff0000, v184
	v_lshlrev_b32_e32 v200, 16, v185
	v_and_b32_e32 v201, 0xffff0000, v185
	v_fma_f32 v202, v171, v148, v198
	v_fma_f32 v203, v171, v149, v199
	v_fma_f32 v204, v171, v150, v200
	v_fma_f32 v205, v171, v151, v201
	v_add_f32_e32 v100, v100, v202
	v_add_f32_e32 v101, v101, v203
	v_add_f32_e32 v102, v102, v204
	v_add_f32_e32 v103, v103, v205
	v_add_f32_e32 v36, v36, v202
	v_add_f32_e32 v37, v37, v203
	v_add_f32_e32 v38, v38, v204
	v_add_f32_e32 v39, v39, v205
	s_waitcnt vmcnt(2)
	v_lshlrev_b32_e32 v198, 16, v188
	v_and_b32_e32 v199, 0xffff0000, v188
	v_lshlrev_b32_e32 v200, 16, v189
	v_and_b32_e32 v201, 0xffff0000, v189
	v_fma_f32 v202, v171, v152, v198
	v_fma_f32 v203, v171, v153, v199
	v_fma_f32 v204, v171, v154, v200
	v_fma_f32 v205, v171, v155, v201
	v_add_f32_e32 v104, v104, v202
	v_add_f32_e32 v105, v105, v203
	v_add_f32_e32 v106, v106, v204
	v_add_f32_e32 v107, v107, v205
	v_add_f32_e32 v40, v40, v202
	v_add_f32_e32 v41, v41, v203
	v_add_f32_e32 v42, v42, v204
	v_add_f32_e32 v43, v43, v205
	s_waitcnt vmcnt(0)
	v_lshlrev_b32_e32 v198, 16, v192
	v_and_b32_e32 v199, 0xffff0000, v192
	v_lshlrev_b32_e32 v200, 16, v193
	v_and_b32_e32 v201, 0xffff0000, v193
	v_fma_f32 v202, v171, v156, v198
	v_fma_f32 v203, v171, v157, v199
	v_fma_f32 v204, v171, v158, v200
	v_fma_f32 v205, v171, v159, v201
	v_add_f32_e32 v108, v108, v202
	v_add_f32_e32 v109, v109, v203
	v_add_f32_e32 v110, v110, v204
	v_add_f32_e32 v111, v111, v205
	v_add_f32_e32 v44, v44, v202
	v_add_f32_e32 v45, v45, v203
	v_add_f32_e32 v46, v46, v204
	v_add_f32_e32 v47, v47, v205
	global_load_dwordx4 v[128:131], v196, s[14:15] offset:256
	global_load_dwordx2 v[160:161], v197, s[12:13] offset:128
	global_load_dwordx4 v[132:135], v196, s[14:15] offset:288
	global_load_dwordx2 v[164:165], v197, s[12:13] offset:144
	global_load_dwordx4 v[136:139], v196, s[14:15] offset:320
	global_load_dwordx2 v[172:173], v197, s[12:13] offset:160
	global_load_dwordx4 v[140:143], v196, s[14:15] offset:352
	global_load_dwordx2 v[176:177], v197, s[12:13] offset:176
	global_load_dwordx4 v[144:147], v196, s[14:15] offset:384
	global_load_dwordx2 v[180:181], v197, s[12:13] offset:192
	global_load_dwordx4 v[148:151], v196, s[14:15] offset:416
	global_load_dwordx2 v[184:185], v197, s[12:13] offset:208
	global_load_dwordx4 v[152:155], v196, s[14:15] offset:448
	global_load_dwordx2 v[188:189], v197, s[12:13] offset:224
	global_load_dwordx4 v[156:159], v196, s[14:15] offset:480
	global_load_dwordx2 v[192:193], v197, s[12:13] offset:240
	s_waitcnt vmcnt(14)
	v_lshlrev_b32_e32 v198, 16, v160
	v_and_b32_e32 v199, 0xffff0000, v160
	v_lshlrev_b32_e32 v200, 16, v161
	v_and_b32_e32 v201, 0xffff0000, v161
	v_fma_f32 v202, v171, v128, v198
	v_fma_f32 v203, v171, v129, v199
	v_fma_f32 v204, v171, v130, v200
	v_fma_f32 v205, v171, v131, v201
	v_add_f32_e32 v80, v80, v202
	v_add_f32_e32 v81, v81, v203
	v_add_f32_e32 v82, v82, v204
	v_add_f32_e32 v83, v83, v205
	v_add_f32_e32 v16, v16, v202
	v_add_f32_e32 v17, v17, v203
	v_add_f32_e32 v18, v18, v204
	v_add_f32_e32 v19, v19, v205
	s_waitcnt vmcnt(12)
	v_lshlrev_b32_e32 v198, 16, v164
	v_and_b32_e32 v199, 0xffff0000, v164
	v_lshlrev_b32_e32 v200, 16, v165
	v_and_b32_e32 v201, 0xffff0000, v165
	v_fma_f32 v202, v171, v132, v198
	v_fma_f32 v203, v171, v133, v199
	v_fma_f32 v204, v171, v134, v200
	v_fma_f32 v205, v171, v135, v201
	v_add_f32_e32 v84, v84, v202
	v_add_f32_e32 v85, v85, v203
	v_add_f32_e32 v86, v86, v204
	v_add_f32_e32 v87, v87, v205
	v_add_f32_e32 v20, v20, v202
	v_add_f32_e32 v21, v21, v203
	v_add_f32_e32 v22, v22, v204
	v_add_f32_e32 v23, v23, v205
	s_waitcnt vmcnt(10)
	v_lshlrev_b32_e32 v198, 16, v172
	v_and_b32_e32 v199, 0xffff0000, v172
	v_lshlrev_b32_e32 v200, 16, v173
	v_and_b32_e32 v201, 0xffff0000, v173
	v_fma_f32 v202, v171, v136, v198
	v_fma_f32 v203, v171, v137, v199
	v_fma_f32 v204, v171, v138, v200
	v_fma_f32 v205, v171, v139, v201
	v_add_f32_e32 v88, v88, v202
	v_add_f32_e32 v89, v89, v203
	v_add_f32_e32 v90, v90, v204
	v_add_f32_e32 v91, v91, v205
	v_add_f32_e32 v24, v24, v202
	v_add_f32_e32 v25, v25, v203
	v_add_f32_e32 v26, v26, v204
	v_add_f32_e32 v27, v27, v205
	s_waitcnt vmcnt(8)
	v_lshlrev_b32_e32 v198, 16, v176
	v_and_b32_e32 v199, 0xffff0000, v176
	v_lshlrev_b32_e32 v200, 16, v177
	v_and_b32_e32 v201, 0xffff0000, v177
	v_fma_f32 v202, v171, v140, v198
	v_fma_f32 v203, v171, v141, v199
	v_fma_f32 v204, v171, v142, v200
	v_fma_f32 v205, v171, v143, v201
	v_add_f32_e32 v92, v92, v202
	v_add_f32_e32 v93, v93, v203
	v_add_f32_e32 v94, v94, v204
	v_add_f32_e32 v95, v95, v205
	v_add_f32_e32 v28, v28, v202
	v_add_f32_e32 v29, v29, v203
	v_add_f32_e32 v30, v30, v204
	v_add_f32_e32 v31, v31, v205
	s_waitcnt vmcnt(6)
	v_lshlrev_b32_e32 v198, 16, v180
	v_and_b32_e32 v199, 0xffff0000, v180
	v_lshlrev_b32_e32 v200, 16, v181
	v_and_b32_e32 v201, 0xffff0000, v181
	v_fma_f32 v202, v171, v144, v198
	v_fma_f32 v203, v171, v145, v199
	v_fma_f32 v204, v171, v146, v200
	v_fma_f32 v205, v171, v147, v201
	v_add_f32_e32 v64, v64, v202
	v_add_f32_e32 v65, v65, v203
	v_add_f32_e32 v66, v66, v204
	v_add_f32_e32 v67, v67, v205
	v_add_f32_e32 v0, v0, v202
	v_add_f32_e32 v1, v1, v203
	v_add_f32_e32 v2, v2, v204
	v_add_f32_e32 v3, v3, v205
	s_waitcnt vmcnt(4)
	v_lshlrev_b32_e32 v198, 16, v184
	v_and_b32_e32 v199, 0xffff0000, v184
	v_lshlrev_b32_e32 v200, 16, v185
	v_and_b32_e32 v201, 0xffff0000, v185
	v_fma_f32 v202, v171, v148, v198
	v_fma_f32 v203, v171, v149, v199
	v_fma_f32 v204, v171, v150, v200
	v_fma_f32 v205, v171, v151, v201
	v_add_f32_e32 v68, v68, v202
	v_add_f32_e32 v69, v69, v203
	v_add_f32_e32 v70, v70, v204
	v_add_f32_e32 v71, v71, v205
	v_add_f32_e32 v4, v4, v202
	v_add_f32_e32 v5, v5, v203
	v_add_f32_e32 v6, v6, v204
	v_add_f32_e32 v7, v7, v205
	s_waitcnt vmcnt(2)
	v_lshlrev_b32_e32 v198, 16, v188
	v_and_b32_e32 v199, 0xffff0000, v188
	v_lshlrev_b32_e32 v200, 16, v189
	v_and_b32_e32 v201, 0xffff0000, v189
	v_fma_f32 v202, v171, v152, v198
	v_fma_f32 v203, v171, v153, v199
	v_fma_f32 v204, v171, v154, v200
	v_fma_f32 v205, v171, v155, v201
	v_add_f32_e32 v72, v72, v202
	v_add_f32_e32 v73, v73, v203
	v_add_f32_e32 v74, v74, v204
	v_add_f32_e32 v75, v75, v205
	v_add_f32_e32 v8, v8, v202
	v_add_f32_e32 v9, v9, v203
	v_add_f32_e32 v10, v10, v204
	v_add_f32_e32 v11, v11, v205
	s_waitcnt vmcnt(0)
	v_lshlrev_b32_e32 v198, 16, v192
	v_and_b32_e32 v199, 0xffff0000, v192
	v_lshlrev_b32_e32 v200, 16, v193
	v_and_b32_e32 v201, 0xffff0000, v193
	v_fma_f32 v202, v171, v156, v198
	v_fma_f32 v203, v171, v157, v199
	v_fma_f32 v204, v171, v158, v200
	v_fma_f32 v205, v171, v159, v201
	v_add_f32_e32 v76, v76, v202
	v_add_f32_e32 v77, v77, v203
	v_add_f32_e32 v78, v78, v204
	v_add_f32_e32 v79, v79, v205
	v_add_f32_e32 v12, v12, v202
	v_add_f32_e32 v13, v13, v203
	v_add_f32_e32 v14, v14, v204
	v_add_f32_e32 v15, v15, v205
.Lfix7_done:
	s_mov_b32 s75, s44
	s_mov_b32 s44, 2
	s_waitcnt vmcnt(0)
	v_mov_b32_e32 v135, v208
	s_lshl_b32 s18, s27, 11
	v_lshrrev_b32_e32 v129, 3, v135
	v_lshlrev_b32_e32 v128, 1, v135
	v_and_b32_e32 v129, 4, v129
	v_and_or_b32 v134, v128, s51, v129
	v_and_b32_e32 v128, 1, v135
	v_cmp_eq_u32_e32 vcc, 0, v128
	v_or_b32_e32 v129, s45, v134
	v_or_b32_e32 v129, s18, v129
	v_cndmask_b32_e64 v128, -1.0, 1.0, vcc
	s_cmp_lt_i32 s44, 1
	s_mov_b64 s[2:3], -1
	s_cbranch_scc1 .LBB0_851
	s_cmp_lt_i32 s44, 3
	s_cbranch_scc1 .LBB0_847
	s_cmp_eq_u32 s44, 3
	v_mov_b32_e32 v131, v115
	v_mov_b32_e32 v130, v114
	v_mov_b32_e32 v133, v113
	v_mov_b32_e32 v132, v112
	s_cbranch_scc0 .LBB0_846
	v_lshlrev_b32_e32 v130, 2, v129
	global_load_dwordx4 v[136:139], v130, s[16:17]
	s_waitcnt vmcnt(0)
	v_pk_fma_f32 v[132:133], v[128:129], v[136:137], v[112:113] op_sel_hi:[0,1,1]
	v_pk_fma_f32 v[130:131], v[128:129], v[138:139], v[114:115] op_sel_hi:[0,1,1]
